# redundant second s_waitcnt lgkmcnt(0) after each pre-MFMA barrier deleted in the eight K-loops (the drain right before the barrier already covers it); on top of v64
# speedup vs baseline: 1.0034x; 1.0034x over previous
; #define PG8_STAGE(bufoff, gbase, voff) do { _Pragma("unroll") for (int _i = 0; _i < 2; ++_i) \
;         __builtin_amdgcn_global_load_lds((const unsigned*)((const char*)(gbase) + (voff)[_i]), (PG8_LAS unsigned*)(lds + (bufoff) + ldsw + _i * 8192), 16, 0, 0); } while (0)
; #define PG8_LDA(dst, b, h) do { _Pragma("unroll") for (int m = 0; m < 4; ++m) _Pragma("unroll") for (int k = 0; k < 2; ++k) dst[m][k] = *(const PG8_LAS bf16x8*)(lds + PG8_SA(b, h) + aoff + m * 2048 + k * 1024); } while (0)
; #define PG8_LDB(dst, b, h) do { _Pragma("unroll") for (int n = 0; n < 2; ++n) _Pragma("unroll") for (int k = 0; k < 2; ++k) dst[n][k] = *(const PG8_LAS bf16x8*)(lds + PG8_SB(b, h) + boff + n * 2048 + k * 1024); } while (0)
; #define PG8_WAIT_V(n) asm volatile("s_waitcnt vmcnt(" #n ")" ::: "memory")
; template <class Epi, bool ALIGN_EPI, bool ABLK = false>
; __device__ __forceinline__ void gemm_phase(PG8_LAS unsigned char* lds, const Gemm g, const StaticOrder& S, const Epi& E) {
;     ...
;         for (int t = 0; t < nt; t += 2) {
;             const bool last = (t == nt - 2);
;             const char* a1 = cA + (size_t)(t + 1) * kstepA;
;             const char* a2 = last ? nA : cA + (size_t)(t + 2) * kstepA; const char* b2 = last ? nB : cB + (size_t)(t + 2) * kstepB;
;             const char* a3 = a2 + kstepA; const char* b3 = b2 + kstepB;
;             PG8_LDB(B0, 0, 0); PG8_LDB(B1, 0, 1); PG8_SCHED; PG8_LDA(At, 0, 0); PG8_STAGE(PG8_SA(1, 1), a1 + hstepA, voffA);
;             PG8_WAIT_V(8); PG8_WAIT_L(0); PG8_BAR; PG8_MMA(0, 0, At, B0); PG8_MMA(0, 1, At, B1); PG8_BAR; PG8_SCHED;
;             PG8_LDA(At, 0, 1); PG8_STAGE(PG8_SB(0, 0), b2, voffB); PG8_STAGE(PG8_SB(0, 1), b2 + hstepB, voffB); PG8_STAGE(PG8_SA(0, 0), a2, voffA);
;             PG8_WAIT_V(8); PG8_WAIT_L(0); PG8_BAR; PG8_MMA(1, 0, At, B0); PG8_MMA(1, 1, At, B1); PG8_BAR; PG8_SCHED;
;             PG8_LDB(B0, 1, 0); PG8_LDB(B1, 1, 1); PG8_SCHED; PG8_LDA(At, 1, 0); PG8_STAGE(PG8_SA(0, 1), a2 + hstepA, voffA);
;             PG8_WAIT_V(8); PG8_WAIT_L(0); PG8_BAR; PG8_MMA(0, 0, At, B0); PG8_MMA(0, 1, At, B1); PG8_BAR; PG8_SCHED;
;             PG8_LDA(At, 1, 1); PG8_STAGE(PG8_SB(1, 0), b3, voffB); PG8_STAGE(PG8_SB(1, 1), b3 + hstepB, voffB); PG8_STAGE(PG8_SA(1, 0), a3, voffA);
;             PG8_WAIT_V(8); PG8_WAIT_L(0); PG8_BAR; PG8_MMA(1, 0, At, B0); PG8_MMA(1, 1, At, B1); PG8_BAR; PG8_SCHED;
.LBB0_402:
	ds_read_b128 v[132:135], v251
	ds_read_b128 v[136:139], v251 offset:1024
	ds_read_b128 v[140:143], v251 offset:2048
	ds_read_b128 v[186:189], v251 offset:3072
	ds_read_b128 v[190:193], v251 offset:16384
	ds_read_b128 v[194:197], v251 offset:17408
	ds_read_b128 v[198:201], v251 offset:18432
	ds_read_b128 v[202:205], v251 offset:19456
	s_add_u32 s48, s24, s46
	s_addc_u32 s49, s25, s47
	s_cmp_eq_u32 s70, 12
	s_cselect_b32 s85, s41, s49
	s_cselect_b32 s84, s66, s48
	s_cselect_b32 s49, s39, s69
	s_cselect_b32 s48, s67, s68
	s_mov_b64 s[74:75], 0xc000
	s_add_i32 m0, s55, 0xc000
	s_mov_b64 s[74:75], 0xe000
	ds_read_b128 v[206:209], v183
	ds_read_b128 v[210:213], v183 offset:1024
	ds_read_b128 v[214:217], v183 offset:2048
	ds_read_b128 v[218:221], v183 offset:3072
	ds_read_b128 v[222:225], v183 offset:4096
	ds_read_b128 v[226:229], v183 offset:5120
	ds_read_b128 v[230:233], v183 offset:6144
	ds_read_b128 v[234:237], v183 offset:7168
	global_load_lds_dwordx4 v249, s[82:83]
	s_add_i32 m0, s55, 0xe000
	s_nop 0
	global_load_lds_dwordx4 v250, s[82:83]
	s_waitcnt vmcnt(8)
	s_waitcnt lgkmcnt(0)
	s_barrier
	s_setprio 1
	v_mfma_f32_16x16x32_bf16 v[126:129], v[132:135], v[206:209], v[126:129]
	v_mfma_f32_16x16x32_bf16 v[122:125], v[140:143], v[206:209], v[122:125]
	v_mfma_f32_16x16x32_bf16 v[118:121], v[132:135], v[214:217], v[118:121]
	v_mfma_f32_16x16x32_bf16 v[114:117], v[140:143], v[214:217], v[114:117]
	v_mfma_f32_16x16x32_bf16 v[110:113], v[132:135], v[222:225], v[110:113]
	v_mfma_f32_16x16x32_bf16 v[106:109], v[140:143], v[222:225], v[106:109]
	v_mfma_f32_16x16x32_bf16 v[102:105], v[132:135], v[230:233], v[102:105]
	v_mfma_f32_16x16x32_bf16 v[98:101], v[140:143], v[230:233], v[98:101]
	v_mfma_f32_16x16x32_bf16 v[126:129], v[136:139], v[210:213], v[126:129]
	v_mfma_f32_16x16x32_bf16 v[122:125], v[186:189], v[210:213], v[122:125]
	v_mfma_f32_16x16x32_bf16 v[118:121], v[136:139], v[218:221], v[118:121]
	v_mfma_f32_16x16x32_bf16 v[114:117], v[186:189], v[218:221], v[114:117]
	v_mfma_f32_16x16x32_bf16 v[110:113], v[136:139], v[226:229], v[110:113]
	v_mfma_f32_16x16x32_bf16 v[106:109], v[186:189], v[226:229], v[106:109]
	v_mfma_f32_16x16x32_bf16 v[102:105], v[136:139], v[234:237], v[102:105]
	v_mfma_f32_16x16x32_bf16 v[98:101], v[186:189], v[234:237], v[98:101]
	s_setprio 0
	s_setprio 1
	v_mfma_f32_16x16x32_bf16 v[94:97], v[190:193], v[206:209], v[94:97]
	s_add_i32 s71, s64, s9
	v_mfma_f32_16x16x32_bf16 v[90:93], v[198:201], v[206:209], v[90:93]
	s_mov_b32 m0, s71
	v_mfma_f32_16x16x32_bf16 v[86:89], v[190:193], v[214:217], v[86:89]
	v_mfma_f32_16x16x32_bf16 v[82:85], v[198:201], v[214:217], v[82:85]
	v_mfma_f32_16x16x32_bf16 v[78:81], v[190:193], v[222:225], v[78:81]
	v_mfma_f32_16x16x32_bf16 v[74:77], v[198:201], v[222:225], v[74:77]
	v_mfma_f32_16x16x32_bf16 v[70:73], v[190:193], v[230:233], v[70:73]
	v_mfma_f32_16x16x32_bf16 v[66:69], v[198:201], v[230:233], v[66:69]
	v_mfma_f32_16x16x32_bf16 v[94:97], v[194:197], v[210:213], v[94:97]
	v_mfma_f32_16x16x32_bf16 v[90:93], v[202:205], v[210:213], v[90:93]
	v_mfma_f32_16x16x32_bf16 v[86:89], v[194:197], v[218:221], v[86:89]
	v_mfma_f32_16x16x32_bf16 v[82:85], v[202:205], v[218:221], v[82:85]
	v_mfma_f32_16x16x32_bf16 v[78:81], v[194:197], v[226:229], v[78:81]
	v_mfma_f32_16x16x32_bf16 v[74:77], v[202:205], v[226:229], v[74:77]
	v_mfma_f32_16x16x32_bf16 v[70:73], v[194:197], v[234:237], v[70:73]
	v_mfma_f32_16x16x32_bf16 v[66:69], v[202:205], v[234:237], v[66:69]
	s_setprio 0
	s_barrier
	ds_read_b128 v[206:209], v183 offset:16384
	ds_read_b128 v[210:213], v183 offset:17408
	ds_read_b128 v[214:217], v183 offset:18432
	ds_read_b128 v[218:221], v183 offset:19456
	ds_read_b128 v[222:225], v183 offset:20480
	ds_read_b128 v[226:229], v183 offset:21504
	ds_read_b128 v[230:233], v183 offset:22528
	ds_read_b128 v[234:237], v183 offset:23552
	global_load_lds_dwordx4 v148, s[48:49]
	s_add_i32 m0, s71, 0x2000
	s_add_u32 s74, s48, 0x40000
	s_addc_u32 s75, s49, 0
	s_add_i32 s71, s65, s9
	global_load_lds_dwordx4 v150, s[48:49]
	s_mov_b32 m0, s71
	s_nop 0
	global_load_lds_dwordx4 v148, s[74:75]
	s_add_i32 m0, s71, 0x2000
	s_nop 0
	global_load_lds_dwordx4 v150, s[74:75]
	s_mov_b32 m0, s55
	s_mov_b64 s[72:73], 0x2000
	global_load_lds_dwordx4 v146, s[84:85]
	s_mov_b32 m0, s56
	s_nop 0
	global_load_lds_dwordx4 v244, s[84:85]
	s_waitcnt vmcnt(8)
	s_waitcnt lgkmcnt(0)
	s_barrier
	s_setprio 1
	v_mfma_f32_16x16x32_bf16 v[62:65], v[132:135], v[206:209], v[62:65]
	v_mfma_f32_16x16x32_bf16 v[58:61], v[140:143], v[206:209], v[58:61]
	v_mfma_f32_16x16x32_bf16 v[54:57], v[132:135], v[214:217], v[54:57]
	v_mfma_f32_16x16x32_bf16 v[50:53], v[140:143], v[214:217], v[50:53]
	v_mfma_f32_16x16x32_bf16 v[46:49], v[132:135], v[222:225], v[46:49]
	v_mfma_f32_16x16x32_bf16 v[42:45], v[140:143], v[222:225], v[42:45]
	v_mfma_f32_16x16x32_bf16 v[38:41], v[132:135], v[230:233], v[38:41]
	v_mfma_f32_16x16x32_bf16 v[34:37], v[140:143], v[230:233], v[34:37]
	v_mfma_f32_16x16x32_bf16 v[62:65], v[136:139], v[210:213], v[62:65]
	v_mfma_f32_16x16x32_bf16 v[58:61], v[186:189], v[210:213], v[58:61]
	v_mfma_f32_16x16x32_bf16 v[54:57], v[136:139], v[218:221], v[54:57]
	v_mfma_f32_16x16x32_bf16 v[50:53], v[186:189], v[218:221], v[50:53]
	v_mfma_f32_16x16x32_bf16 v[46:49], v[136:139], v[226:229], v[46:49]
	v_mfma_f32_16x16x32_bf16 v[42:45], v[186:189], v[226:229], v[42:45]
	v_mfma_f32_16x16x32_bf16 v[38:41], v[136:139], v[234:237], v[38:41]
	v_mfma_f32_16x16x32_bf16 v[34:37], v[186:189], v[234:237], v[34:37]
	s_setprio 0
	s_setprio 1
	v_mfma_f32_16x16x32_bf16 v[30:33], v[190:193], v[206:209], v[30:33]
	s_add_i32 s71, 0, 0x18000
	v_mfma_f32_16x16x32_bf16 v[26:29], v[198:201], v[206:209], v[26:29]
	s_add_i32 s74, 0, 0x1c000
	v_mfma_f32_16x16x32_bf16 v[22:25], v[190:193], v[214:217], v[22:25]
	v_mfma_f32_16x16x32_bf16 v[18:21], v[198:201], v[214:217], v[18:21]
	v_mfma_f32_16x16x32_bf16 v[14:17], v[190:193], v[222:225], v[14:17]
	v_mfma_f32_16x16x32_bf16 v[10:13], v[198:201], v[222:225], v[10:13]
	v_mfma_f32_16x16x32_bf16 v[6:9], v[190:193], v[230:233], v[6:9]
	v_mfma_f32_16x16x32_bf16 v[2:5], v[198:201], v[230:233], v[2:5]
	v_mfma_f32_16x16x32_bf16 v[30:33], v[194:197], v[210:213], v[30:33]
	v_mfma_f32_16x16x32_bf16 v[26:29], v[202:205], v[210:213], v[26:29]
	v_mfma_f32_16x16x32_bf16 v[22:25], v[194:197], v[218:221], v[22:25]
	v_mfma_f32_16x16x32_bf16 v[18:21], v[202:205], v[218:221], v[18:21]
	v_mfma_f32_16x16x32_bf16 v[14:17], v[194:197], v[226:229], v[14:17]
	v_mfma_f32_16x16x32_bf16 v[10:13], v[202:205], v[226:229], v[10:13]
	v_mfma_f32_16x16x32_bf16 v[6:9], v[194:197], v[234:237], v[6:9]
	v_mfma_f32_16x16x32_bf16 v[2:5], v[202:205], v[234:237], v[2:5]
	s_setprio 0
	s_barrier
; #define PG8_STAGE(bufoff, gbase, voff) do { _Pragma("unroll") for (int _i = 0; _i < 2; ++_i) \
;         __builtin_amdgcn_global_load_lds((const unsigned*)((const char*)(gbase) + (voff)[_i]), (PG8_LAS unsigned*)(lds + (bufoff) + ldsw + _i * 8192), 16, 0, 0); } while (0)
; #define PG8_LDA(dst, b, h) do { _Pragma("unroll") for (int m = 0; m < 4; ++m) _Pragma("unroll") for (int k = 0; k < 2; ++k) dst[m][k] = *(const PG8_LAS bf16x8*)(lds + PG8_SA(b, h) + aoff + m * 2048 + k * 1024); } while (0)
; #define PG8_LDB(dst, b, h) do { _Pragma("unroll") for (int n = 0; n < 2; ++n) _Pragma("unroll") for (int k = 0; k < 2; ++k) dst[n][k] = *(const PG8_LAS bf16x8*)(lds + PG8_SB(b, h) + boff + n * 2048 + k * 1024); } while (0)
; #define PG8_WAIT_V(n) asm volatile("s_waitcnt vmcnt(" #n ")" ::: "memory")
; template <class Epi, bool ALIGN_EPI, bool ABLK = false>
; __device__ __forceinline__ void gemm_phase(PG8_LAS unsigned char* lds, const Gemm g, const StaticOrder& S, const Epi& E) {
;     ...
;         for (int t = 0; t < nt; t += 2) {
;             const bool last = (t == nt - 2);
;             const char* a1 = cA + (size_t)(t + 1) * kstepA;
;             const char* a2 = last ? nA : cA + (size_t)(t + 2) * kstepA; const char* b2 = last ? nB : cB + (size_t)(t + 2) * kstepB;
;             const char* a3 = a2 + kstepA; const char* b3 = b2 + kstepB;
;             PG8_LDB(B0, 0, 0); PG8_LDB(B1, 0, 1); PG8_SCHED; PG8_LDA(At, 0, 0); PG8_STAGE(PG8_SA(1, 1), a1 + hstepA, voffA);
;             PG8_WAIT_V(8); PG8_WAIT_L(0); PG8_BAR; PG8_MMA(0, 0, At, B0); PG8_MMA(0, 1, At, B1); PG8_BAR; PG8_SCHED;
;             PG8_LDA(At, 0, 1); PG8_STAGE(PG8_SB(0, 0), b2, voffB); PG8_STAGE(PG8_SB(0, 1), b2 + hstepB, voffB); PG8_STAGE(PG8_SA(0, 0), a2, voffA);
;             PG8_WAIT_V(8); PG8_WAIT_L(0); PG8_BAR; PG8_MMA(1, 0, At, B0); PG8_MMA(1, 1, At, B1); PG8_BAR; PG8_SCHED;
;             PG8_LDB(B0, 1, 0); PG8_LDB(B1, 1, 1); PG8_SCHED; PG8_LDA(At, 1, 0); PG8_STAGE(PG8_SA(0, 1), a2 + hstepA, voffA);
;             PG8_WAIT_V(8); PG8_WAIT_L(0); PG8_BAR; PG8_MMA(0, 0, At, B0); PG8_MMA(0, 1, At, B1); PG8_BAR; PG8_SCHED;
;             PG8_LDA(At, 1, 1); PG8_STAGE(PG8_SB(1, 0), b3, voffB); PG8_STAGE(PG8_SB(1, 1), b3 + hstepB, voffB); PG8_STAGE(PG8_SA(1, 0), a3, voffA);
;             PG8_WAIT_V(8); PG8_WAIT_L(0); PG8_BAR; PG8_MMA(1, 0, At, B0); PG8_MMA(1, 1, At, B1); PG8_BAR; PG8_SCHED;
	ds_read_b128 v[132:135], v251 offset:32768
	ds_read_b128 v[136:139], v251 offset:33792
	ds_read_b128 v[140:143], v251 offset:34816
	ds_read_b128 v[186:189], v251 offset:35840
	ds_read_b128 v[190:193], v251 offset:49152
	ds_read_b128 v[194:197], v251 offset:50176
	ds_read_b128 v[198:201], v251 offset:51200
	ds_read_b128 v[202:205], v251 offset:52224
	s_mov_b64 s[72:73], 0x4000
	s_mov_b32 m0, s57
	s_mov_b64 s[72:73], 0x6000
	ds_read_b128 v[206:209], v183 offset:32768
	ds_read_b128 v[210:213], v183 offset:33792
	ds_read_b128 v[214:217], v183 offset:34816
	ds_read_b128 v[218:221], v183 offset:35840
	ds_read_b128 v[222:225], v183 offset:36864
	ds_read_b128 v[226:229], v183 offset:37888
	ds_read_b128 v[230:233], v183 offset:38912
	ds_read_b128 v[234:237], v183 offset:39936
	global_load_lds_dwordx4 v245, s[84:85]
	s_mov_b32 m0, s58
	s_nop 0
	global_load_lds_dwordx4 v246, s[84:85]
	s_waitcnt vmcnt(8)
	s_waitcnt lgkmcnt(0)
	s_barrier
	s_setprio 1
	v_mfma_f32_16x16x32_bf16 v[126:129], v[132:135], v[206:209], v[126:129]
	v_mfma_f32_16x16x32_bf16 v[122:125], v[140:143], v[206:209], v[122:125]
	v_mfma_f32_16x16x32_bf16 v[118:121], v[132:135], v[214:217], v[118:121]
	v_mfma_f32_16x16x32_bf16 v[114:117], v[140:143], v[214:217], v[114:117]
	v_mfma_f32_16x16x32_bf16 v[110:113], v[132:135], v[222:225], v[110:113]
	v_mfma_f32_16x16x32_bf16 v[106:109], v[140:143], v[222:225], v[106:109]
	v_mfma_f32_16x16x32_bf16 v[102:105], v[132:135], v[230:233], v[102:105]
	v_mfma_f32_16x16x32_bf16 v[98:101], v[140:143], v[230:233], v[98:101]
	v_mfma_f32_16x16x32_bf16 v[126:129], v[136:139], v[210:213], v[126:129]
	v_mfma_f32_16x16x32_bf16 v[122:125], v[186:189], v[210:213], v[122:125]
	v_mfma_f32_16x16x32_bf16 v[118:121], v[136:139], v[218:221], v[118:121]
	v_mfma_f32_16x16x32_bf16 v[114:117], v[186:189], v[218:221], v[114:117]
	v_mfma_f32_16x16x32_bf16 v[110:113], v[136:139], v[226:229], v[110:113]
	v_mfma_f32_16x16x32_bf16 v[106:109], v[186:189], v[226:229], v[106:109]
	v_mfma_f32_16x16x32_bf16 v[102:105], v[136:139], v[234:237], v[102:105]
	v_mfma_f32_16x16x32_bf16 v[98:101], v[186:189], v[234:237], v[98:101]
	s_setprio 0
	s_setprio 1
	v_mfma_f32_16x16x32_bf16 v[94:97], v[190:193], v[206:209], v[94:97]
	s_add_i32 s71, s71, s9
	v_mfma_f32_16x16x32_bf16 v[90:93], v[198:201], v[206:209], v[90:93]
	s_add_u32 s86, s48, s28
	v_mfma_f32_16x16x32_bf16 v[86:89], v[190:193], v[214:217], v[86:89]
	s_addc_u32 s87, s49, s29
	v_mfma_f32_16x16x32_bf16 v[82:85], v[198:201], v[214:217], v[82:85]
	s_mov_b32 m0, s71
	v_mfma_f32_16x16x32_bf16 v[78:81], v[190:193], v[222:225], v[78:81]
	v_mfma_f32_16x16x32_bf16 v[74:77], v[198:201], v[222:225], v[74:77]
	v_mfma_f32_16x16x32_bf16 v[70:73], v[190:193], v[230:233], v[70:73]
	v_mfma_f32_16x16x32_bf16 v[66:69], v[198:201], v[230:233], v[66:69]
	v_mfma_f32_16x16x32_bf16 v[94:97], v[194:197], v[210:213], v[94:97]
	v_mfma_f32_16x16x32_bf16 v[90:93], v[202:205], v[210:213], v[90:93]
	v_mfma_f32_16x16x32_bf16 v[86:89], v[194:197], v[218:221], v[86:89]
	v_mfma_f32_16x16x32_bf16 v[82:85], v[202:205], v[218:221], v[82:85]
	v_mfma_f32_16x16x32_bf16 v[78:81], v[194:197], v[226:229], v[78:81]
	v_mfma_f32_16x16x32_bf16 v[74:77], v[202:205], v[226:229], v[74:77]
	v_mfma_f32_16x16x32_bf16 v[70:73], v[194:197], v[234:237], v[70:73]
	v_mfma_f32_16x16x32_bf16 v[66:69], v[202:205], v[234:237], v[66:69]
	s_setprio 0
	s_barrier
	ds_read_b128 v[206:209], v183 offset:49152
	ds_read_b128 v[210:213], v183 offset:50176
	ds_read_b128 v[214:217], v183 offset:51200
	ds_read_b128 v[218:221], v183 offset:52224
	ds_read_b128 v[222:225], v183 offset:53248
	ds_read_b128 v[226:229], v183 offset:54272
	ds_read_b128 v[230:233], v183 offset:55296
	ds_read_b128 v[234:237], v183 offset:56320
	global_load_lds_dwordx4 v148, s[86:87]
	s_add_i32 m0, s71, 0x2000
	s_add_u32 s48, s48, 0x40080
	s_addc_u32 s49, s49, 0
	s_add_i32 s71, s74, s9
	global_load_lds_dwordx4 v150, s[86:87]
	s_mov_b32 m0, s71
	s_nop 0
	global_load_lds_dwordx4 v148, s[48:49]
	s_add_i32 m0, s71, 0x2000
	s_nop 0
	global_load_lds_dwordx4 v150, s[48:49]
	s_mov_b32 m0, s59
	s_nop 0
	global_load_lds_dwordx4 v247, s[84:85]
	s_mov_b32 m0, s61
	s_nop 0
	global_load_lds_dwordx4 v248, s[84:85]
	s_waitcnt vmcnt(8)
	s_waitcnt lgkmcnt(0)
	s_barrier
	s_setprio 1
	v_mfma_f32_16x16x32_bf16 v[62:65], v[132:135], v[206:209], v[62:65]
	v_mfma_f32_16x16x32_bf16 v[58:61], v[140:143], v[206:209], v[58:61]
	v_mfma_f32_16x16x32_bf16 v[54:57], v[132:135], v[214:217], v[54:57]
	v_mfma_f32_16x16x32_bf16 v[50:53], v[140:143], v[214:217], v[50:53]
	v_mfma_f32_16x16x32_bf16 v[46:49], v[132:135], v[222:225], v[46:49]
	v_mfma_f32_16x16x32_bf16 v[42:45], v[140:143], v[222:225], v[42:45]
	v_mfma_f32_16x16x32_bf16 v[38:41], v[132:135], v[230:233], v[38:41]
	v_mfma_f32_16x16x32_bf16 v[34:37], v[140:143], v[230:233], v[34:37]
	v_mfma_f32_16x16x32_bf16 v[62:65], v[136:139], v[210:213], v[62:65]
	v_mfma_f32_16x16x32_bf16 v[58:61], v[186:189], v[210:213], v[58:61]
	v_mfma_f32_16x16x32_bf16 v[54:57], v[136:139], v[218:221], v[54:57]
	v_mfma_f32_16x16x32_bf16 v[50:53], v[186:189], v[218:221], v[50:53]
	v_mfma_f32_16x16x32_bf16 v[46:49], v[136:139], v[226:229], v[46:49]
	v_mfma_f32_16x16x32_bf16 v[42:45], v[186:189], v[226:229], v[42:45]
	v_mfma_f32_16x16x32_bf16 v[38:41], v[136:139], v[234:237], v[38:41]
	v_mfma_f32_16x16x32_bf16 v[34:37], v[186:189], v[234:237], v[34:37]
	s_setprio 0
	s_setprio 1
	v_mfma_f32_16x16x32_bf16 v[30:33], v[190:193], v[206:209], v[30:33]
	s_add_i32 s70, s70, 2
	v_mfma_f32_16x16x32_bf16 v[26:29], v[198:201], v[206:209], v[26:29]
	s_add_u32 s68, s68, 0x100
	v_mfma_f32_16x16x32_bf16 v[22:25], v[190:193], v[214:217], v[22:25]
	s_addc_u32 s69, s69, 0
	v_mfma_f32_16x16x32_bf16 v[18:21], v[198:201], v[214:217], v[18:21]
	s_add_u32 s46, s46, 0x10000
	v_mfma_f32_16x16x32_bf16 v[14:17], v[190:193], v[222:225], v[14:17]
	s_addc_u32 s47, s47, 0
	v_mfma_f32_16x16x32_bf16 v[10:13], v[198:201], v[222:225], v[10:13]
	s_add_u32 s82, s82, 0x10000
	v_mfma_f32_16x16x32_bf16 v[6:9], v[190:193], v[230:233], v[6:9]
	s_addc_u32 s83, s83, 0
	v_mfma_f32_16x16x32_bf16 v[2:5], v[198:201], v[230:233], v[2:5]
	s_mov_b64 s[48:49], 0x10000
	v_mfma_f32_16x16x32_bf16 v[30:33], v[194:197], v[210:213], v[30:33]
	s_cmp_gt_u32 s70, 13
	v_mfma_f32_16x16x32_bf16 v[26:29], v[202:205], v[210:213], v[26:29]
	v_mfma_f32_16x16x32_bf16 v[22:25], v[194:197], v[218:221], v[22:25]
	v_mfma_f32_16x16x32_bf16 v[18:21], v[202:205], v[218:221], v[18:21]
	v_mfma_f32_16x16x32_bf16 v[14:17], v[194:197], v[226:229], v[14:17]
	v_mfma_f32_16x16x32_bf16 v[10:13], v[202:205], v[226:229], v[10:13]
	v_mfma_f32_16x16x32_bf16 v[6:9], v[194:197], v[234:237], v[6:9]
	v_mfma_f32_16x16x32_bf16 v[2:5], v[202:205], v[234:237], v[2:5]
	s_setprio 0
	s_barrier
	s_cbranch_scc0 .LBB0_402
	s_and_b64 vcc, exec, s[36:37]
	s_cbranch_vccz .LBB0_405
	s_barrier

; #define PG8_STAGE(bufoff, gbase, voff) do { _Pragma("unroll") for (int _i = 0; _i < 2; ++_i) \
;         __builtin_amdgcn_global_load_lds((const unsigned*)((const char*)(gbase) + (voff)[_i]), (PG8_LAS unsigned*)(lds + (bufoff) + ldsw + _i * 8192), 16, 0, 0); } while (0)
; #define PG8_LDA(dst, b, h) do { _Pragma("unroll") for (int m = 0; m < 4; ++m) _Pragma("unroll") for (int k = 0; k < 2; ++k) dst[m][k] = *(const PG8_LAS bf16x8*)(lds + PG8_SA(b, h) + aoff + m * 2048 + k * 1024); } while (0)
; #define PG8_LDB(dst, b, h) do { _Pragma("unroll") for (int n = 0; n < 2; ++n) _Pragma("unroll") for (int k = 0; k < 2; ++k) dst[n][k] = *(const PG8_LAS bf16x8*)(lds + PG8_SB(b, h) + boff + n * 2048 + k * 1024); } while (0)
; #define PG8_WAIT_V(n) asm volatile("s_waitcnt vmcnt(" #n ")" ::: "memory")
; template <class Epi, bool ALIGN_EPI, bool ABLK = false>
; __device__ __forceinline__ void gemm_phase(PG8_LAS unsigned char* lds, const Gemm g, const StaticOrder& S, const Epi& E) {
;     ...
;         for (int t = 0; t < nt; t += 2) {
;             const bool last = (t == nt - 2);
;             const char* a1 = cA + (size_t)(t + 1) * kstepA;
;             const char* a2 = last ? nA : cA + (size_t)(t + 2) * kstepA; const char* b2 = last ? nB : cB + (size_t)(t + 2) * kstepB;
;             const char* a3 = a2 + kstepA; const char* b3 = b2 + kstepB;
;             PG8_LDB(B0, 0, 0); PG8_LDB(B1, 0, 1); PG8_SCHED; PG8_LDA(At, 0, 0); PG8_STAGE(PG8_SA(1, 1), a1 + hstepA, voffA);
;             PG8_WAIT_V(8); PG8_WAIT_L(0); PG8_BAR; PG8_MMA(0, 0, At, B0); PG8_MMA(0, 1, At, B1); PG8_BAR; PG8_SCHED;
;             PG8_LDA(At, 0, 1); PG8_STAGE(PG8_SB(0, 0), b2, voffB); PG8_STAGE(PG8_SB(0, 1), b2 + hstepB, voffB); PG8_STAGE(PG8_SA(0, 0), a2, voffA);
;             PG8_WAIT_V(8); PG8_WAIT_L(0); PG8_BAR; PG8_MMA(1, 0, At, B0); PG8_MMA(1, 1, At, B1); PG8_BAR; PG8_SCHED;
;             PG8_LDB(B0, 1, 0); PG8_LDB(B1, 1, 1); PG8_SCHED; PG8_LDA(At, 1, 0); PG8_STAGE(PG8_SA(0, 1), a2 + hstepA, voffA);
;             PG8_WAIT_V(8); PG8_WAIT_L(0); PG8_BAR; PG8_MMA(0, 0, At, B0); PG8_MMA(0, 1, At, B1); PG8_BAR; PG8_SCHED;
;             PG8_LDA(At, 1, 1); PG8_STAGE(PG8_SB(1, 0), b3, voffB); PG8_STAGE(PG8_SB(1, 1), b3 + hstepB, voffB); PG8_STAGE(PG8_SA(1, 0), a3, voffA);
;             PG8_WAIT_V(8); PG8_WAIT_L(0); PG8_BAR; PG8_MMA(1, 0, At, B0); PG8_MMA(1, 1, At, B1); PG8_BAR; PG8_SCHED;
.LBB0_540:
	ds_read_b128 v[98:101], v238
	ds_read_b128 v[110:113], v238 offset:1024
	ds_read_b128 v[122:125], v238 offset:2048
	ds_read_b128 v[126:129], v238 offset:3072
	ds_read_b128 v[134:137], v239
	ds_read_b128 v[142:145], v239 offset:1024
	ds_read_b128 v[146:149], v239 offset:2048
	ds_read_b128 v[150:153], v239 offset:3072
	s_cmp_eq_u32 s78, 40
	s_cselect_b32 s81, s9, s51
	s_cselect_b32 s80, s8, s50
	s_cselect_b32 s53, s49, s55
	s_cselect_b32 s52, s48, s54
	s_movk_i32 s82, 0xc000
	v_lshl_add_u64 v[242:243], s[50:51], 0, v[194:195]
	s_mov_b32 s83, -1
	v_lshl_add_u64 v[244:245], v[242:243], 0, s[82:83]
	s_movk_i32 s82, 0xe000
	s_add_i32 m0, s61, 0xc000
	s_mov_b32 s83, -1
	ds_read_b128 v[154:157], v240
	ds_read_b128 v[166:169], v240 offset:1024
	ds_read_b128 v[170:173], v240 offset:2048
	ds_read_b128 v[174:177], v240 offset:3072
	ds_read_b128 v[178:181], v240 offset:4096
	ds_read_b128 v[182:185], v240 offset:5120
	ds_read_b128 v[186:189], v240 offset:6144
	ds_read_b128 v[190:193], v240 offset:7168
	global_load_lds_dwordx4 v[244:245], off
	v_lshl_add_u64 v[242:243], v[242:243], 0, s[82:83]
	s_add_i32 m0, s61, 0xe000
	s_nop 0
	global_load_lds_dwordx4 v[242:243], off
	s_waitcnt vmcnt(8)
	s_waitcnt lgkmcnt(0)
	s_barrier
	s_setprio 1
	v_mfma_f32_16x16x32_bf16 v[162:165], v[98:101], v[154:157], v[162:165]
	v_mfma_f32_16x16x32_bf16 v[158:161], v[122:125], v[154:157], v[158:161]
	v_mfma_f32_16x16x32_bf16 v[118:121], v[98:101], v[170:173], v[118:121]
	v_mfma_f32_16x16x32_bf16 v[114:117], v[122:125], v[170:173], v[114:117]
	v_mfma_f32_16x16x32_bf16 v[94:97], v[98:101], v[178:181], v[94:97]
	v_mfma_f32_16x16x32_bf16 v[90:93], v[122:125], v[178:181], v[90:93]
	v_mfma_f32_16x16x32_bf16 v[78:81], v[98:101], v[186:189], v[78:81]
	v_mfma_f32_16x16x32_bf16 v[74:77], v[122:125], v[186:189], v[74:77]
	v_mfma_f32_16x16x32_bf16 v[162:165], v[110:113], v[166:169], v[162:165]
	v_mfma_f32_16x16x32_bf16 v[158:161], v[126:129], v[166:169], v[158:161]
	v_mfma_f32_16x16x32_bf16 v[118:121], v[110:113], v[174:177], v[118:121]
	v_mfma_f32_16x16x32_bf16 v[114:117], v[126:129], v[174:177], v[114:117]
	v_mfma_f32_16x16x32_bf16 v[94:97], v[110:113], v[182:185], v[94:97]
	v_mfma_f32_16x16x32_bf16 v[90:93], v[126:129], v[182:185], v[90:93]
	v_mfma_f32_16x16x32_bf16 v[78:81], v[110:113], v[190:193], v[78:81]
	v_mfma_f32_16x16x32_bf16 v[74:77], v[126:129], v[190:193], v[74:77]
	s_setprio 0
	s_setprio 1
	v_mfma_f32_16x16x32_bf16 v[138:141], v[134:137], v[154:157], v[138:141]
	s_add_i32 s79, s73, s59
	v_mfma_f32_16x16x32_bf16 v[130:133], v[146:149], v[154:157], v[130:133]
	s_mov_b32 m0, s79
	v_mfma_f32_16x16x32_bf16 v[106:109], v[134:137], v[170:173], v[106:109]
	v_mfma_f32_16x16x32_bf16 v[102:105], v[146:149], v[170:173], v[102:105]
	v_mfma_f32_16x16x32_bf16 v[86:89], v[134:137], v[178:181], v[86:89]
	v_mfma_f32_16x16x32_bf16 v[82:85], v[146:149], v[178:181], v[82:85]
	v_mfma_f32_16x16x32_bf16 v[70:73], v[134:137], v[186:189], v[70:73]
	v_mfma_f32_16x16x32_bf16 v[66:69], v[146:149], v[186:189], v[66:69]
	v_mfma_f32_16x16x32_bf16 v[138:141], v[142:145], v[166:169], v[138:141]
	v_mfma_f32_16x16x32_bf16 v[130:133], v[150:153], v[166:169], v[130:133]
	v_mfma_f32_16x16x32_bf16 v[106:109], v[142:145], v[174:177], v[106:109]
	v_mfma_f32_16x16x32_bf16 v[102:105], v[150:153], v[174:177], v[102:105]
	v_mfma_f32_16x16x32_bf16 v[86:89], v[142:145], v[182:185], v[86:89]
	v_mfma_f32_16x16x32_bf16 v[82:85], v[150:153], v[182:185], v[82:85]
	v_mfma_f32_16x16x32_bf16 v[70:73], v[142:145], v[190:193], v[70:73]
	v_mfma_f32_16x16x32_bf16 v[66:69], v[150:153], v[190:193], v[66:69]
	s_setprio 0
	s_barrier
	v_lshl_add_u64 v[242:243], s[52:53], 0, v[196:197]
	ds_read_b128 v[154:157], v240 offset:16384
	ds_read_b128 v[166:169], v240 offset:17408
	ds_read_b128 v[170:173], v240 offset:18432
	ds_read_b128 v[174:177], v240 offset:19456
	ds_read_b128 v[178:181], v240 offset:20480
	ds_read_b128 v[182:185], v240 offset:21504
	ds_read_b128 v[186:189], v240 offset:22528
	ds_read_b128 v[190:193], v240 offset:23552
	global_load_lds_dwordx4 v[242:243], off
	s_add_i32 m0, s79, 0x2000
	s_add_u32 s82, s52, 0xb0000
	v_lshl_add_u64 v[244:245], s[52:53], 0, v[198:199]
	s_addc_u32 s83, s53, 0
	s_add_i32 s79, s74, s59
	global_load_lds_dwordx4 v[244:245], off
	v_lshl_add_u64 v[246:247], s[82:83], 0, v[196:197]
	s_mov_b32 m0, s79
	s_nop 0
	global_load_lds_dwordx4 v[246:247], off
	v_lshl_add_u64 v[246:247], s[82:83], 0, v[198:199]
	s_add_i32 m0, s79, 0x2000
	s_nop 0
	global_load_lds_dwordx4 v[246:247], off
	v_lshl_add_u64 v[246:247], s[80:81], 0, v[194:195]
	s_mov_b32 m0, s61
	v_lshl_add_u64 v[248:249], v[246:247], 0, s[10:11]
	global_load_lds_dwordx4 v[246:247], off
	s_mov_b32 m0, s62
	s_nop 0
	global_load_lds_dwordx4 v[248:249], off
	s_waitcnt vmcnt(8)
	s_waitcnt lgkmcnt(0)
	s_barrier
; #define PG8_STAGE(bufoff, gbase, voff) do { _Pragma("unroll") for (int _i = 0; _i < 2; ++_i) \
;         __builtin_amdgcn_global_load_lds((const unsigned*)((const char*)(gbase) + (voff)[_i]), (PG8_LAS unsigned*)(lds + (bufoff) + ldsw + _i * 8192), 16, 0, 0); } while (0)
; #define PG8_LDA(dst, b, h) do { _Pragma("unroll") for (int m = 0; m < 4; ++m) _Pragma("unroll") for (int k = 0; k < 2; ++k) dst[m][k] = *(const PG8_LAS bf16x8*)(lds + PG8_SA(b, h) + aoff + m * 2048 + k * 1024); } while (0)
; #define PG8_LDB(dst, b, h) do { _Pragma("unroll") for (int n = 0; n < 2; ++n) _Pragma("unroll") for (int k = 0; k < 2; ++k) dst[n][k] = *(const PG8_LAS bf16x8*)(lds + PG8_SB(b, h) + boff + n * 2048 + k * 1024); } while (0)
; #define PG8_WAIT_V(n) asm volatile("s_waitcnt vmcnt(" #n ")" ::: "memory")
; template <class Epi, bool ALIGN_EPI, bool ABLK = false>
; __device__ __forceinline__ void gemm_phase(PG8_LAS unsigned char* lds, const Gemm g, const StaticOrder& S, const Epi& E) {
;     ...
;         for (int t = 0; t < nt; t += 2) {
;             const bool last = (t == nt - 2);
;             const char* a1 = cA + (size_t)(t + 1) * kstepA;
;             const char* a2 = last ? nA : cA + (size_t)(t + 2) * kstepA; const char* b2 = last ? nB : cB + (size_t)(t + 2) * kstepB;
;             const char* a3 = a2 + kstepA; const char* b3 = b2 + kstepB;
;             PG8_LDB(B0, 0, 0); PG8_LDB(B1, 0, 1); PG8_SCHED; PG8_LDA(At, 0, 0); PG8_STAGE(PG8_SA(1, 1), a1 + hstepA, voffA);
;             PG8_WAIT_V(8); PG8_WAIT_L(0); PG8_BAR; PG8_MMA(0, 0, At, B0); PG8_MMA(0, 1, At, B1); PG8_BAR; PG8_SCHED;
;             PG8_LDA(At, 0, 1); PG8_STAGE(PG8_SB(0, 0), b2, voffB); PG8_STAGE(PG8_SB(0, 1), b2 + hstepB, voffB); PG8_STAGE(PG8_SA(0, 0), a2, voffA);
;             PG8_WAIT_V(8); PG8_WAIT_L(0); PG8_BAR; PG8_MMA(1, 0, At, B0); PG8_MMA(1, 1, At, B1); PG8_BAR; PG8_SCHED;
;             PG8_LDB(B0, 1, 0); PG8_LDB(B1, 1, 1); PG8_SCHED; PG8_LDA(At, 1, 0); PG8_STAGE(PG8_SA(0, 1), a2 + hstepA, voffA);
;             PG8_WAIT_V(8); PG8_WAIT_L(0); PG8_BAR; PG8_MMA(0, 0, At, B0); PG8_MMA(0, 1, At, B1); PG8_BAR; PG8_SCHED;
;             PG8_LDA(At, 1, 1); PG8_STAGE(PG8_SB(1, 0), b3, voffB); PG8_STAGE(PG8_SB(1, 1), b3 + hstepB, voffB); PG8_STAGE(PG8_SA(1, 0), a3, voffA);
;             PG8_WAIT_V(8); PG8_WAIT_L(0); PG8_BAR; PG8_MMA(1, 0, At, B0); PG8_MMA(1, 1, At, B1); PG8_BAR; PG8_SCHED;
	s_setprio 1
	v_mfma_f32_16x16x32_bf16 v[62:65], v[98:101], v[154:157], v[62:65]
	v_mfma_f32_16x16x32_bf16 v[58:61], v[122:125], v[154:157], v[58:61]
	v_mfma_f32_16x16x32_bf16 v[46:49], v[98:101], v[170:173], v[46:49]
	v_mfma_f32_16x16x32_bf16 v[42:45], v[122:125], v[170:173], v[42:45]
	v_mfma_f32_16x16x32_bf16 v[30:33], v[98:101], v[178:181], v[30:33]
	v_mfma_f32_16x16x32_bf16 v[26:29], v[122:125], v[178:181], v[26:29]
	v_mfma_f32_16x16x32_bf16 v[14:17], v[98:101], v[186:189], v[14:17]
	v_mfma_f32_16x16x32_bf16 v[10:13], v[122:125], v[186:189], v[10:13]
	v_mfma_f32_16x16x32_bf16 v[62:65], v[110:113], v[166:169], v[62:65]
	v_mfma_f32_16x16x32_bf16 v[58:61], v[126:129], v[166:169], v[58:61]
	v_mfma_f32_16x16x32_bf16 v[46:49], v[110:113], v[174:177], v[46:49]
	v_mfma_f32_16x16x32_bf16 v[42:45], v[126:129], v[174:177], v[42:45]
	v_mfma_f32_16x16x32_bf16 v[30:33], v[110:113], v[182:185], v[30:33]
	v_mfma_f32_16x16x32_bf16 v[26:29], v[126:129], v[182:185], v[26:29]
	v_mfma_f32_16x16x32_bf16 v[14:17], v[110:113], v[190:193], v[14:17]
	v_mfma_f32_16x16x32_bf16 v[10:13], v[126:129], v[190:193], v[10:13]
	s_setprio 0
	s_setprio 1
	v_mfma_f32_16x16x32_bf16 v[54:57], v[134:137], v[154:157], v[54:57]
	s_add_i32 s79, 0, 0x18000
	v_mfma_f32_16x16x32_bf16 v[50:53], v[146:149], v[154:157], v[50:53]
	s_add_i32 s80, 0, 0x1c000
	v_mfma_f32_16x16x32_bf16 v[38:41], v[134:137], v[170:173], v[38:41]
	v_mfma_f32_16x16x32_bf16 v[34:37], v[146:149], v[170:173], v[34:37]
	v_mfma_f32_16x16x32_bf16 v[22:25], v[134:137], v[178:181], v[22:25]
	v_mfma_f32_16x16x32_bf16 v[18:21], v[146:149], v[178:181], v[18:21]
	v_mfma_f32_16x16x32_bf16 v[6:9], v[134:137], v[186:189], v[6:9]
	v_mfma_f32_16x16x32_bf16 v[2:5], v[146:149], v[186:189], v[2:5]
	v_mfma_f32_16x16x32_bf16 v[54:57], v[142:145], v[166:169], v[54:57]
	v_mfma_f32_16x16x32_bf16 v[50:53], v[150:153], v[166:169], v[50:53]
	v_mfma_f32_16x16x32_bf16 v[38:41], v[142:145], v[174:177], v[38:41]
	v_mfma_f32_16x16x32_bf16 v[34:37], v[150:153], v[174:177], v[34:37]
	v_mfma_f32_16x16x32_bf16 v[22:25], v[142:145], v[182:185], v[22:25]
	v_mfma_f32_16x16x32_bf16 v[18:21], v[150:153], v[182:185], v[18:21]
	v_mfma_f32_16x16x32_bf16 v[6:9], v[142:145], v[190:193], v[6:9]
	v_mfma_f32_16x16x32_bf16 v[2:5], v[150:153], v[190:193], v[2:5]
	s_setprio 0
	s_barrier
	v_add_u32_e32 v126, s79, v230
	v_add_u32_e32 v150, s80, v230
	ds_read_b128 v[98:101], v126
	ds_read_b128 v[110:113], v126 offset:1024
	ds_read_b128 v[122:125], v126 offset:2048
	ds_read_b128 v[126:129], v126 offset:3072
	ds_read_b128 v[134:137], v150
	ds_read_b128 v[142:145], v150 offset:1024
	ds_read_b128 v[146:149], v150 offset:2048
	ds_read_b128 v[150:153], v150 offset:3072
	s_mov_b32 m0, s63
	v_lshl_add_u64 v[248:249], v[246:247], 0, s[12:13]
	ds_read_b128 v[154:157], v240 offset:32768
	ds_read_b128 v[166:169], v240 offset:33792
	ds_read_b128 v[170:173], v240 offset:34816
	ds_read_b128 v[174:177], v240 offset:35840
	ds_read_b128 v[178:181], v240 offset:36864
	ds_read_b128 v[182:185], v240 offset:37888
	ds_read_b128 v[186:189], v240 offset:38912
	ds_read_b128 v[190:193], v240 offset:39936
	global_load_lds_dwordx4 v[248:249], off
	v_lshl_add_u64 v[248:249], v[246:247], 0, s[24:25]
	s_mov_b32 m0, s64
	s_nop 0
	global_load_lds_dwordx4 v[248:249], off
	s_waitcnt vmcnt(8)
	s_waitcnt lgkmcnt(0)
	s_barrier
	s_setprio 1
	v_mfma_f32_16x16x32_bf16 v[162:165], v[98:101], v[154:157], v[162:165]
	v_mfma_f32_16x16x32_bf16 v[158:161], v[122:125], v[154:157], v[158:161]
	v_mfma_f32_16x16x32_bf16 v[118:121], v[98:101], v[170:173], v[118:121]
	v_mfma_f32_16x16x32_bf16 v[114:117], v[122:125], v[170:173], v[114:117]
	v_mfma_f32_16x16x32_bf16 v[94:97], v[98:101], v[178:181], v[94:97]
	v_mfma_f32_16x16x32_bf16 v[90:93], v[122:125], v[178:181], v[90:93]
	v_mfma_f32_16x16x32_bf16 v[78:81], v[98:101], v[186:189], v[78:81]
	v_mfma_f32_16x16x32_bf16 v[74:77], v[122:125], v[186:189], v[74:77]
	v_mfma_f32_16x16x32_bf16 v[162:165], v[110:113], v[166:169], v[162:165]
	v_mfma_f32_16x16x32_bf16 v[158:161], v[126:129], v[166:169], v[158:161]
	v_mfma_f32_16x16x32_bf16 v[118:121], v[110:113], v[174:177], v[118:121]
	v_mfma_f32_16x16x32_bf16 v[114:117], v[126:129], v[174:177], v[114:117]
	v_mfma_f32_16x16x32_bf16 v[94:97], v[110:113], v[182:185], v[94:97]
	v_mfma_f32_16x16x32_bf16 v[90:93], v[126:129], v[182:185], v[90:93]
	v_mfma_f32_16x16x32_bf16 v[78:81], v[110:113], v[190:193], v[78:81]
	v_mfma_f32_16x16x32_bf16 v[74:77], v[126:129], v[190:193], v[74:77]
	s_setprio 0
	s_setprio 1
	v_mfma_f32_16x16x32_bf16 v[138:141], v[134:137], v[154:157], v[138:141]
	s_add_i32 s79, s79, s59
	v_mfma_f32_16x16x32_bf16 v[130:133], v[146:149], v[154:157], v[130:133]
	s_mov_b32 m0, s79
	v_mfma_f32_16x16x32_bf16 v[106:109], v[134:137], v[170:173], v[106:109]
	v_mfma_f32_16x16x32_bf16 v[102:105], v[146:149], v[170:173], v[102:105]
	v_mfma_f32_16x16x32_bf16 v[86:89], v[134:137], v[178:181], v[86:89]
	v_mfma_f32_16x16x32_bf16 v[82:85], v[146:149], v[178:181], v[82:85]
	v_mfma_f32_16x16x32_bf16 v[70:73], v[134:137], v[186:189], v[70:73]
	v_mfma_f32_16x16x32_bf16 v[66:69], v[146:149], v[186:189], v[66:69]
	v_mfma_f32_16x16x32_bf16 v[138:141], v[142:145], v[166:169], v[138:141]
	v_mfma_f32_16x16x32_bf16 v[130:133], v[150:153], v[166:169], v[130:133]
	v_mfma_f32_16x16x32_bf16 v[106:109], v[142:145], v[174:177], v[106:109]
	v_mfma_f32_16x16x32_bf16 v[102:105], v[150:153], v[174:177], v[102:105]
	v_mfma_f32_16x16x32_bf16 v[86:89], v[142:145], v[182:185], v[86:89]
	v_mfma_f32_16x16x32_bf16 v[82:85], v[150:153], v[182:185], v[82:85]
	v_mfma_f32_16x16x32_bf16 v[70:73], v[142:145], v[190:193], v[70:73]
	v_mfma_f32_16x16x32_bf16 v[66:69], v[150:153], v[190:193], v[66:69]
	s_setprio 0
	s_barrier
; #define PG8_STAGE(bufoff, gbase, voff) do { _Pragma("unroll") for (int _i = 0; _i < 2; ++_i) \
;         __builtin_amdgcn_global_load_lds((const unsigned*)((const char*)(gbase) + (voff)[_i]), (PG8_LAS unsigned*)(lds + (bufoff) + ldsw + _i * 8192), 16, 0, 0); } while (0)
; #define PG8_LDA(dst, b, h) do { _Pragma("unroll") for (int m = 0; m < 4; ++m) _Pragma("unroll") for (int k = 0; k < 2; ++k) dst[m][k] = *(const PG8_LAS bf16x8*)(lds + PG8_SA(b, h) + aoff + m * 2048 + k * 1024); } while (0)
; #define PG8_LDB(dst, b, h) do { _Pragma("unroll") for (int n = 0; n < 2; ++n) _Pragma("unroll") for (int k = 0; k < 2; ++k) dst[n][k] = *(const PG8_LAS bf16x8*)(lds + PG8_SB(b, h) + boff + n * 2048 + k * 1024); } while (0)
; #define PG8_WAIT_V(n) asm volatile("s_waitcnt vmcnt(" #n ")" ::: "memory")
; template <class Epi, bool ALIGN_EPI, bool ABLK = false>
; __device__ __forceinline__ void gemm_phase(PG8_LAS unsigned char* lds, const Gemm g, const StaticOrder& S, const Epi& E) {
;     ...
;         for (int t = 0; t < nt; t += 2) {
;             const bool last = (t == nt - 2);
;             const char* a1 = cA + (size_t)(t + 1) * kstepA;
;             const char* a2 = last ? nA : cA + (size_t)(t + 2) * kstepA; const char* b2 = last ? nB : cB + (size_t)(t + 2) * kstepB;
;             const char* a3 = a2 + kstepA; const char* b3 = b2 + kstepB;
;             PG8_LDB(B0, 0, 0); PG8_LDB(B1, 0, 1); PG8_SCHED; PG8_LDA(At, 0, 0); PG8_STAGE(PG8_SA(1, 1), a1 + hstepA, voffA);
;             PG8_WAIT_V(8); PG8_WAIT_L(0); PG8_BAR; PG8_MMA(0, 0, At, B0); PG8_MMA(0, 1, At, B1); PG8_BAR; PG8_SCHED;
;             PG8_LDA(At, 0, 1); PG8_STAGE(PG8_SB(0, 0), b2, voffB); PG8_STAGE(PG8_SB(0, 1), b2 + hstepB, voffB); PG8_STAGE(PG8_SA(0, 0), a2, voffA);
;             PG8_WAIT_V(8); PG8_WAIT_L(0); PG8_BAR; PG8_MMA(1, 0, At, B0); PG8_MMA(1, 1, At, B1); PG8_BAR; PG8_SCHED;
;             PG8_LDB(B0, 1, 0); PG8_LDB(B1, 1, 1); PG8_SCHED; PG8_LDA(At, 1, 0); PG8_STAGE(PG8_SA(0, 1), a2 + hstepA, voffA);
;             PG8_WAIT_V(8); PG8_WAIT_L(0); PG8_BAR; PG8_MMA(0, 0, At, B0); PG8_MMA(0, 1, At, B1); PG8_BAR; PG8_SCHED;
;             PG8_LDA(At, 1, 1); PG8_STAGE(PG8_SB(1, 0), b3, voffB); PG8_STAGE(PG8_SB(1, 1), b3 + hstepB, voffB); PG8_STAGE(PG8_SA(1, 0), a3, voffA);
;             PG8_WAIT_V(8); PG8_WAIT_L(0); PG8_BAR; PG8_MMA(1, 0, At, B0); PG8_MMA(1, 1, At, B1); PG8_BAR; PG8_SCHED;
	v_lshl_add_u64 v[242:243], v[242:243], 0, s[34:35]
	ds_read_b128 v[154:157], v240 offset:49152
	ds_read_b128 v[166:169], v240 offset:50176
	ds_read_b128 v[170:173], v240 offset:51200
	ds_read_b128 v[174:177], v240 offset:52224
	ds_read_b128 v[178:181], v240 offset:53248
	ds_read_b128 v[182:185], v240 offset:54272
	ds_read_b128 v[186:189], v240 offset:55296
	ds_read_b128 v[190:193], v240 offset:56320
	global_load_lds_dwordx4 v[242:243], off
	s_add_i32 m0, s79, 0x2000
	s_add_u32 s52, s52, 0xb0080
	v_lshl_add_u64 v[242:243], v[244:245], 0, s[34:35]
	s_addc_u32 s53, s53, 0
	s_add_i32 s79, s80, s59
	global_load_lds_dwordx4 v[242:243], off
	v_lshl_add_u64 v[242:243], s[52:53], 0, v[196:197]
	s_mov_b32 m0, s79
	s_nop 0
	global_load_lds_dwordx4 v[242:243], off
	v_lshl_add_u64 v[242:243], s[52:53], 0, v[198:199]
	s_add_i32 m0, s79, 0x2000
	s_nop 0
	global_load_lds_dwordx4 v[242:243], off
	v_lshl_add_u64 v[242:243], v[246:247], 0, s[36:37]
	s_mov_b32 m0, s67
	s_nop 0
	global_load_lds_dwordx4 v[242:243], off
	v_lshl_add_u64 v[242:243], v[246:247], 0, s[38:39]
	s_mov_b32 m0, s68
	s_nop 0
	global_load_lds_dwordx4 v[242:243], off
	s_waitcnt vmcnt(8)
	s_waitcnt lgkmcnt(0)
	s_barrier
	s_setprio 1
	v_mfma_f32_16x16x32_bf16 v[62:65], v[98:101], v[154:157], v[62:65]
	v_mfma_f32_16x16x32_bf16 v[58:61], v[122:125], v[154:157], v[58:61]
	v_mfma_f32_16x16x32_bf16 v[46:49], v[98:101], v[170:173], v[46:49]
	v_mfma_f32_16x16x32_bf16 v[42:45], v[122:125], v[170:173], v[42:45]
	v_mfma_f32_16x16x32_bf16 v[30:33], v[98:101], v[178:181], v[30:33]
	v_mfma_f32_16x16x32_bf16 v[26:29], v[122:125], v[178:181], v[26:29]
	v_mfma_f32_16x16x32_bf16 v[14:17], v[98:101], v[186:189], v[14:17]
	v_mfma_f32_16x16x32_bf16 v[10:13], v[122:125], v[186:189], v[10:13]
	v_mfma_f32_16x16x32_bf16 v[62:65], v[110:113], v[166:169], v[62:65]
	v_mfma_f32_16x16x32_bf16 v[58:61], v[126:129], v[166:169], v[58:61]
	v_mfma_f32_16x16x32_bf16 v[46:49], v[110:113], v[174:177], v[46:49]
	v_mfma_f32_16x16x32_bf16 v[42:45], v[126:129], v[174:177], v[42:45]
	v_mfma_f32_16x16x32_bf16 v[30:33], v[110:113], v[182:185], v[30:33]
	v_mfma_f32_16x16x32_bf16 v[26:29], v[126:129], v[182:185], v[26:29]
	v_mfma_f32_16x16x32_bf16 v[14:17], v[110:113], v[190:193], v[14:17]
	v_mfma_f32_16x16x32_bf16 v[10:13], v[126:129], v[190:193], v[10:13]
	s_setprio 0
	s_setprio 1
	v_mfma_f32_16x16x32_bf16 v[54:57], v[134:137], v[154:157], v[54:57]
	s_add_i32 s78, s78, 2
	v_mfma_f32_16x16x32_bf16 v[50:53], v[146:149], v[154:157], v[50:53]
	s_add_u32 s54, s54, 0x100
	v_mfma_f32_16x16x32_bf16 v[38:41], v[134:137], v[170:173], v[38:41]
	s_addc_u32 s55, s55, 0
	v_mfma_f32_16x16x32_bf16 v[34:37], v[146:149], v[170:173], v[34:37]
	s_add_u32 s50, s50, 0x10000
	v_mfma_f32_16x16x32_bf16 v[22:25], v[134:137], v[178:181], v[22:25]
	s_addc_u32 s51, s51, 0
	v_mfma_f32_16x16x32_bf16 v[18:21], v[146:149], v[178:181], v[18:21]
	s_cmp_gt_u32 s78, 41
	v_mfma_f32_16x16x32_bf16 v[6:9], v[134:137], v[186:189], v[6:9]
	v_mfma_f32_16x16x32_bf16 v[2:5], v[146:149], v[186:189], v[2:5]
	v_mfma_f32_16x16x32_bf16 v[54:57], v[142:145], v[166:169], v[54:57]
	v_mfma_f32_16x16x32_bf16 v[50:53], v[150:153], v[166:169], v[50:53]
	v_mfma_f32_16x16x32_bf16 v[38:41], v[142:145], v[174:177], v[38:41]
	v_mfma_f32_16x16x32_bf16 v[34:37], v[150:153], v[174:177], v[34:37]
	v_mfma_f32_16x16x32_bf16 v[22:25], v[142:145], v[182:185], v[22:25]
	v_mfma_f32_16x16x32_bf16 v[18:21], v[150:153], v[182:185], v[18:21]
	v_mfma_f32_16x16x32_bf16 v[6:9], v[142:145], v[190:193], v[6:9]
	v_mfma_f32_16x16x32_bf16 v[2:5], v[150:153], v[190:193], v[2:5]
	s_setprio 0
	s_barrier
	s_cbranch_scc0 .LBB0_540
	s_and_b64 vcc, exec, s[40:41]
	s_cbranch_vccz .LBB0_543
	s_barrier

; #define PG8_STAGE(bufoff, gbase, voff) do { _Pragma("unroll") for (int _i = 0; _i < 2; ++_i) \
;         __builtin_amdgcn_global_load_lds((const unsigned*)((const char*)(gbase) + (voff)[_i]), (PG8_LAS unsigned*)(lds + (bufoff) + ldsw + _i * 8192), 16, 0, 0); } while (0)
; #define PG8_LDA(dst, b, h) do { _Pragma("unroll") for (int m = 0; m < 4; ++m) _Pragma("unroll") for (int k = 0; k < 2; ++k) dst[m][k] = *(const PG8_LAS bf16x8*)(lds + PG8_SA(b, h) + aoff + m * 2048 + k * 1024); } while (0)
; #define PG8_LDB(dst, b, h) do { _Pragma("unroll") for (int n = 0; n < 2; ++n) _Pragma("unroll") for (int k = 0; k < 2; ++k) dst[n][k] = *(const PG8_LAS bf16x8*)(lds + PG8_SB(b, h) + boff + n * 2048 + k * 1024); } while (0)
; #define PG8_WAIT_V(n) asm volatile("s_waitcnt vmcnt(" #n ")" ::: "memory")
; template <class Epi, bool ALIGN_EPI, bool ABLK = false>
; __device__ __forceinline__ void gemm_phase(PG8_LAS unsigned char* lds, const Gemm g, const StaticOrder& S, const Epi& E) {
;     ...
;         for (int t = 0; t < nt; t += 2) {
;             const bool last = (t == nt - 2);
;             const char* a1 = cA + (size_t)(t + 1) * kstepA;
;             const char* a2 = last ? nA : cA + (size_t)(t + 2) * kstepA; const char* b2 = last ? nB : cB + (size_t)(t + 2) * kstepB;
;             const char* a3 = a2 + kstepA; const char* b3 = b2 + kstepB;
;             PG8_LDB(B0, 0, 0); PG8_LDB(B1, 0, 1); PG8_SCHED; PG8_LDA(At, 0, 0); PG8_STAGE(PG8_SA(1, 1), a1 + hstepA, voffA);
;             PG8_WAIT_V(8); PG8_WAIT_L(0); PG8_BAR; PG8_MMA(0, 0, At, B0); PG8_MMA(0, 1, At, B1); PG8_BAR; PG8_SCHED;
;             PG8_LDA(At, 0, 1); PG8_STAGE(PG8_SB(0, 0), b2, voffB); PG8_STAGE(PG8_SB(0, 1), b2 + hstepB, voffB); PG8_STAGE(PG8_SA(0, 0), a2, voffA);
;             PG8_WAIT_V(8); PG8_WAIT_L(0); PG8_BAR; PG8_MMA(1, 0, At, B0); PG8_MMA(1, 1, At, B1); PG8_BAR; PG8_SCHED;
;             PG8_LDB(B0, 1, 0); PG8_LDB(B1, 1, 1); PG8_SCHED; PG8_LDA(At, 1, 0); PG8_STAGE(PG8_SA(0, 1), a2 + hstepA, voffA);
;             PG8_WAIT_V(8); PG8_WAIT_L(0); PG8_BAR; PG8_MMA(0, 0, At, B0); PG8_MMA(0, 1, At, B1); PG8_BAR; PG8_SCHED;
;             PG8_LDA(At, 1, 1); PG8_STAGE(PG8_SB(1, 0), b3, voffB); PG8_STAGE(PG8_SB(1, 1), b3 + hstepB, voffB); PG8_STAGE(PG8_SA(1, 0), a3, voffA);
;             PG8_WAIT_V(8); PG8_WAIT_L(0); PG8_BAR; PG8_MMA(1, 0, At, B0); PG8_MMA(1, 1, At, B1); PG8_BAR; PG8_SCHED;
.LBB0_818:
	ds_read_b128 v[132:135], v153
	ds_read_b128 v[136:139], v153 offset:1024
	ds_read_b128 v[140:143], v153 offset:2048
	ds_read_b128 v[144:147], v153 offset:3072
	ds_read_b128 v[148:151], v153 offset:16384
	ds_read_b128 v[178:181], v153 offset:17408
	ds_read_b128 v[182:185], v153 offset:18432
	ds_read_b128 v[212:215], v153 offset:19456
	s_add_u32 s12, s38, s10
	s_addc_u32 s13, s39, s11
	s_sub_u32 s98, s12, 0x10000
	s_subb_u32 s99, s13, 0
	s_cmp_eq_u32 s65, 12
	s_cselect_b32 s101, s33, s13
	s_cselect_b32 s100, s57, s12
	s_cselect_b32 s13, s55, s64
	s_cselect_b32 s12, s62, s63
	s_mov_b64 s[68:69], 0xc000
	s_add_i32 m0, s35, 0xc000
	s_mov_b64 s[68:69], 0xe000
	ds_read_b128 v[216:219], v205
	ds_read_b128 v[220:223], v205 offset:1024
	ds_read_b128 v[224:227], v205 offset:2048
	ds_read_b128 v[228:231], v205 offset:3072
	ds_read_b128 v[232:235], v205 offset:4096
	ds_read_b128 v[236:239], v205 offset:5120
	ds_read_b128 v[240:243], v205 offset:6144
	ds_read_b128 v[244:247], v205 offset:7168
	global_load_lds_dwordx4 v253, s[98:99]
	s_add_i32 m0, s35, 0xe000
	s_nop 0
	global_load_lds_dwordx4 v152, s[98:99]
	s_waitcnt vmcnt(8)
	s_waitcnt lgkmcnt(0)
	s_barrier
	s_setprio 1
	v_mfma_f32_16x16x32_bf16 v[126:129], v[132:135], v[216:219], v[126:129]
	v_mfma_f32_16x16x32_bf16 v[122:125], v[140:143], v[216:219], v[122:125]
	v_mfma_f32_16x16x32_bf16 v[118:121], v[132:135], v[224:227], v[118:121]
	v_mfma_f32_16x16x32_bf16 v[114:117], v[140:143], v[224:227], v[114:117]
	v_mfma_f32_16x16x32_bf16 v[110:113], v[132:135], v[232:235], v[110:113]
	v_mfma_f32_16x16x32_bf16 v[106:109], v[140:143], v[232:235], v[106:109]
	v_mfma_f32_16x16x32_bf16 v[102:105], v[132:135], v[240:243], v[102:105]
	v_mfma_f32_16x16x32_bf16 v[98:101], v[140:143], v[240:243], v[98:101]
	v_mfma_f32_16x16x32_bf16 v[126:129], v[136:139], v[220:223], v[126:129]
	v_mfma_f32_16x16x32_bf16 v[122:125], v[144:147], v[220:223], v[122:125]
	v_mfma_f32_16x16x32_bf16 v[118:121], v[136:139], v[228:231], v[118:121]
	v_mfma_f32_16x16x32_bf16 v[114:117], v[144:147], v[228:231], v[114:117]
	v_mfma_f32_16x16x32_bf16 v[110:113], v[136:139], v[236:239], v[110:113]
	v_mfma_f32_16x16x32_bf16 v[106:109], v[144:147], v[236:239], v[106:109]
	v_mfma_f32_16x16x32_bf16 v[102:105], v[136:139], v[244:247], v[102:105]
	v_mfma_f32_16x16x32_bf16 v[98:101], v[144:147], v[244:247], v[98:101]
	s_setprio 0
	s_setprio 1
	v_mfma_f32_16x16x32_bf16 v[94:97], v[148:151], v[216:219], v[94:97]
	s_add_i32 s68, s42, s31
	v_mfma_f32_16x16x32_bf16 v[90:93], v[182:185], v[216:219], v[90:93]
	s_mov_b32 m0, s68
	v_mfma_f32_16x16x32_bf16 v[86:89], v[148:151], v[224:227], v[86:89]
	v_mfma_f32_16x16x32_bf16 v[82:85], v[182:185], v[224:227], v[82:85]
	v_mfma_f32_16x16x32_bf16 v[78:81], v[148:151], v[232:235], v[78:81]
	v_mfma_f32_16x16x32_bf16 v[74:77], v[182:185], v[232:235], v[74:77]
	v_mfma_f32_16x16x32_bf16 v[70:73], v[148:151], v[240:243], v[70:73]
	v_mfma_f32_16x16x32_bf16 v[66:69], v[182:185], v[240:243], v[66:69]
	v_mfma_f32_16x16x32_bf16 v[94:97], v[178:181], v[220:223], v[94:97]
	v_mfma_f32_16x16x32_bf16 v[90:93], v[212:215], v[220:223], v[90:93]
	v_mfma_f32_16x16x32_bf16 v[86:89], v[178:181], v[228:231], v[86:89]
	v_mfma_f32_16x16x32_bf16 v[82:85], v[212:215], v[228:231], v[82:85]
	v_mfma_f32_16x16x32_bf16 v[78:81], v[178:181], v[236:239], v[78:81]
	v_mfma_f32_16x16x32_bf16 v[74:77], v[212:215], v[236:239], v[74:77]
	v_mfma_f32_16x16x32_bf16 v[70:73], v[178:181], v[244:247], v[70:73]
	v_mfma_f32_16x16x32_bf16 v[66:69], v[212:215], v[244:247], v[66:69]
	s_setprio 0
	s_barrier
	ds_read_b128 v[216:219], v205 offset:16384
	ds_read_b128 v[220:223], v205 offset:17408
	ds_read_b128 v[224:227], v205 offset:18432
	ds_read_b128 v[228:231], v205 offset:19456
	ds_read_b128 v[232:235], v205 offset:20480
	ds_read_b128 v[236:239], v205 offset:21504
	ds_read_b128 v[240:243], v205 offset:22528
	ds_read_b128 v[244:247], v205 offset:23552
	global_load_lds_dwordx4 v156, s[12:13]
	s_add_i32 m0, s68, 0x2000
	s_add_u32 s68, s12, 0x40000
	s_addc_u32 s69, s13, 0
	s_add_i32 s70, s43, s31
	global_load_lds_dwordx4 v158, s[12:13]
	s_mov_b32 m0, s70
	s_nop 0
	global_load_lds_dwordx4 v156, s[68:69]
	s_add_i32 m0, s70, 0x2000
	s_nop 0
	global_load_lds_dwordx4 v158, s[68:69]
	s_mov_b32 m0, s35
	s_mov_b64 s[66:67], 0x2000
	global_load_lds_dwordx4 v154, s[100:101]
	s_mov_b32 m0, s18
	s_nop 0
	global_load_lds_dwordx4 v248, s[100:101]
	s_waitcnt vmcnt(8)
	s_waitcnt lgkmcnt(0)
	s_barrier
	s_setprio 1
	v_mfma_f32_16x16x32_bf16 v[62:65], v[132:135], v[216:219], v[62:65]
	v_mfma_f32_16x16x32_bf16 v[58:61], v[140:143], v[216:219], v[58:61]
	v_mfma_f32_16x16x32_bf16 v[54:57], v[132:135], v[224:227], v[54:57]
	v_mfma_f32_16x16x32_bf16 v[50:53], v[140:143], v[224:227], v[50:53]
	v_mfma_f32_16x16x32_bf16 v[46:49], v[132:135], v[232:235], v[46:49]
	v_mfma_f32_16x16x32_bf16 v[42:45], v[140:143], v[232:235], v[42:45]
	v_mfma_f32_16x16x32_bf16 v[38:41], v[132:135], v[240:243], v[38:41]
	v_mfma_f32_16x16x32_bf16 v[34:37], v[140:143], v[240:243], v[34:37]
	v_mfma_f32_16x16x32_bf16 v[62:65], v[136:139], v[220:223], v[62:65]
	v_mfma_f32_16x16x32_bf16 v[58:61], v[144:147], v[220:223], v[58:61]
	v_mfma_f32_16x16x32_bf16 v[54:57], v[136:139], v[228:231], v[54:57]
	v_mfma_f32_16x16x32_bf16 v[50:53], v[144:147], v[228:231], v[50:53]
	v_mfma_f32_16x16x32_bf16 v[46:49], v[136:139], v[236:239], v[46:49]
	v_mfma_f32_16x16x32_bf16 v[42:45], v[144:147], v[236:239], v[42:45]
	v_mfma_f32_16x16x32_bf16 v[38:41], v[136:139], v[244:247], v[38:41]
	v_mfma_f32_16x16x32_bf16 v[34:37], v[144:147], v[244:247], v[34:37]
	s_setprio 0
	s_setprio 1
	v_mfma_f32_16x16x32_bf16 v[30:33], v[148:151], v[216:219], v[30:33]
	s_add_i32 s68, 0, 0x18000
	v_mfma_f32_16x16x32_bf16 v[26:29], v[182:185], v[216:219], v[26:29]
	s_add_i32 s69, 0, 0x1c000
	v_mfma_f32_16x16x32_bf16 v[22:25], v[148:151], v[224:227], v[22:25]
	v_mfma_f32_16x16x32_bf16 v[18:21], v[182:185], v[224:227], v[18:21]
	v_mfma_f32_16x16x32_bf16 v[14:17], v[148:151], v[232:235], v[14:17]
	v_mfma_f32_16x16x32_bf16 v[10:13], v[182:185], v[232:235], v[10:13]
	v_mfma_f32_16x16x32_bf16 v[6:9], v[148:151], v[240:243], v[6:9]
	v_mfma_f32_16x16x32_bf16 v[2:5], v[182:185], v[240:243], v[2:5]
	v_mfma_f32_16x16x32_bf16 v[30:33], v[178:181], v[220:223], v[30:33]
	v_mfma_f32_16x16x32_bf16 v[26:29], v[212:215], v[220:223], v[26:29]
	v_mfma_f32_16x16x32_bf16 v[22:25], v[178:181], v[228:231], v[22:25]
	v_mfma_f32_16x16x32_bf16 v[18:21], v[212:215], v[228:231], v[18:21]
	v_mfma_f32_16x16x32_bf16 v[14:17], v[178:181], v[236:239], v[14:17]
	v_mfma_f32_16x16x32_bf16 v[10:13], v[212:215], v[236:239], v[10:13]
	v_mfma_f32_16x16x32_bf16 v[6:9], v[178:181], v[244:247], v[6:9]
	v_mfma_f32_16x16x32_bf16 v[2:5], v[212:215], v[244:247], v[2:5]
	s_setprio 0
	s_barrier
; #define PG8_STAGE(bufoff, gbase, voff) do { _Pragma("unroll") for (int _i = 0; _i < 2; ++_i) \
;         __builtin_amdgcn_global_load_lds((const unsigned*)((const char*)(gbase) + (voff)[_i]), (PG8_LAS unsigned*)(lds + (bufoff) + ldsw + _i * 8192), 16, 0, 0); } while (0)
; #define PG8_LDA(dst, b, h) do { _Pragma("unroll") for (int m = 0; m < 4; ++m) _Pragma("unroll") for (int k = 0; k < 2; ++k) dst[m][k] = *(const PG8_LAS bf16x8*)(lds + PG8_SA(b, h) + aoff + m * 2048 + k * 1024); } while (0)
; #define PG8_LDB(dst, b, h) do { _Pragma("unroll") for (int n = 0; n < 2; ++n) _Pragma("unroll") for (int k = 0; k < 2; ++k) dst[n][k] = *(const PG8_LAS bf16x8*)(lds + PG8_SB(b, h) + boff + n * 2048 + k * 1024); } while (0)
; #define PG8_WAIT_V(n) asm volatile("s_waitcnt vmcnt(" #n ")" ::: "memory")
; template <class Epi, bool ALIGN_EPI, bool ABLK = false>
; __device__ __forceinline__ void gemm_phase(PG8_LAS unsigned char* lds, const Gemm g, const StaticOrder& S, const Epi& E) {
;     ...
;         for (int t = 0; t < nt; t += 2) {
;             const bool last = (t == nt - 2);
;             const char* a1 = cA + (size_t)(t + 1) * kstepA;
;             const char* a2 = last ? nA : cA + (size_t)(t + 2) * kstepA; const char* b2 = last ? nB : cB + (size_t)(t + 2) * kstepB;
;             const char* a3 = a2 + kstepA; const char* b3 = b2 + kstepB;
;             PG8_LDB(B0, 0, 0); PG8_LDB(B1, 0, 1); PG8_SCHED; PG8_LDA(At, 0, 0); PG8_STAGE(PG8_SA(1, 1), a1 + hstepA, voffA);
;             PG8_WAIT_V(8); PG8_WAIT_L(0); PG8_BAR; PG8_MMA(0, 0, At, B0); PG8_MMA(0, 1, At, B1); PG8_BAR; PG8_SCHED;
;             PG8_LDA(At, 0, 1); PG8_STAGE(PG8_SB(0, 0), b2, voffB); PG8_STAGE(PG8_SB(0, 1), b2 + hstepB, voffB); PG8_STAGE(PG8_SA(0, 0), a2, voffA);
;             PG8_WAIT_V(8); PG8_WAIT_L(0); PG8_BAR; PG8_MMA(1, 0, At, B0); PG8_MMA(1, 1, At, B1); PG8_BAR; PG8_SCHED;
;             PG8_LDB(B0, 1, 0); PG8_LDB(B1, 1, 1); PG8_SCHED; PG8_LDA(At, 1, 0); PG8_STAGE(PG8_SA(0, 1), a2 + hstepA, voffA);
;             PG8_WAIT_V(8); PG8_WAIT_L(0); PG8_BAR; PG8_MMA(0, 0, At, B0); PG8_MMA(0, 1, At, B1); PG8_BAR; PG8_SCHED;
;             PG8_LDA(At, 1, 1); PG8_STAGE(PG8_SB(1, 0), b3, voffB); PG8_STAGE(PG8_SB(1, 1), b3 + hstepB, voffB); PG8_STAGE(PG8_SA(1, 0), a3, voffA);
;             PG8_WAIT_V(8); PG8_WAIT_L(0); PG8_BAR; PG8_MMA(1, 0, At, B0); PG8_MMA(1, 1, At, B1); PG8_BAR; PG8_SCHED;
	ds_read_b128 v[132:135], v153 offset:32768
	ds_read_b128 v[136:139], v153 offset:33792
	ds_read_b128 v[140:143], v153 offset:34816
	ds_read_b128 v[144:147], v153 offset:35840
	ds_read_b128 v[148:151], v153 offset:49152
	ds_read_b128 v[178:181], v153 offset:50176
	ds_read_b128 v[182:185], v153 offset:51200
	ds_read_b128 v[212:215], v153 offset:52224
	s_mov_b64 s[66:67], 0x4000
	s_mov_b32 m0, s28
	s_mov_b64 s[66:67], 0x6000
	ds_read_b128 v[216:219], v205 offset:32768
	ds_read_b128 v[220:223], v205 offset:33792
	ds_read_b128 v[224:227], v205 offset:34816
	ds_read_b128 v[228:231], v205 offset:35840
	ds_read_b128 v[232:235], v205 offset:36864
	ds_read_b128 v[236:239], v205 offset:37888
	ds_read_b128 v[240:243], v205 offset:38912
	ds_read_b128 v[244:247], v205 offset:39936
	global_load_lds_dwordx4 v249, s[100:101]
	s_mov_b32 m0, s29
	s_nop 0
	global_load_lds_dwordx4 v250, s[100:101]
	s_waitcnt vmcnt(8)
	s_waitcnt lgkmcnt(0)
	s_barrier
	s_setprio 1
	v_mfma_f32_16x16x32_bf16 v[126:129], v[132:135], v[216:219], v[126:129]
	v_mfma_f32_16x16x32_bf16 v[122:125], v[140:143], v[216:219], v[122:125]
	v_mfma_f32_16x16x32_bf16 v[118:121], v[132:135], v[224:227], v[118:121]
	v_mfma_f32_16x16x32_bf16 v[114:117], v[140:143], v[224:227], v[114:117]
	v_mfma_f32_16x16x32_bf16 v[110:113], v[132:135], v[232:235], v[110:113]
	v_mfma_f32_16x16x32_bf16 v[106:109], v[140:143], v[232:235], v[106:109]
	v_mfma_f32_16x16x32_bf16 v[102:105], v[132:135], v[240:243], v[102:105]
	v_mfma_f32_16x16x32_bf16 v[98:101], v[140:143], v[240:243], v[98:101]
	v_mfma_f32_16x16x32_bf16 v[126:129], v[136:139], v[220:223], v[126:129]
	v_mfma_f32_16x16x32_bf16 v[122:125], v[144:147], v[220:223], v[122:125]
	v_mfma_f32_16x16x32_bf16 v[118:121], v[136:139], v[228:231], v[118:121]
	v_mfma_f32_16x16x32_bf16 v[114:117], v[144:147], v[228:231], v[114:117]
	v_mfma_f32_16x16x32_bf16 v[110:113], v[136:139], v[236:239], v[110:113]
	v_mfma_f32_16x16x32_bf16 v[106:109], v[144:147], v[236:239], v[106:109]
	v_mfma_f32_16x16x32_bf16 v[102:105], v[136:139], v[244:247], v[102:105]
	v_mfma_f32_16x16x32_bf16 v[98:101], v[144:147], v[244:247], v[98:101]
	s_setprio 0
	s_setprio 1
	v_mfma_f32_16x16x32_bf16 v[94:97], v[148:151], v[216:219], v[94:97]
	s_add_i32 s66, s68, s31
	v_mfma_f32_16x16x32_bf16 v[90:93], v[182:185], v[216:219], v[90:93]
	s_add_u32 s12, s12, s46
	v_mfma_f32_16x16x32_bf16 v[86:89], v[148:151], v[224:227], v[86:89]
	s_addc_u32 s13, s13, s47
	v_mfma_f32_16x16x32_bf16 v[82:85], v[182:185], v[224:227], v[82:85]
	s_mov_b32 m0, s66
	v_mfma_f32_16x16x32_bf16 v[78:81], v[148:151], v[232:235], v[78:81]
	v_mfma_f32_16x16x32_bf16 v[74:77], v[182:185], v[232:235], v[74:77]
	v_mfma_f32_16x16x32_bf16 v[70:73], v[148:151], v[240:243], v[70:73]
	v_mfma_f32_16x16x32_bf16 v[66:69], v[182:185], v[240:243], v[66:69]
	v_mfma_f32_16x16x32_bf16 v[94:97], v[178:181], v[220:223], v[94:97]
	v_mfma_f32_16x16x32_bf16 v[90:93], v[212:215], v[220:223], v[90:93]
	v_mfma_f32_16x16x32_bf16 v[86:89], v[178:181], v[228:231], v[86:89]
	v_mfma_f32_16x16x32_bf16 v[82:85], v[212:215], v[228:231], v[82:85]
	v_mfma_f32_16x16x32_bf16 v[78:81], v[178:181], v[236:239], v[78:81]
	v_mfma_f32_16x16x32_bf16 v[74:77], v[212:215], v[236:239], v[74:77]
	v_mfma_f32_16x16x32_bf16 v[70:73], v[178:181], v[244:247], v[70:73]
	v_mfma_f32_16x16x32_bf16 v[66:69], v[212:215], v[244:247], v[66:69]
	s_setprio 0
	s_barrier
	ds_read_b128 v[216:219], v205 offset:49152
	ds_read_b128 v[220:223], v205 offset:50176
	ds_read_b128 v[224:227], v205 offset:51200
	ds_read_b128 v[228:231], v205 offset:52224
	ds_read_b128 v[232:235], v205 offset:53248
	ds_read_b128 v[236:239], v205 offset:54272
	ds_read_b128 v[240:243], v205 offset:55296
	ds_read_b128 v[244:247], v205 offset:56320
	global_load_lds_dwordx4 v156, s[12:13]
	s_add_i32 m0, s66, 0x2000
	s_add_i32 s66, s69, s31
	global_load_lds_dwordx4 v158, s[12:13]
	s_add_u32 s12, s12, 0x40000
	s_addc_u32 s13, s13, 0
	s_mov_b32 m0, s66
	s_nop 0
	global_load_lds_dwordx4 v156, s[12:13]
	s_add_i32 m0, s66, 0x2000
	s_nop 0
	global_load_lds_dwordx4 v158, s[12:13]
	s_mov_b32 m0, s0
	s_nop 0
	global_load_lds_dwordx4 v251, s[100:101]
	s_mov_b32 m0, s1
	s_nop 0
	global_load_lds_dwordx4 v252, s[100:101]
	s_waitcnt vmcnt(8)
	s_waitcnt lgkmcnt(0)
	s_barrier
	s_setprio 1
	v_mfma_f32_16x16x32_bf16 v[62:65], v[132:135], v[216:219], v[62:65]
	v_mfma_f32_16x16x32_bf16 v[58:61], v[140:143], v[216:219], v[58:61]
	v_mfma_f32_16x16x32_bf16 v[54:57], v[132:135], v[224:227], v[54:57]
	v_mfma_f32_16x16x32_bf16 v[50:53], v[140:143], v[224:227], v[50:53]
	v_mfma_f32_16x16x32_bf16 v[46:49], v[132:135], v[232:235], v[46:49]
	v_mfma_f32_16x16x32_bf16 v[42:45], v[140:143], v[232:235], v[42:45]
	v_mfma_f32_16x16x32_bf16 v[38:41], v[132:135], v[240:243], v[38:41]
	v_mfma_f32_16x16x32_bf16 v[34:37], v[140:143], v[240:243], v[34:37]
	v_mfma_f32_16x16x32_bf16 v[62:65], v[136:139], v[220:223], v[62:65]
	v_mfma_f32_16x16x32_bf16 v[58:61], v[144:147], v[220:223], v[58:61]
	v_mfma_f32_16x16x32_bf16 v[54:57], v[136:139], v[228:231], v[54:57]
	v_mfma_f32_16x16x32_bf16 v[50:53], v[144:147], v[228:231], v[50:53]
	v_mfma_f32_16x16x32_bf16 v[46:49], v[136:139], v[236:239], v[46:49]
	v_mfma_f32_16x16x32_bf16 v[42:45], v[144:147], v[236:239], v[42:45]
	v_mfma_f32_16x16x32_bf16 v[38:41], v[136:139], v[244:247], v[38:41]
	v_mfma_f32_16x16x32_bf16 v[34:37], v[144:147], v[244:247], v[34:37]
	s_setprio 0
	s_setprio 1
	v_mfma_f32_16x16x32_bf16 v[30:33], v[148:151], v[216:219], v[30:33]
	s_add_i32 s65, s65, 2
	v_mfma_f32_16x16x32_bf16 v[26:29], v[182:185], v[216:219], v[26:29]
	s_add_u32 s63, s63, 0x100
	v_mfma_f32_16x16x32_bf16 v[22:25], v[148:151], v[224:227], v[22:25]
	s_addc_u32 s64, s64, 0
	v_mfma_f32_16x16x32_bf16 v[18:21], v[182:185], v[224:227], v[18:21]
	s_add_u32 s10, s10, 0x10000
	v_mfma_f32_16x16x32_bf16 v[14:17], v[148:151], v[232:235], v[14:17]
	s_addc_u32 s11, s11, 0
	v_mfma_f32_16x16x32_bf16 v[10:13], v[182:185], v[232:235], v[10:13]
	s_mov_b64 s[12:13], 0x10000
	v_mfma_f32_16x16x32_bf16 v[6:9], v[148:151], v[240:243], v[6:9]
	s_cmp_gt_u32 s65, 13
	v_mfma_f32_16x16x32_bf16 v[2:5], v[182:185], v[240:243], v[2:5]
	v_mfma_f32_16x16x32_bf16 v[30:33], v[178:181], v[220:223], v[30:33]
	v_mfma_f32_16x16x32_bf16 v[26:29], v[212:215], v[220:223], v[26:29]
	v_mfma_f32_16x16x32_bf16 v[22:25], v[178:181], v[228:231], v[22:25]
	v_mfma_f32_16x16x32_bf16 v[18:21], v[212:215], v[228:231], v[18:21]
	v_mfma_f32_16x16x32_bf16 v[14:17], v[178:181], v[236:239], v[14:17]
	v_mfma_f32_16x16x32_bf16 v[10:13], v[212:215], v[236:239], v[10:13]
	v_mfma_f32_16x16x32_bf16 v[6:9], v[178:181], v[244:247], v[6:9]
	v_mfma_f32_16x16x32_bf16 v[2:5], v[212:215], v[244:247], v[2:5]
	s_setprio 0
	s_barrier
	s_cbranch_scc0 .LBB0_818
	s_and_b64 vcc, exec, s[52:53]
	s_cbranch_vccz .LBB0_821
	s_barrier

; #define PG8_STAGE(bufoff, gbase, voff) do { _Pragma("unroll") for (int _i = 0; _i < 2; ++_i) \
;         __builtin_amdgcn_global_load_lds((const unsigned*)((const char*)(gbase) + (voff)[_i]), (PG8_LAS unsigned*)(lds + (bufoff) + ldsw + _i * 8192), 16, 0, 0); } while (0)
; #define PG8_LDA(dst, b, h) do { _Pragma("unroll") for (int m = 0; m < 4; ++m) _Pragma("unroll") for (int k = 0; k < 2; ++k) dst[m][k] = *(const PG8_LAS bf16x8*)(lds + PG8_SA(b, h) + aoff + m * 2048 + k * 1024); } while (0)
; #define PG8_LDB(dst, b, h) do { _Pragma("unroll") for (int n = 0; n < 2; ++n) _Pragma("unroll") for (int k = 0; k < 2; ++k) dst[n][k] = *(const PG8_LAS bf16x8*)(lds + PG8_SB(b, h) + boff + n * 2048 + k * 1024); } while (0)
; #define PG8_WAIT_V(n) asm volatile("s_waitcnt vmcnt(" #n ")" ::: "memory")
; template <class Epi, bool ALIGN_EPI, bool ABLK = false>
; __device__ __forceinline__ void gemm_phase(PG8_LAS unsigned char* lds, const Gemm g, const StaticOrder& S, const Epi& E) {
;     ...
;         for (int t = 0; t < nt; t += 2) {
;             const bool last = (t == nt - 2);
;             const char* a1 = cA + (size_t)(t + 1) * kstepA;
;             const char* a2 = last ? nA : cA + (size_t)(t + 2) * kstepA; const char* b2 = last ? nB : cB + (size_t)(t + 2) * kstepB;
;             const char* a3 = a2 + kstepA; const char* b3 = b2 + kstepB;
;             PG8_LDB(B0, 0, 0); PG8_LDB(B1, 0, 1); PG8_SCHED; PG8_LDA(At, 0, 0); PG8_STAGE(PG8_SA(1, 1), a1 + hstepA, voffA);
;             PG8_WAIT_V(8); PG8_WAIT_L(0); PG8_BAR; PG8_MMA(0, 0, At, B0); PG8_MMA(0, 1, At, B1); PG8_BAR; PG8_SCHED;
;             PG8_LDA(At, 0, 1); PG8_STAGE(PG8_SB(0, 0), b2, voffB); PG8_STAGE(PG8_SB(0, 1), b2 + hstepB, voffB); PG8_STAGE(PG8_SA(0, 0), a2, voffA);
;             PG8_WAIT_V(8); PG8_WAIT_L(0); PG8_BAR; PG8_MMA(1, 0, At, B0); PG8_MMA(1, 1, At, B1); PG8_BAR; PG8_SCHED;
;             PG8_LDB(B0, 1, 0); PG8_LDB(B1, 1, 1); PG8_SCHED; PG8_LDA(At, 1, 0); PG8_STAGE(PG8_SA(0, 1), a2 + hstepA, voffA);
;             PG8_WAIT_V(8); PG8_WAIT_L(0); PG8_BAR; PG8_MMA(0, 0, At, B0); PG8_MMA(0, 1, At, B1); PG8_BAR; PG8_SCHED;
;             PG8_LDA(At, 1, 1); PG8_STAGE(PG8_SB(1, 0), b3, voffB); PG8_STAGE(PG8_SB(1, 1), b3 + hstepB, voffB); PG8_STAGE(PG8_SA(1, 0), a3, voffA);
;             PG8_WAIT_V(8); PG8_WAIT_L(0); PG8_BAR; PG8_MMA(1, 0, At, B0); PG8_MMA(1, 1, At, B1); PG8_BAR; PG8_SCHED;
.LBB0_1983:
	v_add_u32_e32 v136, s71, v179
	ds_read_b128 v[132:135], v136
	ds_read_b128 v[184:187], v136 offset:1024
	ds_read_b128 v[188:191], v136 offset:2048
	ds_read_b128 v[192:195], v136 offset:3072
	v_add_u32_e32 v136, s72, v179
	ds_read_b128 v[196:199], v136
	ds_read_b128 v[200:203], v136 offset:1024
	ds_read_b128 v[204:207], v136 offset:2048
	ds_read_b128 v[208:211], v136 offset:3072
	s_add_u32 s62, s26, s60
	s_addc_u32 s63, s27, s61
	s_cmp_eq_u32 s79, 12
	s_cselect_b32 s81, s55, s63
	s_cselect_b32 s80, s75, s62
	s_cselect_b32 s63, s53, s78
	s_cselect_b32 s62, s76, s77
	v_lshl_add_u64 v[136:137], s[26:27], 0, v[130:131]
	v_lshl_add_u64 v[244:245], v[136:137], 0, s[40:41]
	s_add_i32 m0, s23, 0xc000
	ds_read_b128 v[212:215], v182
	ds_read_b128 v[216:219], v182 offset:1024
	ds_read_b128 v[220:223], v182 offset:2048
	ds_read_b128 v[224:227], v182 offset:3072
	ds_read_b128 v[228:231], v182 offset:4096
	ds_read_b128 v[232:235], v182 offset:5120
	ds_read_b128 v[236:239], v182 offset:6144
	ds_read_b128 v[240:243], v182 offset:7168
	global_load_lds_dwordx4 v[244:245], off
	v_lshl_add_u64 v[136:137], v[136:137], 0, s[42:43]
	s_add_i32 m0, s23, 0xe000
	s_nop 0
	global_load_lds_dwordx4 v[136:137], off
	s_waitcnt vmcnt(8)
	s_waitcnt lgkmcnt(0)
	s_barrier
	s_setprio 1
	v_mfma_f32_16x16x32_bf16 v[126:129], v[132:135], v[212:215], v[126:129]
	v_mfma_f32_16x16x32_bf16 v[122:125], v[188:191], v[212:215], v[122:125]
	v_mfma_f32_16x16x32_bf16 v[118:121], v[132:135], v[220:223], v[118:121]
	v_mfma_f32_16x16x32_bf16 v[114:117], v[188:191], v[220:223], v[114:117]
	v_mfma_f32_16x16x32_bf16 v[110:113], v[132:135], v[228:231], v[110:113]
	v_mfma_f32_16x16x32_bf16 v[106:109], v[188:191], v[228:231], v[106:109]
	v_mfma_f32_16x16x32_bf16 v[102:105], v[132:135], v[236:239], v[102:105]
	v_mfma_f32_16x16x32_bf16 v[98:101], v[188:191], v[236:239], v[98:101]
	v_mfma_f32_16x16x32_bf16 v[126:129], v[184:187], v[216:219], v[126:129]
	v_mfma_f32_16x16x32_bf16 v[122:125], v[192:195], v[216:219], v[122:125]
	v_mfma_f32_16x16x32_bf16 v[118:121], v[184:187], v[224:227], v[118:121]
	v_mfma_f32_16x16x32_bf16 v[114:117], v[192:195], v[224:227], v[114:117]
	v_mfma_f32_16x16x32_bf16 v[110:113], v[184:187], v[232:235], v[110:113]
	v_mfma_f32_16x16x32_bf16 v[106:109], v[192:195], v[232:235], v[106:109]
	v_mfma_f32_16x16x32_bf16 v[102:105], v[184:187], v[240:243], v[102:105]
	v_mfma_f32_16x16x32_bf16 v[98:101], v[192:195], v[240:243], v[98:101]
	s_setprio 0
	s_setprio 1
	v_mfma_f32_16x16x32_bf16 v[94:97], v[196:199], v[212:215], v[94:97]
	s_add_i32 s82, s71, s21
	v_mfma_f32_16x16x32_bf16 v[90:93], v[204:207], v[212:215], v[90:93]
	s_mov_b32 m0, s82
	v_mfma_f32_16x16x32_bf16 v[86:89], v[196:199], v[220:223], v[86:89]
	v_mfma_f32_16x16x32_bf16 v[82:85], v[204:207], v[220:223], v[82:85]
	v_mfma_f32_16x16x32_bf16 v[78:81], v[196:199], v[228:231], v[78:81]
	v_mfma_f32_16x16x32_bf16 v[74:77], v[204:207], v[228:231], v[74:77]
	v_mfma_f32_16x16x32_bf16 v[70:73], v[196:199], v[236:239], v[70:73]
	v_mfma_f32_16x16x32_bf16 v[66:69], v[204:207], v[236:239], v[66:69]
	v_mfma_f32_16x16x32_bf16 v[94:97], v[200:203], v[216:219], v[94:97]
	v_mfma_f32_16x16x32_bf16 v[90:93], v[208:211], v[216:219], v[90:93]
	v_mfma_f32_16x16x32_bf16 v[86:89], v[200:203], v[224:227], v[86:89]
	v_mfma_f32_16x16x32_bf16 v[82:85], v[208:211], v[224:227], v[82:85]
	v_mfma_f32_16x16x32_bf16 v[78:81], v[200:203], v[232:235], v[78:81]
	v_mfma_f32_16x16x32_bf16 v[74:77], v[208:211], v[232:235], v[74:77]
	v_mfma_f32_16x16x32_bf16 v[70:73], v[200:203], v[240:243], v[70:73]
	v_mfma_f32_16x16x32_bf16 v[66:69], v[208:211], v[240:243], v[66:69]
	s_setprio 0
	s_barrier
	v_lshl_add_u64 v[136:137], s[62:63], 0, v[140:141]
	ds_read_b128 v[212:215], v182 offset:16384
	ds_read_b128 v[216:219], v182 offset:17408
	ds_read_b128 v[220:223], v182 offset:18432
	ds_read_b128 v[224:227], v182 offset:19456
	ds_read_b128 v[228:231], v182 offset:20480
	ds_read_b128 v[232:235], v182 offset:21504
	ds_read_b128 v[236:239], v182 offset:22528
	ds_read_b128 v[240:243], v182 offset:23552
	global_load_lds_dwordx4 v[136:137], off
	s_add_i32 m0, s82, 0x2000
	s_add_u32 s82, s62, 0x40000
	v_lshl_add_u64 v[244:245], s[62:63], 0, v[142:143]
	s_addc_u32 s83, s63, 0
	s_add_i32 s84, s72, s21
	global_load_lds_dwordx4 v[244:245], off
	v_lshl_add_u64 v[246:247], s[82:83], 0, v[140:141]
	s_mov_b32 m0, s84
	s_nop 0
	global_load_lds_dwordx4 v[246:247], off
	v_lshl_add_u64 v[246:247], s[82:83], 0, v[142:143]
	s_add_i32 m0, s84, 0x2000
	s_nop 0
	global_load_lds_dwordx4 v[246:247], off
	v_lshl_add_u64 v[246:247], s[80:81], 0, v[138:139]
	s_mov_b32 m0, s23
	v_lshl_add_u64 v[248:249], v[246:247], 0, s[44:45]
	global_load_lds_dwordx4 v[246:247], off
	s_mov_b32 m0, s33
	s_nop 0
	global_load_lds_dwordx4 v[248:249], off
	s_waitcnt vmcnt(8)
	s_waitcnt lgkmcnt(0)
	s_barrier
; #define PG8_STAGE(bufoff, gbase, voff) do { _Pragma("unroll") for (int _i = 0; _i < 2; ++_i) \
;         __builtin_amdgcn_global_load_lds((const unsigned*)((const char*)(gbase) + (voff)[_i]), (PG8_LAS unsigned*)(lds + (bufoff) + ldsw + _i * 8192), 16, 0, 0); } while (0)
; #define PG8_LDA(dst, b, h) do { _Pragma("unroll") for (int m = 0; m < 4; ++m) _Pragma("unroll") for (int k = 0; k < 2; ++k) dst[m][k] = *(const PG8_LAS bf16x8*)(lds + PG8_SA(b, h) + aoff + m * 2048 + k * 1024); } while (0)
; #define PG8_LDB(dst, b, h) do { _Pragma("unroll") for (int n = 0; n < 2; ++n) _Pragma("unroll") for (int k = 0; k < 2; ++k) dst[n][k] = *(const PG8_LAS bf16x8*)(lds + PG8_SB(b, h) + boff + n * 2048 + k * 1024); } while (0)
; #define PG8_WAIT_V(n) asm volatile("s_waitcnt vmcnt(" #n ")" ::: "memory")
; template <class Epi, bool ALIGN_EPI, bool ABLK = false>
; __device__ __forceinline__ void gemm_phase(PG8_LAS unsigned char* lds, const Gemm g, const StaticOrder& S, const Epi& E) {
;     ...
;         for (int t = 0; t < nt; t += 2) {
;             const bool last = (t == nt - 2);
;             const char* a1 = cA + (size_t)(t + 1) * kstepA;
;             const char* a2 = last ? nA : cA + (size_t)(t + 2) * kstepA; const char* b2 = last ? nB : cB + (size_t)(t + 2) * kstepB;
;             const char* a3 = a2 + kstepA; const char* b3 = b2 + kstepB;
;             PG8_LDB(B0, 0, 0); PG8_LDB(B1, 0, 1); PG8_SCHED; PG8_LDA(At, 0, 0); PG8_STAGE(PG8_SA(1, 1), a1 + hstepA, voffA);
;             PG8_WAIT_V(8); PG8_WAIT_L(0); PG8_BAR; PG8_MMA(0, 0, At, B0); PG8_MMA(0, 1, At, B1); PG8_BAR; PG8_SCHED;
;             PG8_LDA(At, 0, 1); PG8_STAGE(PG8_SB(0, 0), b2, voffB); PG8_STAGE(PG8_SB(0, 1), b2 + hstepB, voffB); PG8_STAGE(PG8_SA(0, 0), a2, voffA);
;             PG8_WAIT_V(8); PG8_WAIT_L(0); PG8_BAR; PG8_MMA(1, 0, At, B0); PG8_MMA(1, 1, At, B1); PG8_BAR; PG8_SCHED;
;             PG8_LDB(B0, 1, 0); PG8_LDB(B1, 1, 1); PG8_SCHED; PG8_LDA(At, 1, 0); PG8_STAGE(PG8_SA(0, 1), a2 + hstepA, voffA);
;             PG8_WAIT_V(8); PG8_WAIT_L(0); PG8_BAR; PG8_MMA(0, 0, At, B0); PG8_MMA(0, 1, At, B1); PG8_BAR; PG8_SCHED;
;             PG8_LDA(At, 1, 1); PG8_STAGE(PG8_SB(1, 0), b3, voffB); PG8_STAGE(PG8_SB(1, 1), b3 + hstepB, voffB); PG8_STAGE(PG8_SA(1, 0), a3, voffA);
;             PG8_WAIT_V(8); PG8_WAIT_L(0); PG8_BAR; PG8_MMA(1, 0, At, B0); PG8_MMA(1, 1, At, B1); PG8_BAR; PG8_SCHED;
	s_setprio 1
	v_mfma_f32_16x16x32_bf16 v[62:65], v[132:135], v[212:215], v[62:65]
	v_mfma_f32_16x16x32_bf16 v[58:61], v[188:191], v[212:215], v[58:61]
	v_mfma_f32_16x16x32_bf16 v[54:57], v[132:135], v[220:223], v[54:57]
	v_mfma_f32_16x16x32_bf16 v[50:53], v[188:191], v[220:223], v[50:53]
	v_mfma_f32_16x16x32_bf16 v[46:49], v[132:135], v[228:231], v[46:49]
	v_mfma_f32_16x16x32_bf16 v[42:45], v[188:191], v[228:231], v[42:45]
	v_mfma_f32_16x16x32_bf16 v[38:41], v[132:135], v[236:239], v[38:41]
	v_mfma_f32_16x16x32_bf16 v[34:37], v[188:191], v[236:239], v[34:37]
	v_mfma_f32_16x16x32_bf16 v[62:65], v[184:187], v[216:219], v[62:65]
	v_mfma_f32_16x16x32_bf16 v[58:61], v[192:195], v[216:219], v[58:61]
	v_mfma_f32_16x16x32_bf16 v[54:57], v[184:187], v[224:227], v[54:57]
	v_mfma_f32_16x16x32_bf16 v[50:53], v[192:195], v[224:227], v[50:53]
	v_mfma_f32_16x16x32_bf16 v[46:49], v[184:187], v[232:235], v[46:49]
	v_mfma_f32_16x16x32_bf16 v[42:45], v[192:195], v[232:235], v[42:45]
	v_mfma_f32_16x16x32_bf16 v[38:41], v[184:187], v[240:243], v[38:41]
	v_mfma_f32_16x16x32_bf16 v[34:37], v[192:195], v[240:243], v[34:37]
	s_setprio 0
	s_setprio 1
	v_mfma_f32_16x16x32_bf16 v[30:33], v[196:199], v[212:215], v[30:33]
	s_add_i32 s80, 0, 0x18000
	v_mfma_f32_16x16x32_bf16 v[26:29], v[204:207], v[212:215], v[26:29]
	s_add_i32 s81, 0, 0x1c000
	v_mfma_f32_16x16x32_bf16 v[22:25], v[196:199], v[220:223], v[22:25]
	v_mfma_f32_16x16x32_bf16 v[18:21], v[204:207], v[220:223], v[18:21]
	v_mfma_f32_16x16x32_bf16 v[14:17], v[196:199], v[228:231], v[14:17]
	v_mfma_f32_16x16x32_bf16 v[10:13], v[204:207], v[228:231], v[10:13]
	v_mfma_f32_16x16x32_bf16 v[6:9], v[196:199], v[236:239], v[6:9]
	v_mfma_f32_16x16x32_bf16 v[2:5], v[204:207], v[236:239], v[2:5]
	v_mfma_f32_16x16x32_bf16 v[30:33], v[200:203], v[216:219], v[30:33]
	v_mfma_f32_16x16x32_bf16 v[26:29], v[208:211], v[216:219], v[26:29]
	v_mfma_f32_16x16x32_bf16 v[22:25], v[200:203], v[224:227], v[22:25]
	v_mfma_f32_16x16x32_bf16 v[18:21], v[208:211], v[224:227], v[18:21]
	v_mfma_f32_16x16x32_bf16 v[14:17], v[200:203], v[232:235], v[14:17]
	v_mfma_f32_16x16x32_bf16 v[10:13], v[208:211], v[232:235], v[10:13]
	v_mfma_f32_16x16x32_bf16 v[6:9], v[200:203], v[240:243], v[6:9]
	v_mfma_f32_16x16x32_bf16 v[2:5], v[208:211], v[240:243], v[2:5]
	s_setprio 0
	s_barrier
	v_add_u32_e32 v192, s80, v179
	v_add_u32_e32 v208, s81, v179
	ds_read_b128 v[132:135], v192
	ds_read_b128 v[184:187], v192 offset:1024
	ds_read_b128 v[188:191], v192 offset:2048
	ds_read_b128 v[192:195], v192 offset:3072
	ds_read_b128 v[196:199], v208
	ds_read_b128 v[200:203], v208 offset:1024
	ds_read_b128 v[204:207], v208 offset:2048
	ds_read_b128 v[208:211], v208 offset:3072
	s_mov_b32 m0, s67
	v_lshl_add_u64 v[248:249], v[246:247], 0, s[46:47]
	ds_read_b128 v[212:215], v182 offset:32768
	ds_read_b128 v[216:219], v182 offset:33792
	ds_read_b128 v[220:223], v182 offset:34816
	ds_read_b128 v[224:227], v182 offset:35840
	ds_read_b128 v[228:231], v182 offset:36864
	ds_read_b128 v[232:235], v182 offset:37888
	ds_read_b128 v[236:239], v182 offset:38912
	ds_read_b128 v[240:243], v182 offset:39936
	global_load_lds_dwordx4 v[248:249], off
	v_lshl_add_u64 v[248:249], v[246:247], 0, s[48:49]
	s_mov_b32 m0, s68
	s_nop 0
	global_load_lds_dwordx4 v[248:249], off
	s_waitcnt vmcnt(8)
	s_waitcnt lgkmcnt(0)
	s_barrier
	s_setprio 1
	v_mfma_f32_16x16x32_bf16 v[126:129], v[132:135], v[212:215], v[126:129]
	v_mfma_f32_16x16x32_bf16 v[122:125], v[188:191], v[212:215], v[122:125]
	v_mfma_f32_16x16x32_bf16 v[118:121], v[132:135], v[220:223], v[118:121]
	v_mfma_f32_16x16x32_bf16 v[114:117], v[188:191], v[220:223], v[114:117]
	v_mfma_f32_16x16x32_bf16 v[110:113], v[132:135], v[228:231], v[110:113]
	v_mfma_f32_16x16x32_bf16 v[106:109], v[188:191], v[228:231], v[106:109]
	v_mfma_f32_16x16x32_bf16 v[102:105], v[132:135], v[236:239], v[102:105]
	v_mfma_f32_16x16x32_bf16 v[98:101], v[188:191], v[236:239], v[98:101]
	v_mfma_f32_16x16x32_bf16 v[126:129], v[184:187], v[216:219], v[126:129]
	v_mfma_f32_16x16x32_bf16 v[122:125], v[192:195], v[216:219], v[122:125]
	v_mfma_f32_16x16x32_bf16 v[118:121], v[184:187], v[224:227], v[118:121]
	v_mfma_f32_16x16x32_bf16 v[114:117], v[192:195], v[224:227], v[114:117]
	v_mfma_f32_16x16x32_bf16 v[110:113], v[184:187], v[232:235], v[110:113]
	v_mfma_f32_16x16x32_bf16 v[106:109], v[192:195], v[232:235], v[106:109]
	v_mfma_f32_16x16x32_bf16 v[102:105], v[184:187], v[240:243], v[102:105]
	v_mfma_f32_16x16x32_bf16 v[98:101], v[192:195], v[240:243], v[98:101]
	s_setprio 0
	s_setprio 1
	v_mfma_f32_16x16x32_bf16 v[94:97], v[196:199], v[212:215], v[94:97]
	s_add_i32 s80, s80, s21
	v_mfma_f32_16x16x32_bf16 v[90:93], v[204:207], v[212:215], v[90:93]
	s_mov_b32 m0, s80
	v_mfma_f32_16x16x32_bf16 v[86:89], v[196:199], v[220:223], v[86:89]
	v_mfma_f32_16x16x32_bf16 v[82:85], v[204:207], v[220:223], v[82:85]
	v_mfma_f32_16x16x32_bf16 v[78:81], v[196:199], v[228:231], v[78:81]
	v_mfma_f32_16x16x32_bf16 v[74:77], v[204:207], v[228:231], v[74:77]
	v_mfma_f32_16x16x32_bf16 v[70:73], v[196:199], v[236:239], v[70:73]
	v_mfma_f32_16x16x32_bf16 v[66:69], v[204:207], v[236:239], v[66:69]
	v_mfma_f32_16x16x32_bf16 v[94:97], v[200:203], v[216:219], v[94:97]
	v_mfma_f32_16x16x32_bf16 v[90:93], v[208:211], v[216:219], v[90:93]
	v_mfma_f32_16x16x32_bf16 v[86:89], v[200:203], v[224:227], v[86:89]
	v_mfma_f32_16x16x32_bf16 v[82:85], v[208:211], v[224:227], v[82:85]
	v_mfma_f32_16x16x32_bf16 v[78:81], v[200:203], v[232:235], v[78:81]
	v_mfma_f32_16x16x32_bf16 v[74:77], v[208:211], v[232:235], v[74:77]
	v_mfma_f32_16x16x32_bf16 v[70:73], v[200:203], v[240:243], v[70:73]
	v_mfma_f32_16x16x32_bf16 v[66:69], v[208:211], v[240:243], v[66:69]
	s_setprio 0
	s_barrier
; #define PG8_STAGE(bufoff, gbase, voff) do { _Pragma("unroll") for (int _i = 0; _i < 2; ++_i) \
;         __builtin_amdgcn_global_load_lds((const unsigned*)((const char*)(gbase) + (voff)[_i]), (PG8_LAS unsigned*)(lds + (bufoff) + ldsw + _i * 8192), 16, 0, 0); } while (0)
; #define PG8_LDA(dst, b, h) do { _Pragma("unroll") for (int m = 0; m < 4; ++m) _Pragma("unroll") for (int k = 0; k < 2; ++k) dst[m][k] = *(const PG8_LAS bf16x8*)(lds + PG8_SA(b, h) + aoff + m * 2048 + k * 1024); } while (0)
; #define PG8_MMA(ai, bj, At, Bt) do { __builtin_amdgcn_s_setprio(1); _Pragma("unroll") for (int m = 0; m < 4; ++m) _Pragma("unroll") for (int n = 0; n < 2; ++n) _Pragma("unroll") for (int k = 0; k < 2; ++k) \
;         acc[ai][bj][m][n] = __builtin_amdgcn_mfma_f32_16x16x32_bf16(Bt[n][k], At[m][k], acc[ai][bj][m][n], 0, 0, 0); __builtin_amdgcn_s_setprio(0); } while (0)
; #define PG8_WAIT_V(n) asm volatile("s_waitcnt vmcnt(" #n ")" ::: "memory")
; #define PG8_WAIT_L(n) asm volatile("s_waitcnt lgkmcnt(" #n ")" ::: "memory")
; #define PG8_BAR __builtin_amdgcn_s_barrier()
; #define PG8_SCHED __builtin_amdgcn_sched_barrier(0)
; template <class Epi, bool ALIGN_EPI, bool ABLK = false>
; __device__ __forceinline__ void gemm_phase(PG8_LAS unsigned char* lds, const Gemm g, const StaticOrder& S, const Epi& E) {
;     ...
;             PG8_LDA(At, 1, 1); PG8_STAGE(PG8_SB(1, 0), b3, voffB); PG8_STAGE(PG8_SB(1, 1), b3 + hstepB, voffB); PG8_STAGE(PG8_SA(1, 0), a3, voffA);
;             PG8_WAIT_V(8); PG8_WAIT_L(0); PG8_BAR; PG8_MMA(1, 0, At, B0); PG8_MMA(1, 1, At, B1); PG8_BAR; PG8_SCHED;
;         }
;         if constexpr (ALIGN_EPI) { if (wr == 0) PG8_BAR; }
	v_lshl_add_u64 v[136:137], v[136:137], 0, s[30:31]
	ds_read_b128 v[212:215], v182 offset:49152
	ds_read_b128 v[216:219], v182 offset:50176
	ds_read_b128 v[220:223], v182 offset:51200
	ds_read_b128 v[224:227], v182 offset:52224
	ds_read_b128 v[228:231], v182 offset:53248
	ds_read_b128 v[232:235], v182 offset:54272
	ds_read_b128 v[236:239], v182 offset:55296
	ds_read_b128 v[240:243], v182 offset:56320
	global_load_lds_dwordx4 v[136:137], off
	s_add_i32 m0, s80, 0x2000
	s_add_u32 s62, s62, 0x40080
	v_lshl_add_u64 v[136:137], v[244:245], 0, s[30:31]
	s_addc_u32 s63, s63, 0
	s_add_i32 s80, s81, s21
	global_load_lds_dwordx4 v[136:137], off
	v_lshl_add_u64 v[136:137], s[62:63], 0, v[140:141]
	s_mov_b32 m0, s80
	s_nop 0
	global_load_lds_dwordx4 v[136:137], off
	v_lshl_add_u64 v[136:137], s[62:63], 0, v[142:143]
	s_add_i32 m0, s80, 0x2000
	s_nop 0
	global_load_lds_dwordx4 v[136:137], off
	v_lshl_add_u64 v[136:137], v[246:247], 0, s[34:35]
	s_mov_b32 m0, s9
	s_nop 0
	global_load_lds_dwordx4 v[136:137], off
	v_lshl_add_u64 v[136:137], v[246:247], 0, s[36:37]
	s_mov_b32 m0, s70
	s_nop 0
	global_load_lds_dwordx4 v[136:137], off
	s_waitcnt vmcnt(8)
	s_waitcnt lgkmcnt(0)
	s_barrier
	s_setprio 1
	v_mfma_f32_16x16x32_bf16 v[62:65], v[132:135], v[212:215], v[62:65]
	v_mfma_f32_16x16x32_bf16 v[58:61], v[188:191], v[212:215], v[58:61]
	v_mfma_f32_16x16x32_bf16 v[54:57], v[132:135], v[220:223], v[54:57]
	v_mfma_f32_16x16x32_bf16 v[50:53], v[188:191], v[220:223], v[50:53]
	v_mfma_f32_16x16x32_bf16 v[46:49], v[132:135], v[228:231], v[46:49]
	v_mfma_f32_16x16x32_bf16 v[42:45], v[188:191], v[228:231], v[42:45]
	v_mfma_f32_16x16x32_bf16 v[38:41], v[132:135], v[236:239], v[38:41]
	v_mfma_f32_16x16x32_bf16 v[34:37], v[188:191], v[236:239], v[34:37]
	v_mfma_f32_16x16x32_bf16 v[62:65], v[184:187], v[216:219], v[62:65]
	v_mfma_f32_16x16x32_bf16 v[58:61], v[192:195], v[216:219], v[58:61]
	v_mfma_f32_16x16x32_bf16 v[54:57], v[184:187], v[224:227], v[54:57]
	v_mfma_f32_16x16x32_bf16 v[50:53], v[192:195], v[224:227], v[50:53]
	v_mfma_f32_16x16x32_bf16 v[46:49], v[184:187], v[232:235], v[46:49]
	v_mfma_f32_16x16x32_bf16 v[42:45], v[192:195], v[232:235], v[42:45]
	v_mfma_f32_16x16x32_bf16 v[38:41], v[184:187], v[240:243], v[38:41]
	v_mfma_f32_16x16x32_bf16 v[34:37], v[192:195], v[240:243], v[34:37]
	s_setprio 0
	s_setprio 1
	v_mfma_f32_16x16x32_bf16 v[30:33], v[196:199], v[212:215], v[30:33]
	s_add_i32 s79, s79, 2
	v_mfma_f32_16x16x32_bf16 v[26:29], v[204:207], v[212:215], v[26:29]
	s_add_u32 s77, s77, 0x100
	v_mfma_f32_16x16x32_bf16 v[22:25], v[196:199], v[220:223], v[22:25]
	s_addc_u32 s78, s78, 0
	v_mfma_f32_16x16x32_bf16 v[18:21], v[204:207], v[220:223], v[18:21]
	s_add_u32 s60, s60, 0x10000
	v_mfma_f32_16x16x32_bf16 v[14:17], v[196:199], v[228:231], v[14:17]
	s_addc_u32 s61, s61, 0
	v_mfma_f32_16x16x32_bf16 v[10:13], v[204:207], v[228:231], v[10:13]
	s_cmp_gt_u32 s79, 13
	v_mfma_f32_16x16x32_bf16 v[6:9], v[196:199], v[236:239], v[6:9]
	v_mfma_f32_16x16x32_bf16 v[2:5], v[204:207], v[236:239], v[2:5]
	v_mfma_f32_16x16x32_bf16 v[30:33], v[200:203], v[216:219], v[30:33]
	v_mfma_f32_16x16x32_bf16 v[26:29], v[208:211], v[216:219], v[26:29]
	v_mfma_f32_16x16x32_bf16 v[22:25], v[200:203], v[224:227], v[22:25]
	v_mfma_f32_16x16x32_bf16 v[18:21], v[208:211], v[224:227], v[18:21]
	v_mfma_f32_16x16x32_bf16 v[14:17], v[200:203], v[232:235], v[14:17]
	v_mfma_f32_16x16x32_bf16 v[10:13], v[208:211], v[232:235], v[10:13]
	v_mfma_f32_16x16x32_bf16 v[6:9], v[200:203], v[240:243], v[6:9]
	v_mfma_f32_16x16x32_bf16 v[2:5], v[208:211], v[240:243], v[2:5]
	s_setprio 0
	s_barrier
	v_lshl_add_u64 v[130:131], v[130:131], 0, s[50:51]
	s_cbranch_scc0 .LBB0_1983
	s_and_b64 vcc, exec, s[38:39]
	s_cbranch_vccz .LBB0_1986
	s_barrier

; #define PG8_STAGE(bufoff, gbase, voff) do { _Pragma("unroll") for (int _i = 0; _i < 2; ++_i) \
;         __builtin_amdgcn_global_load_lds((const unsigned*)((const char*)(gbase) + (voff)[_i]), (PG8_LAS unsigned*)(lds + (bufoff) + ldsw + _i * 8192), 16, 0, 0); } while (0)
; #define PG8_LDA(dst, b, h) do { _Pragma("unroll") for (int m = 0; m < 4; ++m) _Pragma("unroll") for (int k = 0; k < 2; ++k) dst[m][k] = *(const PG8_LAS bf16x8*)(lds + PG8_SA(b, h) + aoff + m * 2048 + k * 1024); } while (0)
; #define PG8_LDB(dst, b, h) do { _Pragma("unroll") for (int n = 0; n < 2; ++n) _Pragma("unroll") for (int k = 0; k < 2; ++k) dst[n][k] = *(const PG8_LAS bf16x8*)(lds + PG8_SB(b, h) + boff + n * 2048 + k * 1024); } while (0)
; #define PG8_MMA(ai, bj, At, Bt) do { __builtin_amdgcn_s_setprio(1); _Pragma("unroll") for (int m = 0; m < 4; ++m) _Pragma("unroll") for (int n = 0; n < 2; ++n) _Pragma("unroll") for (int k = 0; k < 2; ++k) \
;         acc[ai][bj][m][n] = __builtin_amdgcn_mfma_f32_16x16x32_bf16(Bt[n][k], At[m][k], acc[ai][bj][m][n], 0, 0, 0); __builtin_amdgcn_s_setprio(0); } while (0)
; #define PG8_WAIT_V(n) asm volatile("s_waitcnt vmcnt(" #n ")" ::: "memory")
; #define PG8_WAIT_L(n) asm volatile("s_waitcnt lgkmcnt(" #n ")" ::: "memory")
; #define PG8_BAR __builtin_amdgcn_s_barrier()
; #define PG8_SCHED __builtin_amdgcn_sched_barrier(0)
; template <class Epi, bool ALIGN_EPI, bool ABLK = false>
; __device__ __forceinline__ void gemm_phase(PG8_LAS unsigned char* lds, const Gemm g, const StaticOrder& S, const Epi& E) {
;     ...
;             PG8_LDB(B0, 0, 0); PG8_LDB(B1, 0, 1); PG8_SCHED; PG8_LDA(At, 0, 0); PG8_STAGE(PG8_SA(1, 1), a1 + hstepA, voffA);
;             PG8_WAIT_V(8); PG8_WAIT_L(0); PG8_BAR; PG8_MMA(0, 0, At, B0); PG8_MMA(0, 1, At, B1); PG8_BAR; PG8_SCHED;
;             PG8_LDA(At, 0, 1); PG8_STAGE(PG8_SB(0, 0), b2, voffB); PG8_STAGE(PG8_SB(0, 1), b2 + hstepB, voffB); PG8_STAGE(PG8_SA(0, 0), a2, voffA);
;             PG8_WAIT_V(8); PG8_WAIT_L(0); PG8_BAR; PG8_MMA(1, 0, At, B0); PG8_MMA(1, 1, At, B1); PG8_BAR; PG8_SCHED;
.LBB0_2105:
	v_add_u32_e32 v3, s64, v239
	ds_read_b128 v[134:137], v3
	ds_read_b128 v[138:141], v3 offset:1024
	ds_read_b128 v[142:145], v3 offset:2048
	ds_read_b128 v[146:149], v3 offset:3072
	v_add_u32_e32 v3, s65, v239
	ds_read_b128 v[150:153], v3
	ds_read_b128 v[154:157], v3 offset:1024
	ds_read_b128 v[158:161], v3 offset:2048
	ds_read_b128 v[162:165], v3 offset:3072
	s_add_u32 s48, s6, 0xfffc0080
	s_addc_u32 s49, s7, -1
	s_cmp_eq_u32 s73, 12
	s_cselect_b32 s51, s43, s49
	s_cselect_b32 s50, s69, s48
	s_cselect_b32 s49, s41, s72
	s_cselect_b32 s48, s70, s71
	v_lshl_add_u64 v[4:5], s[6:7], 0, v[218:219]
	s_add_i32 m0, s37, 0xc000
	ds_read_b128 v[166:169], v240
	ds_read_b128 v[170:173], v240 offset:1024
	ds_read_b128 v[174:177], v240 offset:2048
	ds_read_b128 v[178:181], v240 offset:3072
	ds_read_b128 v[182:185], v240 offset:4096
	ds_read_b128 v[186:189], v240 offset:5120
	ds_read_b128 v[190:193], v240 offset:6144
	ds_read_b128 v[226:229], v240 offset:7168
	global_load_lds_dwordx4 v[4:5], off
	v_lshl_add_u64 v[4:5], s[6:7], 0, v[220:221]
	s_add_i32 m0, s37, 0xe000
	s_nop 0
	global_load_lds_dwordx4 v[4:5], off
	s_waitcnt vmcnt(8)
	s_waitcnt lgkmcnt(0)
	s_barrier
	s_setprio 1
	v_mfma_f32_16x16x32_bf16 v[130:133], v[134:137], v[166:169], v[130:133]
	v_mfma_f32_16x16x32_bf16 v[126:129], v[142:145], v[166:169], v[126:129]
	v_mfma_f32_16x16x32_bf16 v[122:125], v[134:137], v[174:177], v[122:125]
	v_mfma_f32_16x16x32_bf16 v[118:121], v[142:145], v[174:177], v[118:121]
	v_mfma_f32_16x16x32_bf16 v[114:117], v[134:137], v[182:185], v[114:117]
	v_mfma_f32_16x16x32_bf16 v[110:113], v[142:145], v[182:185], v[110:113]
	v_mfma_f32_16x16x32_bf16 v[106:109], v[134:137], v[190:193], v[106:109]
	v_mfma_f32_16x16x32_bf16 v[102:105], v[142:145], v[190:193], v[102:105]
	v_mfma_f32_16x16x32_bf16 v[130:133], v[138:141], v[170:173], v[130:133]
	v_mfma_f32_16x16x32_bf16 v[126:129], v[146:149], v[170:173], v[126:129]
	v_mfma_f32_16x16x32_bf16 v[122:125], v[138:141], v[178:181], v[122:125]
	v_mfma_f32_16x16x32_bf16 v[118:121], v[146:149], v[178:181], v[118:121]
	v_mfma_f32_16x16x32_bf16 v[114:117], v[138:141], v[186:189], v[114:117]
	v_mfma_f32_16x16x32_bf16 v[110:113], v[146:149], v[186:189], v[110:113]
	v_mfma_f32_16x16x32_bf16 v[106:109], v[138:141], v[226:229], v[106:109]
	v_mfma_f32_16x16x32_bf16 v[102:105], v[146:149], v[226:229], v[102:105]
	s_setprio 0
	s_setprio 1
	v_mfma_f32_16x16x32_bf16 v[98:101], v[150:153], v[166:169], v[98:101]
	s_add_i32 s74, s64, s54
	v_mfma_f32_16x16x32_bf16 v[94:97], v[158:161], v[166:169], v[94:97]
	s_mov_b32 m0, s74
	v_mfma_f32_16x16x32_bf16 v[90:93], v[150:153], v[174:177], v[90:93]
	v_mfma_f32_16x16x32_bf16 v[86:89], v[158:161], v[174:177], v[86:89]
	v_mfma_f32_16x16x32_bf16 v[82:85], v[150:153], v[182:185], v[82:85]
	v_mfma_f32_16x16x32_bf16 v[78:81], v[158:161], v[182:185], v[78:81]
	v_mfma_f32_16x16x32_bf16 v[74:77], v[150:153], v[190:193], v[74:77]
	v_mfma_f32_16x16x32_bf16 v[70:73], v[158:161], v[190:193], v[70:73]
	v_mfma_f32_16x16x32_bf16 v[98:101], v[154:157], v[170:173], v[98:101]
	v_mfma_f32_16x16x32_bf16 v[94:97], v[162:165], v[170:173], v[94:97]
	v_mfma_f32_16x16x32_bf16 v[90:93], v[154:157], v[178:181], v[90:93]
	v_mfma_f32_16x16x32_bf16 v[86:89], v[162:165], v[178:181], v[86:89]
	v_mfma_f32_16x16x32_bf16 v[82:85], v[154:157], v[186:189], v[82:85]
	v_mfma_f32_16x16x32_bf16 v[78:81], v[162:165], v[186:189], v[78:81]
	v_mfma_f32_16x16x32_bf16 v[74:77], v[154:157], v[226:229], v[74:77]
	v_mfma_f32_16x16x32_bf16 v[70:73], v[162:165], v[226:229], v[70:73]
	s_setprio 0
	s_barrier
	v_lshl_add_u64 v[230:231], s[48:49], 0, v[196:197]
	ds_read_b128 v[166:169], v240 offset:16384
	ds_read_b128 v[170:173], v240 offset:17408
	ds_read_b128 v[174:177], v240 offset:18432
	ds_read_b128 v[178:181], v240 offset:19456
	ds_read_b128 v[182:185], v240 offset:20480
	ds_read_b128 v[186:189], v240 offset:21504
	ds_read_b128 v[190:193], v240 offset:22528
	ds_read_b128 v[226:229], v240 offset:23552
	global_load_lds_dwordx4 v[230:231], off
	s_add_i32 m0, s74, 0x2000
	s_add_u32 s74, s48, 0x80000
	v_lshl_add_u64 v[242:243], s[48:49], 0, v[200:201]
	s_addc_u32 s75, s49, 0
	s_add_i32 s76, s65, s54
	global_load_lds_dwordx4 v[242:243], off
	v_lshl_add_u64 v[4:5], s[74:75], 0, v[196:197]
	s_mov_b32 m0, s76
	v_lshl_add_u64 v[244:245], s[50:51], 0, v[194:195]
	global_load_lds_dwordx4 v[4:5], off
	v_lshl_add_u64 v[4:5], s[74:75], 0, v[200:201]
	s_add_i32 m0, s76, 0x2000
	v_lshl_add_u64 v[246:247], s[50:51], 0, v[198:199]
	global_load_lds_dwordx4 v[4:5], off
	s_mov_b32 m0, s37
	s_nop 0
	global_load_lds_dwordx4 v[244:245], off
	s_mov_b32 m0, s39
	s_nop 0
	global_load_lds_dwordx4 v[246:247], off
	s_waitcnt vmcnt(8)
	s_waitcnt lgkmcnt(0)
	s_barrier
; #define PG8_STAGE(bufoff, gbase, voff) do { _Pragma("unroll") for (int _i = 0; _i < 2; ++_i) \
;         __builtin_amdgcn_global_load_lds((const unsigned*)((const char*)(gbase) + (voff)[_i]), (PG8_LAS unsigned*)(lds + (bufoff) + ldsw + _i * 8192), 16, 0, 0); } while (0)
; #define PG8_LDA(dst, b, h) do { _Pragma("unroll") for (int m = 0; m < 4; ++m) _Pragma("unroll") for (int k = 0; k < 2; ++k) dst[m][k] = *(const PG8_LAS bf16x8*)(lds + PG8_SA(b, h) + aoff + m * 2048 + k * 1024); } while (0)
; #define PG8_LDB(dst, b, h) do { _Pragma("unroll") for (int n = 0; n < 2; ++n) _Pragma("unroll") for (int k = 0; k < 2; ++k) dst[n][k] = *(const PG8_LAS bf16x8*)(lds + PG8_SB(b, h) + boff + n * 2048 + k * 1024); } while (0)
; #define PG8_MMA(ai, bj, At, Bt) do { __builtin_amdgcn_s_setprio(1); _Pragma("unroll") for (int m = 0; m < 4; ++m) _Pragma("unroll") for (int n = 0; n < 2; ++n) _Pragma("unroll") for (int k = 0; k < 2; ++k) \
;         acc[ai][bj][m][n] = __builtin_amdgcn_mfma_f32_16x16x32_bf16(Bt[n][k], At[m][k], acc[ai][bj][m][n], 0, 0, 0); __builtin_amdgcn_s_setprio(0); } while (0)
; #define PG8_WAIT_V(n) asm volatile("s_waitcnt vmcnt(" #n ")" ::: "memory")
; #define PG8_WAIT_L(n) asm volatile("s_waitcnt lgkmcnt(" #n ")" ::: "memory")
; #define PG8_BAR __builtin_amdgcn_s_barrier()
; #define PG8_SCHED __builtin_amdgcn_sched_barrier(0)
; template <class Epi, bool ALIGN_EPI, bool ABLK = false>
; __device__ __forceinline__ void gemm_phase(PG8_LAS unsigned char* lds, const Gemm g, const StaticOrder& S, const Epi& E) {
;     ...
;             PG8_WAIT_V(8); PG8_WAIT_L(0); PG8_BAR; PG8_MMA(1, 0, At, B0); PG8_MMA(1, 1, At, B1); PG8_BAR; PG8_SCHED;
;             PG8_LDB(B0, 1, 0); PG8_LDB(B1, 1, 1); PG8_SCHED; PG8_LDA(At, 1, 0); PG8_STAGE(PG8_SA(0, 1), a2 + hstepA, voffA);
;             PG8_WAIT_V(8); PG8_WAIT_L(0); PG8_BAR; PG8_MMA(0, 0, At, B0); PG8_MMA(0, 1, At, B1); PG8_BAR; PG8_SCHED;
;             PG8_LDA(At, 1, 1); PG8_STAGE(PG8_SB(1, 0), b3, voffB); PG8_STAGE(PG8_SB(1, 1), b3 + hstepB, voffB); PG8_STAGE(PG8_SA(1, 0), a3, voffA);
	s_setprio 1
	v_mfma_f32_16x16x32_bf16 v[66:69], v[134:137], v[166:169], v[66:69]
	v_mfma_f32_16x16x32_bf16 v[62:65], v[142:145], v[166:169], v[62:65]
	v_mfma_f32_16x16x32_bf16 v[58:61], v[134:137], v[174:177], v[58:61]
	v_mfma_f32_16x16x32_bf16 v[54:57], v[142:145], v[174:177], v[54:57]
	v_mfma_f32_16x16x32_bf16 v[50:53], v[134:137], v[182:185], v[50:53]
	v_mfma_f32_16x16x32_bf16 v[46:49], v[142:145], v[182:185], v[46:49]
	v_mfma_f32_16x16x32_bf16 v[42:45], v[134:137], v[190:193], v[42:45]
	v_mfma_f32_16x16x32_bf16 v[38:41], v[142:145], v[190:193], v[38:41]
	v_mfma_f32_16x16x32_bf16 v[66:69], v[138:141], v[170:173], v[66:69]
	v_mfma_f32_16x16x32_bf16 v[62:65], v[146:149], v[170:173], v[62:65]
	v_mfma_f32_16x16x32_bf16 v[58:61], v[138:141], v[178:181], v[58:61]
	v_mfma_f32_16x16x32_bf16 v[54:57], v[146:149], v[178:181], v[54:57]
	v_mfma_f32_16x16x32_bf16 v[50:53], v[138:141], v[186:189], v[50:53]
	v_mfma_f32_16x16x32_bf16 v[46:49], v[146:149], v[186:189], v[46:49]
	v_mfma_f32_16x16x32_bf16 v[42:45], v[138:141], v[226:229], v[42:45]
	v_mfma_f32_16x16x32_bf16 v[38:41], v[146:149], v[226:229], v[38:41]
	s_setprio 0
	s_setprio 1
	v_mfma_f32_16x16x32_bf16 v[34:37], v[150:153], v[166:169], v[34:37]
	s_add_i32 s74, 0, 0x18000
	v_mfma_f32_16x16x32_bf16 v[30:33], v[158:161], v[166:169], v[30:33]
	s_add_i32 s75, 0, 0x1c000
	v_mfma_f32_16x16x32_bf16 v[26:29], v[150:153], v[174:177], v[26:29]
	v_mfma_f32_16x16x32_bf16 v[22:25], v[158:161], v[174:177], v[22:25]
	v_mfma_f32_16x16x32_bf16 v[18:21], v[150:153], v[182:185], v[18:21]
	v_mfma_f32_16x16x32_bf16 v[14:17], v[158:161], v[182:185], v[14:17]
	v_mfma_f32_16x16x32_bf16 v[10:13], v[150:153], v[190:193], v[10:13]
	v_mfma_f32_16x16x32_bf16 v[4:7], v[158:161], v[190:193], v[6:9]
	v_mfma_f32_16x16x32_bf16 v[34:37], v[154:157], v[170:173], v[34:37]
	v_mfma_f32_16x16x32_bf16 v[30:33], v[162:165], v[170:173], v[30:33]
	v_mfma_f32_16x16x32_bf16 v[26:29], v[154:157], v[178:181], v[26:29]
	v_mfma_f32_16x16x32_bf16 v[22:25], v[162:165], v[178:181], v[22:25]
	v_mfma_f32_16x16x32_bf16 v[18:21], v[154:157], v[186:189], v[18:21]
	v_mfma_f32_16x16x32_bf16 v[14:17], v[162:165], v[186:189], v[14:17]
	v_mfma_f32_16x16x32_bf16 v[10:13], v[154:157], v[226:229], v[10:13]
	v_mfma_f32_16x16x32_bf16 v[4:7], v[162:165], v[226:229], v[4:7]
	s_setprio 0
	s_barrier
	v_add_u32_e32 v3, s74, v239
	ds_read_b128 v[134:137], v3
	ds_read_b128 v[138:141], v3 offset:1024
	ds_read_b128 v[142:145], v3 offset:2048
	ds_read_b128 v[146:149], v3 offset:3072
	v_add_u32_e32 v3, s75, v239
	ds_read_b128 v[150:153], v3
	ds_read_b128 v[154:157], v3 offset:1024
	ds_read_b128 v[158:161], v3 offset:2048
	ds_read_b128 v[162:165], v3 offset:3072
	s_add_u32 s50, s50, 0x40000
	s_addc_u32 s51, s51, 0
	s_mov_b32 m0, s55
	v_lshl_add_u64 v[8:9], s[50:51], 0, v[194:195]
	ds_read_b128 v[166:169], v240 offset:32768
	ds_read_b128 v[170:173], v240 offset:33792
	ds_read_b128 v[174:177], v240 offset:34816
	ds_read_b128 v[178:181], v240 offset:35840
	ds_read_b128 v[182:185], v240 offset:36864
	ds_read_b128 v[186:189], v240 offset:37888
	ds_read_b128 v[190:193], v240 offset:38912
	ds_read_b128 v[226:229], v240 offset:39936
	global_load_lds_dwordx4 v[8:9], off
	v_lshl_add_u64 v[8:9], s[50:51], 0, v[198:199]
	s_mov_b32 m0, s56
	s_nop 0
	global_load_lds_dwordx4 v[8:9], off
	s_waitcnt vmcnt(8)
	s_waitcnt lgkmcnt(0)
	s_barrier
	s_setprio 1
	v_mfma_f32_16x16x32_bf16 v[130:133], v[134:137], v[166:169], v[130:133]
	v_mfma_f32_16x16x32_bf16 v[126:129], v[142:145], v[166:169], v[126:129]
	v_mfma_f32_16x16x32_bf16 v[122:125], v[134:137], v[174:177], v[122:125]
	v_mfma_f32_16x16x32_bf16 v[118:121], v[142:145], v[174:177], v[118:121]
	v_mfma_f32_16x16x32_bf16 v[114:117], v[134:137], v[182:185], v[114:117]
	v_mfma_f32_16x16x32_bf16 v[110:113], v[142:145], v[182:185], v[110:113]
	v_mfma_f32_16x16x32_bf16 v[106:109], v[134:137], v[190:193], v[106:109]
	v_mfma_f32_16x16x32_bf16 v[102:105], v[142:145], v[190:193], v[102:105]
	v_mfma_f32_16x16x32_bf16 v[130:133], v[138:141], v[170:173], v[130:133]
	v_mfma_f32_16x16x32_bf16 v[126:129], v[146:149], v[170:173], v[126:129]
	v_mfma_f32_16x16x32_bf16 v[122:125], v[138:141], v[178:181], v[122:125]
	v_mfma_f32_16x16x32_bf16 v[118:121], v[146:149], v[178:181], v[118:121]
	v_mfma_f32_16x16x32_bf16 v[114:117], v[138:141], v[186:189], v[114:117]
	v_mfma_f32_16x16x32_bf16 v[110:113], v[146:149], v[186:189], v[110:113]
	v_mfma_f32_16x16x32_bf16 v[106:109], v[138:141], v[226:229], v[106:109]
	v_mfma_f32_16x16x32_bf16 v[102:105], v[146:149], v[226:229], v[102:105]
	s_setprio 0
	s_setprio 1
	v_mfma_f32_16x16x32_bf16 v[98:101], v[150:153], v[166:169], v[98:101]
	s_add_i32 s50, s74, s54
	v_mfma_f32_16x16x32_bf16 v[94:97], v[158:161], v[166:169], v[94:97]
	s_mov_b32 m0, s50
	v_mfma_f32_16x16x32_bf16 v[90:93], v[150:153], v[174:177], v[90:93]
	v_mfma_f32_16x16x32_bf16 v[86:89], v[158:161], v[174:177], v[86:89]
	v_mfma_f32_16x16x32_bf16 v[82:85], v[150:153], v[182:185], v[82:85]
	v_mfma_f32_16x16x32_bf16 v[78:81], v[158:161], v[182:185], v[78:81]
	v_mfma_f32_16x16x32_bf16 v[74:77], v[150:153], v[190:193], v[74:77]
	v_mfma_f32_16x16x32_bf16 v[70:73], v[158:161], v[190:193], v[70:73]
	v_mfma_f32_16x16x32_bf16 v[98:101], v[154:157], v[170:173], v[98:101]
	v_mfma_f32_16x16x32_bf16 v[94:97], v[162:165], v[170:173], v[94:97]
	v_mfma_f32_16x16x32_bf16 v[90:93], v[154:157], v[178:181], v[90:93]
	v_mfma_f32_16x16x32_bf16 v[86:89], v[162:165], v[178:181], v[86:89]
	v_mfma_f32_16x16x32_bf16 v[82:85], v[154:157], v[186:189], v[82:85]
	v_mfma_f32_16x16x32_bf16 v[78:81], v[162:165], v[186:189], v[78:81]
	v_mfma_f32_16x16x32_bf16 v[74:77], v[154:157], v[226:229], v[74:77]
	v_mfma_f32_16x16x32_bf16 v[70:73], v[162:165], v[226:229], v[70:73]
	s_setprio 0
	s_barrier
; #define PG8_STAGE(bufoff, gbase, voff) do { _Pragma("unroll") for (int _i = 0; _i < 2; ++_i) \
;         __builtin_amdgcn_global_load_lds((const unsigned*)((const char*)(gbase) + (voff)[_i]), (PG8_LAS unsigned*)(lds + (bufoff) + ldsw + _i * 8192), 16, 0, 0); } while (0)
; #define PG8_LDA(dst, b, h) do { _Pragma("unroll") for (int m = 0; m < 4; ++m) _Pragma("unroll") for (int k = 0; k < 2; ++k) dst[m][k] = *(const PG8_LAS bf16x8*)(lds + PG8_SA(b, h) + aoff + m * 2048 + k * 1024); } while (0)
; #define PG8_MMA(ai, bj, At, Bt) do { __builtin_amdgcn_s_setprio(1); _Pragma("unroll") for (int m = 0; m < 4; ++m) _Pragma("unroll") for (int n = 0; n < 2; ++n) _Pragma("unroll") for (int k = 0; k < 2; ++k) \
;         acc[ai][bj][m][n] = __builtin_amdgcn_mfma_f32_16x16x32_bf16(Bt[n][k], At[m][k], acc[ai][bj][m][n], 0, 0, 0); __builtin_amdgcn_s_setprio(0); } while (0)
; #define PG8_WAIT_V(n) asm volatile("s_waitcnt vmcnt(" #n ")" ::: "memory")
; #define PG8_WAIT_L(n) asm volatile("s_waitcnt lgkmcnt(" #n ")" ::: "memory")
; #define PG8_BAR __builtin_amdgcn_s_barrier()
; #define PG8_SCHED __builtin_amdgcn_sched_barrier(0)
; template <class Epi, bool ALIGN_EPI, bool ABLK = false>
; __device__ __forceinline__ void gemm_phase(PG8_LAS unsigned char* lds, const Gemm g, const StaticOrder& S, const Epi& E) {
;     ...
;             PG8_LDA(At, 1, 1); PG8_STAGE(PG8_SB(1, 0), b3, voffB); PG8_STAGE(PG8_SB(1, 1), b3 + hstepB, voffB); PG8_STAGE(PG8_SA(1, 0), a3, voffA);
;             PG8_WAIT_V(8); PG8_WAIT_L(0); PG8_BAR; PG8_MMA(1, 0, At, B0); PG8_MMA(1, 1, At, B1); PG8_BAR; PG8_SCHED;
;         }
;         if constexpr (ALIGN_EPI) { if (wr == 0) PG8_BAR; }
	v_lshl_add_u64 v[8:9], v[230:231], 0, s[22:23]
	ds_read_b128 v[166:169], v240 offset:49152
	ds_read_b128 v[170:173], v240 offset:50176
	ds_read_b128 v[174:177], v240 offset:51200
	ds_read_b128 v[178:181], v240 offset:52224
	ds_read_b128 v[182:185], v240 offset:53248
	ds_read_b128 v[186:189], v240 offset:54272
	ds_read_b128 v[190:193], v240 offset:55296
	ds_read_b128 v[226:229], v240 offset:56320
	global_load_lds_dwordx4 v[8:9], off
	s_add_i32 m0, s50, 0x2000
	s_add_u32 s48, s48, 0x80080
	v_lshl_add_u64 v[8:9], v[242:243], 0, s[22:23]
	s_addc_u32 s49, s49, 0
	s_add_i32 s50, s75, s54
	global_load_lds_dwordx4 v[8:9], off
	v_lshl_add_u64 v[8:9], s[48:49], 0, v[196:197]
	s_mov_b32 m0, s50
	s_nop 0
	global_load_lds_dwordx4 v[8:9], off
	v_lshl_add_u64 v[8:9], s[48:49], 0, v[200:201]
	s_add_i32 m0, s50, 0x2000
	s_nop 0
	global_load_lds_dwordx4 v[8:9], off
	v_lshl_add_u64 v[8:9], v[244:245], 0, s[22:23]
	s_mov_b32 m0, s59
	s_nop 0
	global_load_lds_dwordx4 v[8:9], off
	v_lshl_add_u64 v[8:9], v[246:247], 0, s[22:23]
	s_mov_b32 m0, s60
	s_nop 0
	global_load_lds_dwordx4 v[8:9], off
	s_waitcnt vmcnt(8)
	s_waitcnt lgkmcnt(0)
	s_barrier
	s_setprio 1
	v_mfma_f32_16x16x32_bf16 v[66:69], v[134:137], v[166:169], v[66:69]
	v_mfma_f32_16x16x32_bf16 v[62:65], v[142:145], v[166:169], v[62:65]
	v_mfma_f32_16x16x32_bf16 v[58:61], v[134:137], v[174:177], v[58:61]
	v_mfma_f32_16x16x32_bf16 v[54:57], v[142:145], v[174:177], v[54:57]
	v_mfma_f32_16x16x32_bf16 v[50:53], v[134:137], v[182:185], v[50:53]
	v_mfma_f32_16x16x32_bf16 v[46:49], v[142:145], v[182:185], v[46:49]
	v_mfma_f32_16x16x32_bf16 v[42:45], v[134:137], v[190:193], v[42:45]
	v_mfma_f32_16x16x32_bf16 v[38:41], v[142:145], v[190:193], v[38:41]
	v_mfma_f32_16x16x32_bf16 v[66:69], v[138:141], v[170:173], v[66:69]
	v_mfma_f32_16x16x32_bf16 v[62:65], v[146:149], v[170:173], v[62:65]
	v_mfma_f32_16x16x32_bf16 v[58:61], v[138:141], v[178:181], v[58:61]
	v_mfma_f32_16x16x32_bf16 v[54:57], v[146:149], v[178:181], v[54:57]
	v_mfma_f32_16x16x32_bf16 v[50:53], v[138:141], v[186:189], v[50:53]
	v_mfma_f32_16x16x32_bf16 v[46:49], v[146:149], v[186:189], v[46:49]
	v_mfma_f32_16x16x32_bf16 v[42:45], v[138:141], v[226:229], v[42:45]
	v_mfma_f32_16x16x32_bf16 v[38:41], v[146:149], v[226:229], v[38:41]
	s_setprio 0
	s_setprio 1
	v_mfma_f32_16x16x32_bf16 v[34:37], v[150:153], v[166:169], v[34:37]
	s_add_i32 s73, s73, 2
	v_mfma_f32_16x16x32_bf16 v[30:33], v[158:161], v[166:169], v[30:33]
	s_add_u32 s6, s6, 0x100
	v_mfma_f32_16x16x32_bf16 v[26:29], v[150:153], v[174:177], v[26:29]
	s_addc_u32 s7, s7, 0
	v_mfma_f32_16x16x32_bf16 v[22:25], v[158:161], v[174:177], v[22:25]
	s_add_u32 s71, s71, 0x100
	v_mfma_f32_16x16x32_bf16 v[18:21], v[150:153], v[182:185], v[18:21]
	s_addc_u32 s72, s72, 0
	v_mfma_f32_16x16x32_bf16 v[14:17], v[158:161], v[182:185], v[14:17]
	s_cmp_gt_u32 s73, 13
	v_mfma_f32_16x16x32_bf16 v[8:11], v[150:153], v[190:193], v[10:13]
	v_mfma_f32_16x16x32_bf16 v[4:7], v[158:161], v[190:193], v[4:7]
	v_mfma_f32_16x16x32_bf16 v[34:37], v[154:157], v[170:173], v[34:37]
	v_mfma_f32_16x16x32_bf16 v[30:33], v[162:165], v[170:173], v[30:33]
	v_mfma_f32_16x16x32_bf16 v[26:29], v[154:157], v[178:181], v[26:29]
	v_mfma_f32_16x16x32_bf16 v[22:25], v[162:165], v[178:181], v[22:25]
	v_mfma_f32_16x16x32_bf16 v[18:21], v[154:157], v[186:189], v[18:21]
	v_mfma_f32_16x16x32_bf16 v[14:17], v[162:165], v[186:189], v[14:17]
	v_mfma_f32_16x16x32_bf16 v[10:13], v[154:157], v[226:229], v[8:11]
	v_mfma_f32_16x16x32_bf16 v[6:9], v[162:165], v[226:229], v[4:7]
	s_setprio 0
	s_barrier
	s_cbranch_scc0 .LBB0_2105
	s_and_b64 vcc, exec, s[24:25]
	s_cbranch_vccz .LBB0_2108
	s_barrier

; #define PG8_STAGE(bufoff, gbase, voff) do { _Pragma("unroll") for (int _i = 0; _i < 2; ++_i) \
;         __builtin_amdgcn_global_load_lds((const unsigned*)((const char*)(gbase) + (voff)[_i]), (PG8_LAS unsigned*)(lds + (bufoff) + ldsw + _i * 8192), 16, 0, 0); } while (0)
; #define PG8_LDA(dst, b, h) do { _Pragma("unroll") for (int m = 0; m < 4; ++m) _Pragma("unroll") for (int k = 0; k < 2; ++k) dst[m][k] = *(const PG8_LAS bf16x8*)(lds + PG8_SA(b, h) + aoff + m * 2048 + k * 1024); } while (0)
; #define PG8_LDB(dst, b, h) do { _Pragma("unroll") for (int n = 0; n < 2; ++n) _Pragma("unroll") for (int k = 0; k < 2; ++k) dst[n][k] = *(const PG8_LAS bf16x8*)(lds + PG8_SB(b, h) + boff + n * 2048 + k * 1024); } while (0)
; #define PG8_MMA(ai, bj, At, Bt) do { __builtin_amdgcn_s_setprio(1); _Pragma("unroll") for (int m = 0; m < 4; ++m) _Pragma("unroll") for (int n = 0; n < 2; ++n) _Pragma("unroll") for (int k = 0; k < 2; ++k) \
;         acc[ai][bj][m][n] = __builtin_amdgcn_mfma_f32_16x16x32_bf16(Bt[n][k], At[m][k], acc[ai][bj][m][n], 0, 0, 0); __builtin_amdgcn_s_setprio(0); } while (0)
; #define PG8_WAIT_V(n) asm volatile("s_waitcnt vmcnt(" #n ")" ::: "memory")
; #define PG8_WAIT_L(n) asm volatile("s_waitcnt lgkmcnt(" #n ")" ::: "memory")
; #define PG8_BAR __builtin_amdgcn_s_barrier()
; #define PG8_SCHED __builtin_amdgcn_sched_barrier(0)
; template <class Epi, bool ALIGN_EPI, bool ABLK = false>
; __device__ __forceinline__ void gemm_phase(PG8_LAS unsigned char* lds, const Gemm g, const StaticOrder& S, const Epi& E) {
;     ...
;             PG8_LDB(B0, 0, 0); PG8_LDB(B1, 0, 1); PG8_SCHED; PG8_LDA(At, 0, 0); PG8_STAGE(PG8_SA(1, 1), a1 + hstepA, voffA);
;             PG8_WAIT_V(8); PG8_WAIT_L(0); PG8_BAR; PG8_MMA(0, 0, At, B0); PG8_MMA(0, 1, At, B1); PG8_BAR; PG8_SCHED;
;             PG8_LDA(At, 0, 1); PG8_STAGE(PG8_SB(0, 0), b2, voffB); PG8_STAGE(PG8_SB(0, 1), b2 + hstepB, voffB); PG8_STAGE(PG8_SA(0, 0), a2, voffA);
;             PG8_WAIT_V(8); PG8_WAIT_L(0); PG8_BAR; PG8_MMA(1, 0, At, B0); PG8_MMA(1, 1, At, B1); PG8_BAR; PG8_SCHED;
.LBB0_2289:
	ds_read_b128 v[102:105], v232
	ds_read_b128 v[110:113], v232 offset:1024
	ds_read_b128 v[122:125], v232 offset:2048
	ds_read_b128 v[134:137], v232 offset:3072
	ds_read_b128 v[146:149], v233
	ds_read_b128 v[150:153], v233 offset:1024
	ds_read_b128 v[154:157], v233 offset:2048
	ds_read_b128 v[158:161], v233 offset:3072
	s_cmp_eq_u32 s82, 12
	s_cselect_b32 s85, s51, s57
	s_cselect_b32 s84, s60, s56
	s_cselect_b32 s59, s49, s81
	s_cselect_b32 s58, s61, s80
	s_movk_i32 s86, 0xc000
	v_lshl_add_u64 v[212:213], s[56:57], 0, v[186:187]
	s_mov_b32 s87, -1
	v_lshl_add_u64 v[244:245], v[212:213], 0, s[86:87]
	s_movk_i32 s86, 0xe000
	s_add_i32 m0, s9, 0xc000
	s_mov_b32 s87, -1
	ds_read_b128 v[162:165], v234
	ds_read_b128 v[166:169], v234 offset:1024
	ds_read_b128 v[170:173], v234 offset:2048
	ds_read_b128 v[174:177], v234 offset:3072
	ds_read_b128 v[178:181], v234 offset:4096
	ds_read_b128 v[182:185], v234 offset:5120
	ds_read_b128 v[236:239], v234 offset:6144
	ds_read_b128 v[240:243], v234 offset:7168
	global_load_lds_dwordx4 v[244:245], off
	v_lshl_add_u64 v[212:213], v[212:213], 0, s[86:87]
	s_add_i32 m0, s9, 0xe000
	s_nop 0
	global_load_lds_dwordx4 v[212:213], off
	s_waitcnt vmcnt(8)
	s_waitcnt lgkmcnt(0)
	s_barrier
	s_setprio 1
	v_mfma_f32_16x16x32_bf16 v[142:145], v[102:105], v[162:165], v[142:145]
	v_mfma_f32_16x16x32_bf16 v[138:141], v[122:125], v[162:165], v[138:141]
	v_mfma_f32_16x16x32_bf16 v[118:121], v[102:105], v[170:173], v[118:121]
	v_mfma_f32_16x16x32_bf16 v[114:117], v[122:125], v[170:173], v[114:117]
	v_mfma_f32_16x16x32_bf16 v[94:97], v[102:105], v[178:181], v[94:97]
	v_mfma_f32_16x16x32_bf16 v[90:93], v[122:125], v[178:181], v[90:93]
	v_mfma_f32_16x16x32_bf16 v[78:81], v[102:105], v[236:239], v[78:81]
	v_mfma_f32_16x16x32_bf16 v[74:77], v[122:125], v[236:239], v[74:77]
	v_mfma_f32_16x16x32_bf16 v[142:145], v[110:113], v[166:169], v[142:145]
	v_mfma_f32_16x16x32_bf16 v[138:141], v[134:137], v[166:169], v[138:141]
	v_mfma_f32_16x16x32_bf16 v[118:121], v[110:113], v[174:177], v[118:121]
	v_mfma_f32_16x16x32_bf16 v[114:117], v[134:137], v[174:177], v[114:117]
	v_mfma_f32_16x16x32_bf16 v[94:97], v[110:113], v[182:185], v[94:97]
	v_mfma_f32_16x16x32_bf16 v[90:93], v[134:137], v[182:185], v[90:93]
	v_mfma_f32_16x16x32_bf16 v[78:81], v[110:113], v[240:243], v[78:81]
	v_mfma_f32_16x16x32_bf16 v[74:77], v[134:137], v[240:243], v[74:77]
	s_setprio 0
	s_setprio 1
	v_mfma_f32_16x16x32_bf16 v[130:133], v[146:149], v[162:165], v[130:133]
	s_add_i32 s83, s77, s65
	v_mfma_f32_16x16x32_bf16 v[126:129], v[154:157], v[162:165], v[126:129]
	s_mov_b32 m0, s83
	v_mfma_f32_16x16x32_bf16 v[106:109], v[146:149], v[170:173], v[106:109]
	v_mfma_f32_16x16x32_bf16 v[98:101], v[154:157], v[170:173], v[98:101]
	v_mfma_f32_16x16x32_bf16 v[86:89], v[146:149], v[178:181], v[86:89]
	v_mfma_f32_16x16x32_bf16 v[82:85], v[154:157], v[178:181], v[82:85]
	v_mfma_f32_16x16x32_bf16 v[70:73], v[146:149], v[236:239], v[70:73]
	v_mfma_f32_16x16x32_bf16 v[66:69], v[154:157], v[236:239], v[66:69]
	v_mfma_f32_16x16x32_bf16 v[130:133], v[150:153], v[166:169], v[130:133]
	v_mfma_f32_16x16x32_bf16 v[126:129], v[158:161], v[166:169], v[126:129]
	v_mfma_f32_16x16x32_bf16 v[106:109], v[150:153], v[174:177], v[106:109]
	v_mfma_f32_16x16x32_bf16 v[98:101], v[158:161], v[174:177], v[98:101]
	v_mfma_f32_16x16x32_bf16 v[86:89], v[150:153], v[182:185], v[86:89]
	v_mfma_f32_16x16x32_bf16 v[82:85], v[158:161], v[182:185], v[82:85]
	v_mfma_f32_16x16x32_bf16 v[70:73], v[150:153], v[240:243], v[70:73]
	v_mfma_f32_16x16x32_bf16 v[66:69], v[158:161], v[240:243], v[66:69]
	s_setprio 0
	s_barrier
	v_lshl_add_u64 v[212:213], s[58:59], 0, v[188:189]
	ds_read_b128 v[162:165], v234 offset:16384
	ds_read_b128 v[166:169], v234 offset:17408
	ds_read_b128 v[170:173], v234 offset:18432
	ds_read_b128 v[174:177], v234 offset:19456
	ds_read_b128 v[178:181], v234 offset:20480
	ds_read_b128 v[182:185], v234 offset:21504
	ds_read_b128 v[236:239], v234 offset:22528
	ds_read_b128 v[240:243], v234 offset:23552
	global_load_lds_dwordx4 v[212:213], off
	s_add_i32 m0, s83, 0x2000
	s_add_u32 s86, s58, 0x40000
	v_lshl_add_u64 v[244:245], s[58:59], 0, v[190:191]
	s_addc_u32 s87, s59, 0
	s_add_i32 s83, s78, s65
	global_load_lds_dwordx4 v[244:245], off
	v_lshl_add_u64 v[246:247], s[86:87], 0, v[188:189]
	s_mov_b32 m0, s83
	s_nop 0
	global_load_lds_dwordx4 v[246:247], off
	v_lshl_add_u64 v[246:247], s[86:87], 0, v[190:191]
	s_add_i32 m0, s83, 0x2000
	s_nop 0
	global_load_lds_dwordx4 v[246:247], off
	v_lshl_add_u64 v[246:247], s[84:85], 0, v[186:187]
	s_mov_b32 m0, s9
	v_lshl_add_u64 v[248:249], v[246:247], 0, s[10:11]
	global_load_lds_dwordx4 v[246:247], off
	s_mov_b32 m0, s66
	s_nop 0
	global_load_lds_dwordx4 v[248:249], off
	s_waitcnt vmcnt(8)
	s_waitcnt lgkmcnt(0)
	s_barrier
; #define PG8_STAGE(bufoff, gbase, voff) do { _Pragma("unroll") for (int _i = 0; _i < 2; ++_i) \
;         __builtin_amdgcn_global_load_lds((const unsigned*)((const char*)(gbase) + (voff)[_i]), (PG8_LAS unsigned*)(lds + (bufoff) + ldsw + _i * 8192), 16, 0, 0); } while (0)
; #define PG8_LDA(dst, b, h) do { _Pragma("unroll") for (int m = 0; m < 4; ++m) _Pragma("unroll") for (int k = 0; k < 2; ++k) dst[m][k] = *(const PG8_LAS bf16x8*)(lds + PG8_SA(b, h) + aoff + m * 2048 + k * 1024); } while (0)
; #define PG8_LDB(dst, b, h) do { _Pragma("unroll") for (int n = 0; n < 2; ++n) _Pragma("unroll") for (int k = 0; k < 2; ++k) dst[n][k] = *(const PG8_LAS bf16x8*)(lds + PG8_SB(b, h) + boff + n * 2048 + k * 1024); } while (0)
; #define PG8_MMA(ai, bj, At, Bt) do { __builtin_amdgcn_s_setprio(1); _Pragma("unroll") for (int m = 0; m < 4; ++m) _Pragma("unroll") for (int n = 0; n < 2; ++n) _Pragma("unroll") for (int k = 0; k < 2; ++k) \
;         acc[ai][bj][m][n] = __builtin_amdgcn_mfma_f32_16x16x32_bf16(Bt[n][k], At[m][k], acc[ai][bj][m][n], 0, 0, 0); __builtin_amdgcn_s_setprio(0); } while (0)
; #define PG8_WAIT_V(n) asm volatile("s_waitcnt vmcnt(" #n ")" ::: "memory")
; #define PG8_WAIT_L(n) asm volatile("s_waitcnt lgkmcnt(" #n ")" ::: "memory")
; #define PG8_BAR __builtin_amdgcn_s_barrier()
; #define PG8_SCHED __builtin_amdgcn_sched_barrier(0)
; template <class Epi, bool ALIGN_EPI, bool ABLK = false>
; __device__ __forceinline__ void gemm_phase(PG8_LAS unsigned char* lds, const Gemm g, const StaticOrder& S, const Epi& E) {
;     ...
;             PG8_WAIT_V(8); PG8_WAIT_L(0); PG8_BAR; PG8_MMA(1, 0, At, B0); PG8_MMA(1, 1, At, B1); PG8_BAR; PG8_SCHED;
;             PG8_LDB(B0, 1, 0); PG8_LDB(B1, 1, 1); PG8_SCHED; PG8_LDA(At, 1, 0); PG8_STAGE(PG8_SA(0, 1), a2 + hstepA, voffA);
;             PG8_WAIT_V(8); PG8_WAIT_L(0); PG8_BAR; PG8_MMA(0, 0, At, B0); PG8_MMA(0, 1, At, B1); PG8_BAR; PG8_SCHED;
;             PG8_LDA(At, 1, 1); PG8_STAGE(PG8_SB(1, 0), b3, voffB); PG8_STAGE(PG8_SB(1, 1), b3 + hstepB, voffB); PG8_STAGE(PG8_SA(1, 0), a3, voffA);
	s_setprio 1
	v_mfma_f32_16x16x32_bf16 v[62:65], v[102:105], v[162:165], v[62:65]
	v_mfma_f32_16x16x32_bf16 v[58:61], v[122:125], v[162:165], v[58:61]
	v_mfma_f32_16x16x32_bf16 v[46:49], v[102:105], v[170:173], v[46:49]
	v_mfma_f32_16x16x32_bf16 v[42:45], v[122:125], v[170:173], v[42:45]
	v_mfma_f32_16x16x32_bf16 v[30:33], v[102:105], v[178:181], v[30:33]
	v_mfma_f32_16x16x32_bf16 v[26:29], v[122:125], v[178:181], v[26:29]
	v_mfma_f32_16x16x32_bf16 v[14:17], v[102:105], v[236:239], v[14:17]
	v_mfma_f32_16x16x32_bf16 v[10:13], v[122:125], v[236:239], v[10:13]
	v_mfma_f32_16x16x32_bf16 v[62:65], v[110:113], v[166:169], v[62:65]
	v_mfma_f32_16x16x32_bf16 v[58:61], v[134:137], v[166:169], v[58:61]
	v_mfma_f32_16x16x32_bf16 v[46:49], v[110:113], v[174:177], v[46:49]
	v_mfma_f32_16x16x32_bf16 v[42:45], v[134:137], v[174:177], v[42:45]
	v_mfma_f32_16x16x32_bf16 v[30:33], v[110:113], v[182:185], v[30:33]
	v_mfma_f32_16x16x32_bf16 v[26:29], v[134:137], v[182:185], v[26:29]
	v_mfma_f32_16x16x32_bf16 v[14:17], v[110:113], v[240:243], v[14:17]
	v_mfma_f32_16x16x32_bf16 v[10:13], v[134:137], v[240:243], v[10:13]
	s_setprio 0
	s_setprio 1
	v_mfma_f32_16x16x32_bf16 v[54:57], v[146:149], v[162:165], v[54:57]
	s_add_i32 s83, 0, 0x18000
	v_mfma_f32_16x16x32_bf16 v[50:53], v[154:157], v[162:165], v[50:53]
	s_add_i32 s84, 0, 0x1c000
	v_mfma_f32_16x16x32_bf16 v[38:41], v[146:149], v[170:173], v[38:41]
	v_mfma_f32_16x16x32_bf16 v[34:37], v[154:157], v[170:173], v[34:37]
	v_mfma_f32_16x16x32_bf16 v[22:25], v[146:149], v[178:181], v[22:25]
	v_mfma_f32_16x16x32_bf16 v[18:21], v[154:157], v[178:181], v[18:21]
	v_mfma_f32_16x16x32_bf16 v[6:9], v[146:149], v[236:239], v[6:9]
	v_mfma_f32_16x16x32_bf16 v[2:5], v[154:157], v[236:239], v[2:5]
	v_mfma_f32_16x16x32_bf16 v[54:57], v[150:153], v[166:169], v[54:57]
	v_mfma_f32_16x16x32_bf16 v[50:53], v[158:161], v[166:169], v[50:53]
	v_mfma_f32_16x16x32_bf16 v[38:41], v[150:153], v[174:177], v[38:41]
	v_mfma_f32_16x16x32_bf16 v[34:37], v[158:161], v[174:177], v[34:37]
	v_mfma_f32_16x16x32_bf16 v[22:25], v[150:153], v[182:185], v[22:25]
	v_mfma_f32_16x16x32_bf16 v[18:21], v[158:161], v[182:185], v[18:21]
	v_mfma_f32_16x16x32_bf16 v[6:9], v[150:153], v[240:243], v[6:9]
	v_mfma_f32_16x16x32_bf16 v[2:5], v[158:161], v[240:243], v[2:5]
	s_setprio 0
	s_barrier
	v_add_u32_e32 v134, s83, v224
	v_add_u32_e32 v158, s84, v224
	ds_read_b128 v[102:105], v134
	ds_read_b128 v[110:113], v134 offset:1024
	ds_read_b128 v[122:125], v134 offset:2048
	ds_read_b128 v[134:137], v134 offset:3072
	ds_read_b128 v[146:149], v158
	ds_read_b128 v[150:153], v158 offset:1024
	ds_read_b128 v[154:157], v158 offset:2048
	ds_read_b128 v[158:161], v158 offset:3072
	s_mov_b32 m0, s67
	v_lshl_add_u64 v[248:249], v[246:247], 0, s[12:13]
	ds_read_b128 v[162:165], v234 offset:32768
	ds_read_b128 v[166:169], v234 offset:33792
	ds_read_b128 v[170:173], v234 offset:34816
	ds_read_b128 v[174:177], v234 offset:35840
	ds_read_b128 v[178:181], v234 offset:36864
	ds_read_b128 v[182:185], v234 offset:37888
	ds_read_b128 v[236:239], v234 offset:38912
	ds_read_b128 v[240:243], v234 offset:39936
	global_load_lds_dwordx4 v[248:249], off
	v_lshl_add_u64 v[248:249], v[246:247], 0, s[24:25]
	s_mov_b32 m0, s68
	s_nop 0
	global_load_lds_dwordx4 v[248:249], off
	s_waitcnt vmcnt(8)
	s_waitcnt lgkmcnt(0)
	s_barrier
	s_setprio 1
	v_mfma_f32_16x16x32_bf16 v[142:145], v[102:105], v[162:165], v[142:145]
	v_mfma_f32_16x16x32_bf16 v[138:141], v[122:125], v[162:165], v[138:141]
	v_mfma_f32_16x16x32_bf16 v[118:121], v[102:105], v[170:173], v[118:121]
	v_mfma_f32_16x16x32_bf16 v[114:117], v[122:125], v[170:173], v[114:117]
	v_mfma_f32_16x16x32_bf16 v[94:97], v[102:105], v[178:181], v[94:97]
	v_mfma_f32_16x16x32_bf16 v[90:93], v[122:125], v[178:181], v[90:93]
	v_mfma_f32_16x16x32_bf16 v[78:81], v[102:105], v[236:239], v[78:81]
	v_mfma_f32_16x16x32_bf16 v[74:77], v[122:125], v[236:239], v[74:77]
	v_mfma_f32_16x16x32_bf16 v[142:145], v[110:113], v[166:169], v[142:145]
	v_mfma_f32_16x16x32_bf16 v[138:141], v[134:137], v[166:169], v[138:141]
	v_mfma_f32_16x16x32_bf16 v[118:121], v[110:113], v[174:177], v[118:121]
	v_mfma_f32_16x16x32_bf16 v[114:117], v[134:137], v[174:177], v[114:117]
	v_mfma_f32_16x16x32_bf16 v[94:97], v[110:113], v[182:185], v[94:97]
	v_mfma_f32_16x16x32_bf16 v[90:93], v[134:137], v[182:185], v[90:93]
	v_mfma_f32_16x16x32_bf16 v[78:81], v[110:113], v[240:243], v[78:81]
	v_mfma_f32_16x16x32_bf16 v[74:77], v[134:137], v[240:243], v[74:77]
	s_setprio 0
	s_setprio 1
	v_mfma_f32_16x16x32_bf16 v[130:133], v[146:149], v[162:165], v[130:133]
	s_add_i32 s83, s83, s65
	v_mfma_f32_16x16x32_bf16 v[126:129], v[154:157], v[162:165], v[126:129]
	s_mov_b32 m0, s83
	v_mfma_f32_16x16x32_bf16 v[106:109], v[146:149], v[170:173], v[106:109]
	v_mfma_f32_16x16x32_bf16 v[98:101], v[154:157], v[170:173], v[98:101]
	v_mfma_f32_16x16x32_bf16 v[86:89], v[146:149], v[178:181], v[86:89]
	v_mfma_f32_16x16x32_bf16 v[82:85], v[154:157], v[178:181], v[82:85]
	v_mfma_f32_16x16x32_bf16 v[70:73], v[146:149], v[236:239], v[70:73]
	v_mfma_f32_16x16x32_bf16 v[66:69], v[154:157], v[236:239], v[66:69]
	v_mfma_f32_16x16x32_bf16 v[130:133], v[150:153], v[166:169], v[130:133]
	v_mfma_f32_16x16x32_bf16 v[126:129], v[158:161], v[166:169], v[126:129]
	v_mfma_f32_16x16x32_bf16 v[106:109], v[150:153], v[174:177], v[106:109]
	v_mfma_f32_16x16x32_bf16 v[98:101], v[158:161], v[174:177], v[98:101]
	v_mfma_f32_16x16x32_bf16 v[86:89], v[150:153], v[182:185], v[86:89]
	v_mfma_f32_16x16x32_bf16 v[82:85], v[158:161], v[182:185], v[82:85]
	v_mfma_f32_16x16x32_bf16 v[70:73], v[150:153], v[240:243], v[70:73]
	v_mfma_f32_16x16x32_bf16 v[66:69], v[158:161], v[240:243], v[66:69]
	s_setprio 0
	s_barrier
; #define PG8_STAGE(bufoff, gbase, voff) do { _Pragma("unroll") for (int _i = 0; _i < 2; ++_i) \
;         __builtin_amdgcn_global_load_lds((const unsigned*)((const char*)(gbase) + (voff)[_i]), (PG8_LAS unsigned*)(lds + (bufoff) + ldsw + _i * 8192), 16, 0, 0); } while (0)
; #define PG8_LDA(dst, b, h) do { _Pragma("unroll") for (int m = 0; m < 4; ++m) _Pragma("unroll") for (int k = 0; k < 2; ++k) dst[m][k] = *(const PG8_LAS bf16x8*)(lds + PG8_SA(b, h) + aoff + m * 2048 + k * 1024); } while (0)
; #define PG8_MMA(ai, bj, At, Bt) do { __builtin_amdgcn_s_setprio(1); _Pragma("unroll") for (int m = 0; m < 4; ++m) _Pragma("unroll") for (int n = 0; n < 2; ++n) _Pragma("unroll") for (int k = 0; k < 2; ++k) \
;         acc[ai][bj][m][n] = __builtin_amdgcn_mfma_f32_16x16x32_bf16(Bt[n][k], At[m][k], acc[ai][bj][m][n], 0, 0, 0); __builtin_amdgcn_s_setprio(0); } while (0)
; #define PG8_WAIT_V(n) asm volatile("s_waitcnt vmcnt(" #n ")" ::: "memory")
; #define PG8_WAIT_L(n) asm volatile("s_waitcnt lgkmcnt(" #n ")" ::: "memory")
; #define PG8_BAR __builtin_amdgcn_s_barrier()
; #define PG8_SCHED __builtin_amdgcn_sched_barrier(0)
; template <class Epi, bool ALIGN_EPI, bool ABLK = false>
; __device__ __forceinline__ void gemm_phase(PG8_LAS unsigned char* lds, const Gemm g, const StaticOrder& S, const Epi& E) {
;     ...
;             PG8_LDA(At, 1, 1); PG8_STAGE(PG8_SB(1, 0), b3, voffB); PG8_STAGE(PG8_SB(1, 1), b3 + hstepB, voffB); PG8_STAGE(PG8_SA(1, 0), a3, voffA);
;             PG8_WAIT_V(8); PG8_WAIT_L(0); PG8_BAR; PG8_MMA(1, 0, At, B0); PG8_MMA(1, 1, At, B1); PG8_BAR; PG8_SCHED;
;         }
;         if constexpr (ALIGN_EPI) { if (wr == 0) PG8_BAR; }
	v_lshl_add_u64 v[212:213], v[212:213], 0, s[34:35]
	ds_read_b128 v[162:165], v234 offset:49152
	ds_read_b128 v[166:169], v234 offset:50176
	ds_read_b128 v[170:173], v234 offset:51200
	ds_read_b128 v[174:177], v234 offset:52224
	ds_read_b128 v[178:181], v234 offset:53248
	ds_read_b128 v[182:185], v234 offset:54272
	ds_read_b128 v[236:239], v234 offset:55296
	ds_read_b128 v[240:243], v234 offset:56320
	global_load_lds_dwordx4 v[212:213], off
	s_add_i32 m0, s83, 0x2000
	s_add_u32 s58, s58, 0x40080
	v_lshl_add_u64 v[212:213], v[244:245], 0, s[34:35]
	s_addc_u32 s59, s59, 0
	s_add_i32 s83, s84, s65
	global_load_lds_dwordx4 v[212:213], off
	v_lshl_add_u64 v[212:213], s[58:59], 0, v[188:189]
	s_mov_b32 m0, s83
	s_nop 0
	global_load_lds_dwordx4 v[212:213], off
	v_lshl_add_u64 v[212:213], s[58:59], 0, v[190:191]
	s_add_i32 m0, s83, 0x2000
	s_nop 0
	global_load_lds_dwordx4 v[212:213], off
	v_lshl_add_u64 v[212:213], v[246:247], 0, s[36:37]
	s_mov_b32 m0, s71
	s_nop 0
	global_load_lds_dwordx4 v[212:213], off
	v_lshl_add_u64 v[212:213], v[246:247], 0, s[38:39]
	s_mov_b32 m0, s72
	s_nop 0
	global_load_lds_dwordx4 v[212:213], off
	s_waitcnt vmcnt(8)
	s_waitcnt lgkmcnt(0)
	s_barrier
	s_setprio 1
	v_mfma_f32_16x16x32_bf16 v[62:65], v[102:105], v[162:165], v[62:65]
	v_mfma_f32_16x16x32_bf16 v[58:61], v[122:125], v[162:165], v[58:61]
	v_mfma_f32_16x16x32_bf16 v[46:49], v[102:105], v[170:173], v[46:49]
	v_mfma_f32_16x16x32_bf16 v[42:45], v[122:125], v[170:173], v[42:45]
	v_mfma_f32_16x16x32_bf16 v[30:33], v[102:105], v[178:181], v[30:33]
	v_mfma_f32_16x16x32_bf16 v[26:29], v[122:125], v[178:181], v[26:29]
	v_mfma_f32_16x16x32_bf16 v[14:17], v[102:105], v[236:239], v[14:17]
	v_mfma_f32_16x16x32_bf16 v[10:13], v[122:125], v[236:239], v[10:13]
	v_mfma_f32_16x16x32_bf16 v[62:65], v[110:113], v[166:169], v[62:65]
	v_mfma_f32_16x16x32_bf16 v[58:61], v[134:137], v[166:169], v[58:61]
	v_mfma_f32_16x16x32_bf16 v[46:49], v[110:113], v[174:177], v[46:49]
	v_mfma_f32_16x16x32_bf16 v[42:45], v[134:137], v[174:177], v[42:45]
	v_mfma_f32_16x16x32_bf16 v[30:33], v[110:113], v[182:185], v[30:33]
	v_mfma_f32_16x16x32_bf16 v[26:29], v[134:137], v[182:185], v[26:29]
	v_mfma_f32_16x16x32_bf16 v[14:17], v[110:113], v[240:243], v[14:17]
	v_mfma_f32_16x16x32_bf16 v[10:13], v[134:137], v[240:243], v[10:13]
	s_setprio 0
	s_setprio 1
	v_mfma_f32_16x16x32_bf16 v[54:57], v[146:149], v[162:165], v[54:57]
	s_add_i32 s82, s82, 2
	v_mfma_f32_16x16x32_bf16 v[50:53], v[154:157], v[162:165], v[50:53]
	s_add_u32 s80, s80, 0x100
	v_mfma_f32_16x16x32_bf16 v[38:41], v[146:149], v[170:173], v[38:41]
	s_addc_u32 s81, s81, 0
	v_mfma_f32_16x16x32_bf16 v[34:37], v[154:157], v[170:173], v[34:37]
	s_add_u32 s56, s56, 0x10000
	v_mfma_f32_16x16x32_bf16 v[22:25], v[146:149], v[178:181], v[22:25]
	s_addc_u32 s57, s57, 0
	v_mfma_f32_16x16x32_bf16 v[18:21], v[154:157], v[178:181], v[18:21]
	s_cmp_gt_u32 s82, 13
	v_mfma_f32_16x16x32_bf16 v[6:9], v[146:149], v[236:239], v[6:9]
	v_mfma_f32_16x16x32_bf16 v[2:5], v[154:157], v[236:239], v[2:5]
	v_mfma_f32_16x16x32_bf16 v[54:57], v[150:153], v[166:169], v[54:57]
	v_mfma_f32_16x16x32_bf16 v[50:53], v[158:161], v[166:169], v[50:53]
	v_mfma_f32_16x16x32_bf16 v[38:41], v[150:153], v[174:177], v[38:41]
	v_mfma_f32_16x16x32_bf16 v[34:37], v[158:161], v[174:177], v[34:37]
	v_mfma_f32_16x16x32_bf16 v[22:25], v[150:153], v[182:185], v[22:25]
	v_mfma_f32_16x16x32_bf16 v[18:21], v[158:161], v[182:185], v[18:21]
	v_mfma_f32_16x16x32_bf16 v[6:9], v[150:153], v[240:243], v[6:9]
	v_mfma_f32_16x16x32_bf16 v[2:5], v[158:161], v[240:243], v[2:5]
	s_setprio 0
	s_barrier
	s_cbranch_scc0 .LBB0_2289
	s_and_b64 vcc, exec, s[40:41]
	s_cbranch_vccz .LBB0_2292
	s_barrier

; #define PG8_STAGE(bufoff, gbase, voff) do { _Pragma("unroll") for (int _i = 0; _i < 2; ++_i) \
;         __builtin_amdgcn_global_load_lds((const unsigned*)((const char*)(gbase) + (voff)[_i]), (PG8_LAS unsigned*)(lds + (bufoff) + ldsw + _i * 8192), 16, 0, 0); } while (0)
; #define PG8_LDA(dst, b, h) do { _Pragma("unroll") for (int m = 0; m < 4; ++m) _Pragma("unroll") for (int k = 0; k < 2; ++k) dst[m][k] = *(const PG8_LAS bf16x8*)(lds + PG8_SA(b, h) + aoff + m * 2048 + k * 1024); } while (0)
; #define PG8_LDB(dst, b, h) do { _Pragma("unroll") for (int n = 0; n < 2; ++n) _Pragma("unroll") for (int k = 0; k < 2; ++k) dst[n][k] = *(const PG8_LAS bf16x8*)(lds + PG8_SB(b, h) + boff + n * 2048 + k * 1024); } while (0)
; #define PG8_MMA(ai, bj, At, Bt) do { __builtin_amdgcn_s_setprio(1); _Pragma("unroll") for (int m = 0; m < 4; ++m) _Pragma("unroll") for (int n = 0; n < 2; ++n) _Pragma("unroll") for (int k = 0; k < 2; ++k) \
;         acc[ai][bj][m][n] = __builtin_amdgcn_mfma_f32_16x16x32_bf16(Bt[n][k], At[m][k], acc[ai][bj][m][n], 0, 0, 0); __builtin_amdgcn_s_setprio(0); } while (0)
; #define PG8_WAIT_V(n) asm volatile("s_waitcnt vmcnt(" #n ")" ::: "memory")
; #define PG8_WAIT_L(n) asm volatile("s_waitcnt lgkmcnt(" #n ")" ::: "memory")
; #define PG8_BAR __builtin_amdgcn_s_barrier()
; template <class Epi, bool ALIGN_EPI, bool ABLK = false>
; __device__ __forceinline__ void gemm_phase(PG8_LAS unsigned char* lds, const Gemm g, const StaticOrder& S, const Epi& E) {
;     ...
;         for (int t = 0; t < nt; t += 2) {
;             const bool last = (t == nt - 2);
;             const char* a1 = cA + (size_t)(t + 1) * kstepA;
;             const char* a2 = last ? nA : cA + (size_t)(t + 2) * kstepA; const char* b2 = last ? nB : cB + (size_t)(t + 2) * kstepB;
;             const char* a3 = a2 + kstepA; const char* b3 = b2 + kstepB;
;             PG8_LDB(B0, 0, 0); PG8_LDB(B1, 0, 1); PG8_SCHED; PG8_LDA(At, 0, 0); PG8_STAGE(PG8_SA(1, 1), a1 + hstepA, voffA);
;             PG8_WAIT_V(8); PG8_WAIT_L(0); PG8_BAR; PG8_MMA(0, 0, At, B0); PG8_MMA(0, 1, At, B1); PG8_BAR; PG8_SCHED;
;             PG8_LDA(At, 0, 1); PG8_STAGE(PG8_SB(0, 0), b2, voffB); PG8_STAGE(PG8_SB(0, 1), b2 + hstepB, voffB); PG8_STAGE(PG8_SA(0, 0), a2, voffA);
;             PG8_WAIT_V(8); PG8_WAIT_L(0); PG8_BAR; PG8_MMA(1, 0, At, B0); PG8_MMA(1, 1, At, B1); PG8_BAR; PG8_SCHED;
.LBB0_2495:
	ds_read_b128 v[132:135], v251
	ds_read_b128 v[178:181], v251 offset:1024
	ds_read_b128 v[182:185], v251 offset:2048
	ds_read_b128 v[186:189], v251 offset:3072
	ds_read_b128 v[190:193], v251 offset:16384
	ds_read_b128 v[194:197], v251 offset:17408
	ds_read_b128 v[198:201], v251 offset:18432
	ds_read_b128 v[202:205], v251 offset:19456
	s_add_u32 s60, s24, s58
	s_addc_u32 s61, s25, s59
	s_sub_u32 s98, s60, 0x10000
	s_subb_u32 s99, s61, 0
	s_cmp_eq_u32 s83, 12
	s_cselect_b32 s101, s53, s61
	s_cselect_b32 s100, s79, s60
	s_cselect_b32 s61, s51, s82
	s_cselect_b32 s60, s80, s81
	s_add_i32 m0, s66, 0xc000
	ds_read_b128 v[206:209], v176
	ds_read_b128 v[210:213], v176 offset:1024
	ds_read_b128 v[214:217], v176 offset:2048
	ds_read_b128 v[218:221], v176 offset:3072
	ds_read_b128 v[222:225], v176 offset:4096
	ds_read_b128 v[226:229], v176 offset:5120
	ds_read_b128 v[230:233], v176 offset:6144
	ds_read_b128 v[234:237], v176 offset:7168
	global_load_lds_dwordx4 v249, s[98:99]
	s_add_i32 m0, s66, 0xe000
	s_nop 0
	global_load_lds_dwordx4 v250, s[98:99]
	s_waitcnt vmcnt(8)
	s_waitcnt lgkmcnt(0)
	s_barrier
	s_setprio 1
	v_mfma_f32_16x16x32_bf16 v[126:129], v[132:135], v[206:209], v[126:129]
	v_mfma_f32_16x16x32_bf16 v[122:125], v[182:185], v[206:209], v[122:125]
	v_mfma_f32_16x16x32_bf16 v[118:121], v[132:135], v[214:217], v[118:121]
	v_mfma_f32_16x16x32_bf16 v[114:117], v[182:185], v[214:217], v[114:117]
	v_mfma_f32_16x16x32_bf16 v[110:113], v[132:135], v[222:225], v[110:113]
	v_mfma_f32_16x16x32_bf16 v[106:109], v[182:185], v[222:225], v[106:109]
	v_mfma_f32_16x16x32_bf16 v[102:105], v[132:135], v[230:233], v[102:105]
	v_mfma_f32_16x16x32_bf16 v[98:101], v[182:185], v[230:233], v[98:101]
	v_mfma_f32_16x16x32_bf16 v[126:129], v[178:181], v[210:213], v[126:129]
	v_mfma_f32_16x16x32_bf16 v[122:125], v[186:189], v[210:213], v[122:125]
	v_mfma_f32_16x16x32_bf16 v[118:121], v[178:181], v[218:221], v[118:121]
	v_mfma_f32_16x16x32_bf16 v[114:117], v[186:189], v[218:221], v[114:117]
	v_mfma_f32_16x16x32_bf16 v[110:113], v[178:181], v[226:229], v[110:113]
	v_mfma_f32_16x16x32_bf16 v[106:109], v[186:189], v[226:229], v[106:109]
	v_mfma_f32_16x16x32_bf16 v[102:105], v[178:181], v[234:237], v[102:105]
	v_mfma_f32_16x16x32_bf16 v[98:101], v[186:189], v[234:237], v[98:101]
	s_setprio 0
	s_setprio 1
	v_mfma_f32_16x16x32_bf16 v[94:97], v[190:193], v[206:209], v[94:97]
	s_add_i32 s86, s75, s9
	v_mfma_f32_16x16x32_bf16 v[90:93], v[198:201], v[206:209], v[90:93]
	s_mov_b32 m0, s86
	v_mfma_f32_16x16x32_bf16 v[86:89], v[190:193], v[214:217], v[86:89]
	v_mfma_f32_16x16x32_bf16 v[82:85], v[198:201], v[214:217], v[82:85]
	v_mfma_f32_16x16x32_bf16 v[78:81], v[190:193], v[222:225], v[78:81]
	v_mfma_f32_16x16x32_bf16 v[74:77], v[198:201], v[222:225], v[74:77]
	v_mfma_f32_16x16x32_bf16 v[70:73], v[190:193], v[230:233], v[70:73]
	v_mfma_f32_16x16x32_bf16 v[66:69], v[198:201], v[230:233], v[66:69]
	v_mfma_f32_16x16x32_bf16 v[94:97], v[194:197], v[210:213], v[94:97]
	v_mfma_f32_16x16x32_bf16 v[90:93], v[202:205], v[210:213], v[90:93]
	v_mfma_f32_16x16x32_bf16 v[86:89], v[194:197], v[218:221], v[86:89]
	v_mfma_f32_16x16x32_bf16 v[82:85], v[202:205], v[218:221], v[82:85]
	v_mfma_f32_16x16x32_bf16 v[78:81], v[194:197], v[226:229], v[78:81]
	v_mfma_f32_16x16x32_bf16 v[74:77], v[202:205], v[226:229], v[74:77]
	v_mfma_f32_16x16x32_bf16 v[70:73], v[194:197], v[234:237], v[70:73]
	v_mfma_f32_16x16x32_bf16 v[66:69], v[202:205], v[234:237], v[66:69]
	s_setprio 0
	s_barrier
	ds_read_b128 v[206:209], v176 offset:16384
	ds_read_b128 v[210:213], v176 offset:17408
	ds_read_b128 v[214:217], v176 offset:18432
	ds_read_b128 v[218:221], v176 offset:19456
	ds_read_b128 v[222:225], v176 offset:20480
	ds_read_b128 v[226:229], v176 offset:21504
	ds_read_b128 v[230:233], v176 offset:22528
	ds_read_b128 v[234:237], v176 offset:23552
	global_load_lds_dwordx4 v140, s[60:61]
	s_add_i32 m0, s86, 0x2000
	s_add_u32 s86, s60, 0x40000
	s_addc_u32 s87, s61, 0
	s_add_i32 s88, s76, s9
	global_load_lds_dwordx4 v142, s[60:61]
	s_mov_b32 m0, s88
	s_nop 0
	global_load_lds_dwordx4 v140, s[86:87]
	s_add_i32 m0, s88, 0x2000
	s_nop 0
	global_load_lds_dwordx4 v142, s[86:87]
	s_mov_b32 m0, s66
	s_nop 0
	global_load_lds_dwordx4 v138, s[100:101]
	s_mov_b32 m0, s67
	s_nop 0
	global_load_lds_dwordx4 v244, s[100:101]
	s_waitcnt vmcnt(8)
	s_waitcnt lgkmcnt(0)
	s_barrier
	s_setprio 1
	v_mfma_f32_16x16x32_bf16 v[62:65], v[132:135], v[206:209], v[62:65]
	v_mfma_f32_16x16x32_bf16 v[58:61], v[182:185], v[206:209], v[58:61]
	v_mfma_f32_16x16x32_bf16 v[54:57], v[132:135], v[214:217], v[54:57]
	v_mfma_f32_16x16x32_bf16 v[50:53], v[182:185], v[214:217], v[50:53]
	v_mfma_f32_16x16x32_bf16 v[46:49], v[132:135], v[222:225], v[46:49]
	v_mfma_f32_16x16x32_bf16 v[42:45], v[182:185], v[222:225], v[42:45]
	v_mfma_f32_16x16x32_bf16 v[38:41], v[132:135], v[230:233], v[38:41]
	v_mfma_f32_16x16x32_bf16 v[34:37], v[182:185], v[230:233], v[34:37]
	v_mfma_f32_16x16x32_bf16 v[62:65], v[178:181], v[210:213], v[62:65]
	v_mfma_f32_16x16x32_bf16 v[58:61], v[186:189], v[210:213], v[58:61]
	v_mfma_f32_16x16x32_bf16 v[54:57], v[178:181], v[218:221], v[54:57]
	v_mfma_f32_16x16x32_bf16 v[50:53], v[186:189], v[218:221], v[50:53]
	v_mfma_f32_16x16x32_bf16 v[46:49], v[178:181], v[226:229], v[46:49]
	v_mfma_f32_16x16x32_bf16 v[42:45], v[186:189], v[226:229], v[42:45]
	v_mfma_f32_16x16x32_bf16 v[38:41], v[178:181], v[234:237], v[38:41]
	v_mfma_f32_16x16x32_bf16 v[34:37], v[186:189], v[234:237], v[34:37]
	s_setprio 0
	s_setprio 1
	v_mfma_f32_16x16x32_bf16 v[30:33], v[190:193], v[206:209], v[30:33]
	s_add_i32 s84, 0, 0x18000
	v_mfma_f32_16x16x32_bf16 v[26:29], v[198:201], v[206:209], v[26:29]
	s_add_i32 s85, 0, 0x1c000
	v_mfma_f32_16x16x32_bf16 v[22:25], v[190:193], v[214:217], v[22:25]
	v_mfma_f32_16x16x32_bf16 v[18:21], v[198:201], v[214:217], v[18:21]
	v_mfma_f32_16x16x32_bf16 v[14:17], v[190:193], v[222:225], v[14:17]
	v_mfma_f32_16x16x32_bf16 v[10:13], v[198:201], v[222:225], v[10:13]
	v_mfma_f32_16x16x32_bf16 v[6:9], v[190:193], v[230:233], v[6:9]
	v_mfma_f32_16x16x32_bf16 v[2:5], v[198:201], v[230:233], v[2:5]
	v_mfma_f32_16x16x32_bf16 v[30:33], v[194:197], v[210:213], v[30:33]
	v_mfma_f32_16x16x32_bf16 v[26:29], v[202:205], v[210:213], v[26:29]
	v_mfma_f32_16x16x32_bf16 v[22:25], v[194:197], v[218:221], v[22:25]
	v_mfma_f32_16x16x32_bf16 v[18:21], v[202:205], v[218:221], v[18:21]
	v_mfma_f32_16x16x32_bf16 v[14:17], v[194:197], v[226:229], v[14:17]
	v_mfma_f32_16x16x32_bf16 v[10:13], v[202:205], v[226:229], v[10:13]
	v_mfma_f32_16x16x32_bf16 v[6:9], v[194:197], v[234:237], v[6:9]
	v_mfma_f32_16x16x32_bf16 v[2:5], v[202:205], v[234:237], v[2:5]
	s_setprio 0
	s_barrier
; #define PG8_STAGE(bufoff, gbase, voff) do { _Pragma("unroll") for (int _i = 0; _i < 2; ++_i) \
;         __builtin_amdgcn_global_load_lds((const unsigned*)((const char*)(gbase) + (voff)[_i]), (PG8_LAS unsigned*)(lds + (bufoff) + ldsw + _i * 8192), 16, 0, 0); } while (0)
; #define PG8_LDA(dst, b, h) do { _Pragma("unroll") for (int m = 0; m < 4; ++m) _Pragma("unroll") for (int k = 0; k < 2; ++k) dst[m][k] = *(const PG8_LAS bf16x8*)(lds + PG8_SA(b, h) + aoff + m * 2048 + k * 1024); } while (0)
; #define PG8_LDB(dst, b, h) do { _Pragma("unroll") for (int n = 0; n < 2; ++n) _Pragma("unroll") for (int k = 0; k < 2; ++k) dst[n][k] = *(const PG8_LAS bf16x8*)(lds + PG8_SB(b, h) + boff + n * 2048 + k * 1024); } while (0)
; #define PG8_MMA(ai, bj, At, Bt) do { __builtin_amdgcn_s_setprio(1); _Pragma("unroll") for (int m = 0; m < 4; ++m) _Pragma("unroll") for (int n = 0; n < 2; ++n) _Pragma("unroll") for (int k = 0; k < 2; ++k) \
;         acc[ai][bj][m][n] = __builtin_amdgcn_mfma_f32_16x16x32_bf16(Bt[n][k], At[m][k], acc[ai][bj][m][n], 0, 0, 0); __builtin_amdgcn_s_setprio(0); } while (0)
; #define PG8_WAIT_V(n) asm volatile("s_waitcnt vmcnt(" #n ")" ::: "memory")
; #define PG8_WAIT_L(n) asm volatile("s_waitcnt lgkmcnt(" #n ")" ::: "memory")
; #define PG8_BAR __builtin_amdgcn_s_barrier()
; #define PG8_SCHED __builtin_amdgcn_sched_barrier(0)
; template <class Epi, bool ALIGN_EPI, bool ABLK = false>
; __device__ __forceinline__ void gemm_phase(PG8_LAS unsigned char* lds, const Gemm g, const StaticOrder& S, const Epi& E) {
;     ...
;             PG8_LDB(B0, 1, 0); PG8_LDB(B1, 1, 1); PG8_SCHED; PG8_LDA(At, 1, 0); PG8_STAGE(PG8_SA(0, 1), a2 + hstepA, voffA);
;             PG8_WAIT_V(8); PG8_WAIT_L(0); PG8_BAR; PG8_MMA(0, 0, At, B0); PG8_MMA(0, 1, At, B1); PG8_BAR; PG8_SCHED;
;             PG8_LDA(At, 1, 1); PG8_STAGE(PG8_SB(1, 0), b3, voffB); PG8_STAGE(PG8_SB(1, 1), b3 + hstepB, voffB); PG8_STAGE(PG8_SA(1, 0), a3, voffA);
;             PG8_WAIT_V(8); PG8_WAIT_L(0); PG8_BAR; PG8_MMA(1, 0, At, B0); PG8_MMA(1, 1, At, B1); PG8_BAR; PG8_SCHED;
;         }
;         if constexpr (ALIGN_EPI) { if (wr == 0) PG8_BAR; }
	ds_read_b128 v[132:135], v251 offset:32768
	ds_read_b128 v[178:181], v251 offset:33792
	ds_read_b128 v[182:185], v251 offset:34816
	ds_read_b128 v[186:189], v251 offset:35840
	ds_read_b128 v[190:193], v251 offset:49152
	ds_read_b128 v[194:197], v251 offset:50176
	ds_read_b128 v[198:201], v251 offset:51200
	ds_read_b128 v[202:205], v251 offset:52224
	s_mov_b32 m0, s68
	ds_read_b128 v[206:209], v176 offset:32768
	ds_read_b128 v[210:213], v176 offset:33792
	ds_read_b128 v[214:217], v176 offset:34816
	ds_read_b128 v[218:221], v176 offset:35840
	ds_read_b128 v[222:225], v176 offset:36864
	ds_read_b128 v[226:229], v176 offset:37888
	ds_read_b128 v[230:233], v176 offset:38912
	ds_read_b128 v[234:237], v176 offset:39936
	global_load_lds_dwordx4 v245, s[100:101]
	s_mov_b32 m0, s69
	s_nop 0
	global_load_lds_dwordx4 v246, s[100:101]
	s_waitcnt vmcnt(8)
	s_waitcnt lgkmcnt(0)
	s_barrier
	s_setprio 1
	v_mfma_f32_16x16x32_bf16 v[126:129], v[132:135], v[206:209], v[126:129]
	v_mfma_f32_16x16x32_bf16 v[122:125], v[182:185], v[206:209], v[122:125]
	v_mfma_f32_16x16x32_bf16 v[118:121], v[132:135], v[214:217], v[118:121]
	v_mfma_f32_16x16x32_bf16 v[114:117], v[182:185], v[214:217], v[114:117]
	v_mfma_f32_16x16x32_bf16 v[110:113], v[132:135], v[222:225], v[110:113]
	v_mfma_f32_16x16x32_bf16 v[106:109], v[182:185], v[222:225], v[106:109]
	v_mfma_f32_16x16x32_bf16 v[102:105], v[132:135], v[230:233], v[102:105]
	v_mfma_f32_16x16x32_bf16 v[98:101], v[182:185], v[230:233], v[98:101]
	v_mfma_f32_16x16x32_bf16 v[126:129], v[178:181], v[210:213], v[126:129]
	v_mfma_f32_16x16x32_bf16 v[122:125], v[186:189], v[210:213], v[122:125]
	v_mfma_f32_16x16x32_bf16 v[118:121], v[178:181], v[218:221], v[118:121]
	v_mfma_f32_16x16x32_bf16 v[114:117], v[186:189], v[218:221], v[114:117]
	v_mfma_f32_16x16x32_bf16 v[110:113], v[178:181], v[226:229], v[110:113]
	v_mfma_f32_16x16x32_bf16 v[106:109], v[186:189], v[226:229], v[106:109]
	v_mfma_f32_16x16x32_bf16 v[102:105], v[178:181], v[234:237], v[102:105]
	v_mfma_f32_16x16x32_bf16 v[98:101], v[186:189], v[234:237], v[98:101]
	s_setprio 0
	s_setprio 1
	v_mfma_f32_16x16x32_bf16 v[94:97], v[190:193], v[206:209], v[94:97]
	s_add_i32 s84, s84, s9
	v_mfma_f32_16x16x32_bf16 v[90:93], v[198:201], v[206:209], v[90:93]
	s_add_u32 s60, s60, s28
	v_mfma_f32_16x16x32_bf16 v[86:89], v[190:193], v[214:217], v[86:89]
	s_addc_u32 s61, s61, s29
	v_mfma_f32_16x16x32_bf16 v[82:85], v[198:201], v[214:217], v[82:85]
	s_mov_b32 m0, s84
	v_mfma_f32_16x16x32_bf16 v[78:81], v[190:193], v[222:225], v[78:81]
	v_mfma_f32_16x16x32_bf16 v[74:77], v[198:201], v[222:225], v[74:77]
	v_mfma_f32_16x16x32_bf16 v[70:73], v[190:193], v[230:233], v[70:73]
	v_mfma_f32_16x16x32_bf16 v[66:69], v[198:201], v[230:233], v[66:69]
	v_mfma_f32_16x16x32_bf16 v[94:97], v[194:197], v[210:213], v[94:97]
	v_mfma_f32_16x16x32_bf16 v[90:93], v[202:205], v[210:213], v[90:93]
	v_mfma_f32_16x16x32_bf16 v[86:89], v[194:197], v[218:221], v[86:89]
	v_mfma_f32_16x16x32_bf16 v[82:85], v[202:205], v[218:221], v[82:85]
	v_mfma_f32_16x16x32_bf16 v[78:81], v[194:197], v[226:229], v[78:81]
	v_mfma_f32_16x16x32_bf16 v[74:77], v[202:205], v[226:229], v[74:77]
	v_mfma_f32_16x16x32_bf16 v[70:73], v[194:197], v[234:237], v[70:73]
	v_mfma_f32_16x16x32_bf16 v[66:69], v[202:205], v[234:237], v[66:69]
	s_setprio 0
	s_barrier
	ds_read_b128 v[206:209], v176 offset:49152
	ds_read_b128 v[210:213], v176 offset:50176
	ds_read_b128 v[214:217], v176 offset:51200
	ds_read_b128 v[218:221], v176 offset:52224
	ds_read_b128 v[222:225], v176 offset:53248
	ds_read_b128 v[226:229], v176 offset:54272
	ds_read_b128 v[230:233], v176 offset:55296
	ds_read_b128 v[234:237], v176 offset:56320
	global_load_lds_dwordx4 v140, s[60:61]
	s_add_i32 m0, s84, 0x2000
	s_add_i32 s84, s85, s9
	global_load_lds_dwordx4 v142, s[60:61]
	s_add_u32 s60, s60, 0x40000
	s_addc_u32 s61, s61, 0
	s_mov_b32 m0, s84
	s_nop 0
	global_load_lds_dwordx4 v140, s[60:61]
	s_add_i32 m0, s84, 0x2000
	s_nop 0
	global_load_lds_dwordx4 v142, s[60:61]
	s_mov_b32 m0, s70
	s_nop 0
	global_load_lds_dwordx4 v247, s[100:101]
	s_mov_b32 m0, s72
	s_nop 0
	global_load_lds_dwordx4 v248, s[100:101]
	s_waitcnt vmcnt(8)
	s_waitcnt lgkmcnt(0)
	s_barrier
	s_setprio 1
	v_mfma_f32_16x16x32_bf16 v[62:65], v[132:135], v[206:209], v[62:65]
	v_mfma_f32_16x16x32_bf16 v[58:61], v[182:185], v[206:209], v[58:61]
	v_mfma_f32_16x16x32_bf16 v[54:57], v[132:135], v[214:217], v[54:57]
	v_mfma_f32_16x16x32_bf16 v[50:53], v[182:185], v[214:217], v[50:53]
	v_mfma_f32_16x16x32_bf16 v[46:49], v[132:135], v[222:225], v[46:49]
	v_mfma_f32_16x16x32_bf16 v[42:45], v[182:185], v[222:225], v[42:45]
	v_mfma_f32_16x16x32_bf16 v[38:41], v[132:135], v[230:233], v[38:41]
	v_mfma_f32_16x16x32_bf16 v[34:37], v[182:185], v[230:233], v[34:37]
	v_mfma_f32_16x16x32_bf16 v[62:65], v[178:181], v[210:213], v[62:65]
	v_mfma_f32_16x16x32_bf16 v[58:61], v[186:189], v[210:213], v[58:61]
	v_mfma_f32_16x16x32_bf16 v[54:57], v[178:181], v[218:221], v[54:57]
	v_mfma_f32_16x16x32_bf16 v[50:53], v[186:189], v[218:221], v[50:53]
	v_mfma_f32_16x16x32_bf16 v[46:49], v[178:181], v[226:229], v[46:49]
	v_mfma_f32_16x16x32_bf16 v[42:45], v[186:189], v[226:229], v[42:45]
	v_mfma_f32_16x16x32_bf16 v[38:41], v[178:181], v[234:237], v[38:41]
	v_mfma_f32_16x16x32_bf16 v[34:37], v[186:189], v[234:237], v[34:37]
	s_setprio 0
	s_setprio 1
	v_mfma_f32_16x16x32_bf16 v[30:33], v[190:193], v[206:209], v[30:33]
	s_add_i32 s83, s83, 2
	v_mfma_f32_16x16x32_bf16 v[26:29], v[198:201], v[206:209], v[26:29]
	s_add_u32 s81, s81, 0x100
	v_mfma_f32_16x16x32_bf16 v[22:25], v[190:193], v[214:217], v[22:25]
	s_addc_u32 s82, s82, 0
	v_mfma_f32_16x16x32_bf16 v[18:21], v[198:201], v[214:217], v[18:21]
	s_add_u32 s58, s58, 0x10000
	v_mfma_f32_16x16x32_bf16 v[14:17], v[190:193], v[222:225], v[14:17]
	s_addc_u32 s59, s59, 0
	v_mfma_f32_16x16x32_bf16 v[10:13], v[198:201], v[222:225], v[10:13]
	s_cmp_gt_u32 s83, 13
	v_mfma_f32_16x16x32_bf16 v[6:9], v[190:193], v[230:233], v[6:9]
	v_mfma_f32_16x16x32_bf16 v[2:5], v[198:201], v[230:233], v[2:5]
	v_mfma_f32_16x16x32_bf16 v[30:33], v[194:197], v[210:213], v[30:33]
	v_mfma_f32_16x16x32_bf16 v[26:29], v[202:205], v[210:213], v[26:29]
	v_mfma_f32_16x16x32_bf16 v[22:25], v[194:197], v[218:221], v[22:25]
	v_mfma_f32_16x16x32_bf16 v[18:21], v[202:205], v[218:221], v[18:21]
	v_mfma_f32_16x16x32_bf16 v[14:17], v[194:197], v[226:229], v[14:17]
	v_mfma_f32_16x16x32_bf16 v[10:13], v[202:205], v[226:229], v[10:13]
	v_mfma_f32_16x16x32_bf16 v[6:9], v[194:197], v[234:237], v[6:9]
	v_mfma_f32_16x16x32_bf16 v[2:5], v[202:205], v[234:237], v[2:5]
	s_setprio 0
	s_barrier
	s_cbranch_scc0 .LBB0_2495
	s_and_b64 vcc, exec, s[36:37]
	s_cbranch_vccz .LBB0_2498
	s_barrier

; #define PG8_STAGE(bufoff, gbase, voff) do { _Pragma("unroll") for (int _i = 0; _i < 2; ++_i) \
;         __builtin_amdgcn_global_load_lds((const unsigned*)((const char*)(gbase) + (voff)[_i]), (PG8_LAS unsigned*)(lds + (bufoff) + ldsw + _i * 8192), 16, 0, 0); } while (0)
; #define PG8_LDA(dst, b, h) do { _Pragma("unroll") for (int m = 0; m < 4; ++m) _Pragma("unroll") for (int k = 0; k < 2; ++k) dst[m][k] = *(const PG8_LAS bf16x8*)(lds + PG8_SA(b, h) + aoff + m * 2048 + k * 1024); } while (0)
; #define PG8_LDB(dst, b, h) do { _Pragma("unroll") for (int n = 0; n < 2; ++n) _Pragma("unroll") for (int k = 0; k < 2; ++k) dst[n][k] = *(const PG8_LAS bf16x8*)(lds + PG8_SB(b, h) + boff + n * 2048 + k * 1024); } while (0)
; #define PG8_MMA(ai, bj, At, Bt) do { __builtin_amdgcn_s_setprio(1); _Pragma("unroll") for (int m = 0; m < 4; ++m) _Pragma("unroll") for (int n = 0; n < 2; ++n) _Pragma("unroll") for (int k = 0; k < 2; ++k) \
;         acc[ai][bj][m][n] = __builtin_amdgcn_mfma_f32_16x16x32_bf16(Bt[n][k], At[m][k], acc[ai][bj][m][n], 0, 0, 0); __builtin_amdgcn_s_setprio(0); } while (0)
; #define PG8_WAIT_V(n) asm volatile("s_waitcnt vmcnt(" #n ")" ::: "memory")
; #define PG8_WAIT_L(n) asm volatile("s_waitcnt lgkmcnt(" #n ")" ::: "memory")
; #define PG8_BAR __builtin_amdgcn_s_barrier()
; #define PG8_SCHED __builtin_amdgcn_sched_barrier(0)
; template <class Epi, bool ALIGN_EPI, bool ABLK = false>
; __device__ __forceinline__ void gemm_phase(PG8_LAS unsigned char* lds, const Gemm g, const StaticOrder& S, const Epi& E) {
;     ...
;             PG8_LDB(B0, 0, 0); PG8_LDB(B1, 0, 1); PG8_SCHED; PG8_LDA(At, 0, 0); PG8_STAGE(PG8_SA(1, 1), a1 + hstepA, voffA);
;             PG8_WAIT_V(8); PG8_WAIT_L(0); PG8_BAR; PG8_MMA(0, 0, At, B0); PG8_MMA(0, 1, At, B1); PG8_BAR; PG8_SCHED;
;             PG8_LDA(At, 0, 1); PG8_STAGE(PG8_SB(0, 0), b2, voffB); PG8_STAGE(PG8_SB(0, 1), b2 + hstepB, voffB); PG8_STAGE(PG8_SA(0, 0), a2, voffA);
;             PG8_WAIT_V(8); PG8_WAIT_L(0); PG8_BAR; PG8_MMA(1, 0, At, B0); PG8_MMA(1, 1, At, B1); PG8_BAR; PG8_SCHED;
.LBB0_2631:
	ds_read_b128 v[130:133], v234
	ds_read_b128 v[134:137], v234 offset:1024
	ds_read_b128 v[138:141], v234 offset:2048
	ds_read_b128 v[142:145], v234 offset:3072
	ds_read_b128 v[146:149], v235
	ds_read_b128 v[150:153], v235 offset:1024
	ds_read_b128 v[154:157], v235 offset:2048
	ds_read_b128 v[158:161], v235 offset:3072
	s_cmp_eq_u32 s57, 40
	s_cselect_b32 s81, s13, s53
	s_cselect_b32 s80, s12, s52
	s_cselect_b32 s55, s49, s56
	s_cselect_b32 s54, s48, s51
	v_lshl_add_u64 v[248:249], s[52:53], 0, v[186:187]
	v_lshl_add_u64 v[250:251], v[248:249], 0, s[44:45]
	s_add_i32 m0, s62, 0xc000
	ds_read_b128 v[162:165], v236
	ds_read_b128 v[166:169], v236 offset:1024
	ds_read_b128 v[170:173], v236 offset:2048
	ds_read_b128 v[174:177], v236 offset:3072
	ds_read_b128 v[178:181], v236 offset:4096
	ds_read_b128 v[182:185], v236 offset:5120
	ds_read_b128 v[240:243], v236 offset:6144
	ds_read_b128 v[244:247], v236 offset:7168
	global_load_lds_dwordx4 v[250:251], off
	v_lshl_add_u64 v[248:249], v[248:249], 0, s[46:47]
	s_add_i32 m0, s62, 0xe000
	s_nop 0
	global_load_lds_dwordx4 v[248:249], off
	s_waitcnt vmcnt(8)
	s_waitcnt lgkmcnt(0)
	s_barrier
	s_setprio 1
	v_mfma_f32_16x16x32_bf16 v[126:129], v[130:133], v[162:165], v[126:129]
	v_mfma_f32_16x16x32_bf16 v[122:125], v[138:141], v[162:165], v[122:125]
	v_mfma_f32_16x16x32_bf16 v[110:113], v[130:133], v[170:173], v[110:113]
	v_mfma_f32_16x16x32_bf16 v[106:109], v[138:141], v[170:173], v[106:109]
	v_mfma_f32_16x16x32_bf16 v[94:97], v[130:133], v[178:181], v[94:97]
	v_mfma_f32_16x16x32_bf16 v[90:93], v[138:141], v[178:181], v[90:93]
	v_mfma_f32_16x16x32_bf16 v[78:81], v[130:133], v[240:243], v[78:81]
	v_mfma_f32_16x16x32_bf16 v[74:77], v[138:141], v[240:243], v[74:77]
	v_mfma_f32_16x16x32_bf16 v[126:129], v[134:137], v[166:169], v[126:129]
	v_mfma_f32_16x16x32_bf16 v[122:125], v[142:145], v[166:169], v[122:125]
	v_mfma_f32_16x16x32_bf16 v[110:113], v[134:137], v[174:177], v[110:113]
	v_mfma_f32_16x16x32_bf16 v[106:109], v[142:145], v[174:177], v[106:109]
	v_mfma_f32_16x16x32_bf16 v[94:97], v[134:137], v[182:185], v[94:97]
	v_mfma_f32_16x16x32_bf16 v[90:93], v[142:145], v[182:185], v[90:93]
	v_mfma_f32_16x16x32_bf16 v[78:81], v[134:137], v[244:247], v[78:81]
	v_mfma_f32_16x16x32_bf16 v[74:77], v[142:145], v[244:247], v[74:77]
	s_setprio 0
	s_setprio 1
	v_mfma_f32_16x16x32_bf16 v[118:121], v[146:149], v[162:165], v[118:121]
	s_add_i32 s79, s74, s61
	v_mfma_f32_16x16x32_bf16 v[114:117], v[154:157], v[162:165], v[114:117]
	s_mov_b32 m0, s79
	v_mfma_f32_16x16x32_bf16 v[102:105], v[146:149], v[170:173], v[102:105]
	v_mfma_f32_16x16x32_bf16 v[98:101], v[154:157], v[170:173], v[98:101]
	v_mfma_f32_16x16x32_bf16 v[86:89], v[146:149], v[178:181], v[86:89]
	v_mfma_f32_16x16x32_bf16 v[82:85], v[154:157], v[178:181], v[82:85]
	v_mfma_f32_16x16x32_bf16 v[70:73], v[146:149], v[240:243], v[70:73]
	v_mfma_f32_16x16x32_bf16 v[66:69], v[154:157], v[240:243], v[66:69]
	v_mfma_f32_16x16x32_bf16 v[118:121], v[150:153], v[166:169], v[118:121]
	v_mfma_f32_16x16x32_bf16 v[114:117], v[158:161], v[166:169], v[114:117]
	v_mfma_f32_16x16x32_bf16 v[102:105], v[150:153], v[174:177], v[102:105]
	v_mfma_f32_16x16x32_bf16 v[98:101], v[158:161], v[174:177], v[98:101]
	v_mfma_f32_16x16x32_bf16 v[86:89], v[150:153], v[182:185], v[86:89]
	v_mfma_f32_16x16x32_bf16 v[82:85], v[158:161], v[182:185], v[82:85]
	v_mfma_f32_16x16x32_bf16 v[70:73], v[150:153], v[244:247], v[70:73]
	v_mfma_f32_16x16x32_bf16 v[66:69], v[158:161], v[244:247], v[66:69]
	s_setprio 0
	s_barrier
	v_lshl_add_u64 v[248:249], s[54:55], 0, v[188:189]
	ds_read_b128 v[162:165], v236 offset:16384
	ds_read_b128 v[166:169], v236 offset:17408
	ds_read_b128 v[170:173], v236 offset:18432
	ds_read_b128 v[174:177], v236 offset:19456
	ds_read_b128 v[178:181], v236 offset:20480
	ds_read_b128 v[182:185], v236 offset:21504
	ds_read_b128 v[240:243], v236 offset:22528
	ds_read_b128 v[244:247], v236 offset:23552
	global_load_lds_dwordx4 v[248:249], off
	s_add_i32 m0, s79, 0x2000
	s_add_u32 s82, s54, 0xb0000
	v_lshl_add_u64 v[250:251], s[54:55], 0, v[190:191]
	s_addc_u32 s83, s55, 0
	s_add_i32 s79, s75, s61
	global_load_lds_dwordx4 v[250:251], off
	v_lshl_add_u64 v[252:253], s[82:83], 0, v[188:189]
	s_mov_b32 m0, s79
	s_nop 0
	global_load_lds_dwordx4 v[252:253], off
	v_lshl_add_u64 v[252:253], s[82:83], 0, v[190:191]
	s_add_i32 m0, s79, 0x2000
	s_nop 0
	global_load_lds_dwordx4 v[252:253], off
	v_lshl_add_u64 v[252:253], s[80:81], 0, v[186:187]
	s_mov_b32 m0, s62
	v_lshl_add_u64 v[208:209], v[252:253], 0, s[22:23]
	global_load_lds_dwordx4 v[252:253], off
	s_mov_b32 m0, s63
	s_nop 0
	global_load_lds_dwordx4 v[208:209], off
	s_waitcnt vmcnt(8)
	s_waitcnt lgkmcnt(0)
	s_barrier
; #define PG8_STAGE(bufoff, gbase, voff) do { _Pragma("unroll") for (int _i = 0; _i < 2; ++_i) \
;         __builtin_amdgcn_global_load_lds((const unsigned*)((const char*)(gbase) + (voff)[_i]), (PG8_LAS unsigned*)(lds + (bufoff) + ldsw + _i * 8192), 16, 0, 0); } while (0)
; #define PG8_LDA(dst, b, h) do { _Pragma("unroll") for (int m = 0; m < 4; ++m) _Pragma("unroll") for (int k = 0; k < 2; ++k) dst[m][k] = *(const PG8_LAS bf16x8*)(lds + PG8_SA(b, h) + aoff + m * 2048 + k * 1024); } while (0)
; #define PG8_LDB(dst, b, h) do { _Pragma("unroll") for (int n = 0; n < 2; ++n) _Pragma("unroll") for (int k = 0; k < 2; ++k) dst[n][k] = *(const PG8_LAS bf16x8*)(lds + PG8_SB(b, h) + boff + n * 2048 + k * 1024); } while (0)
; #define PG8_MMA(ai, bj, At, Bt) do { __builtin_amdgcn_s_setprio(1); _Pragma("unroll") for (int m = 0; m < 4; ++m) _Pragma("unroll") for (int n = 0; n < 2; ++n) _Pragma("unroll") for (int k = 0; k < 2; ++k) \
;         acc[ai][bj][m][n] = __builtin_amdgcn_mfma_f32_16x16x32_bf16(Bt[n][k], At[m][k], acc[ai][bj][m][n], 0, 0, 0); __builtin_amdgcn_s_setprio(0); } while (0)
; #define PG8_WAIT_V(n) asm volatile("s_waitcnt vmcnt(" #n ")" ::: "memory")
; #define PG8_WAIT_L(n) asm volatile("s_waitcnt lgkmcnt(" #n ")" ::: "memory")
; #define PG8_BAR __builtin_amdgcn_s_barrier()
; #define PG8_SCHED __builtin_amdgcn_sched_barrier(0)
; template <class Epi, bool ALIGN_EPI, bool ABLK = false>
; __device__ __forceinline__ void gemm_phase(PG8_LAS unsigned char* lds, const Gemm g, const StaticOrder& S, const Epi& E) {
;     ...
;             PG8_WAIT_V(8); PG8_WAIT_L(0); PG8_BAR; PG8_MMA(1, 0, At, B0); PG8_MMA(1, 1, At, B1); PG8_BAR; PG8_SCHED;
;             PG8_LDB(B0, 1, 0); PG8_LDB(B1, 1, 1); PG8_SCHED; PG8_LDA(At, 1, 0); PG8_STAGE(PG8_SA(0, 1), a2 + hstepA, voffA);
;             PG8_WAIT_V(8); PG8_WAIT_L(0); PG8_BAR; PG8_MMA(0, 0, At, B0); PG8_MMA(0, 1, At, B1); PG8_BAR; PG8_SCHED;
;             PG8_LDA(At, 1, 1); PG8_STAGE(PG8_SB(1, 0), b3, voffB); PG8_STAGE(PG8_SB(1, 1), b3 + hstepB, voffB); PG8_STAGE(PG8_SA(1, 0), a3, voffA);
	s_setprio 1
	v_mfma_f32_16x16x32_bf16 v[62:65], v[130:133], v[162:165], v[62:65]
	v_mfma_f32_16x16x32_bf16 v[58:61], v[138:141], v[162:165], v[58:61]
	v_mfma_f32_16x16x32_bf16 v[46:49], v[130:133], v[170:173], v[46:49]
	v_mfma_f32_16x16x32_bf16 v[42:45], v[138:141], v[170:173], v[42:45]
	v_mfma_f32_16x16x32_bf16 v[30:33], v[130:133], v[178:181], v[30:33]
	v_mfma_f32_16x16x32_bf16 v[26:29], v[138:141], v[178:181], v[26:29]
	v_mfma_f32_16x16x32_bf16 v[14:17], v[130:133], v[240:243], v[14:17]
	v_mfma_f32_16x16x32_bf16 v[10:13], v[138:141], v[240:243], v[10:13]
	v_mfma_f32_16x16x32_bf16 v[62:65], v[134:137], v[166:169], v[62:65]
	v_mfma_f32_16x16x32_bf16 v[58:61], v[142:145], v[166:169], v[58:61]
	v_mfma_f32_16x16x32_bf16 v[46:49], v[134:137], v[174:177], v[46:49]
	v_mfma_f32_16x16x32_bf16 v[42:45], v[142:145], v[174:177], v[42:45]
	v_mfma_f32_16x16x32_bf16 v[30:33], v[134:137], v[182:185], v[30:33]
	v_mfma_f32_16x16x32_bf16 v[26:29], v[142:145], v[182:185], v[26:29]
	v_mfma_f32_16x16x32_bf16 v[14:17], v[134:137], v[244:247], v[14:17]
	v_mfma_f32_16x16x32_bf16 v[10:13], v[142:145], v[244:247], v[10:13]
	s_setprio 0
	s_setprio 1
	v_mfma_f32_16x16x32_bf16 v[54:57], v[146:149], v[162:165], v[54:57]
	s_add_i32 s79, 0, 0x18000
	v_mfma_f32_16x16x32_bf16 v[50:53], v[154:157], v[162:165], v[50:53]
	s_add_i32 s80, 0, 0x1c000
	v_mfma_f32_16x16x32_bf16 v[38:41], v[146:149], v[170:173], v[38:41]
	v_mfma_f32_16x16x32_bf16 v[34:37], v[154:157], v[170:173], v[34:37]
	v_mfma_f32_16x16x32_bf16 v[22:25], v[146:149], v[178:181], v[22:25]
	v_mfma_f32_16x16x32_bf16 v[18:21], v[154:157], v[178:181], v[18:21]
	v_mfma_f32_16x16x32_bf16 v[6:9], v[146:149], v[240:243], v[6:9]
	v_mfma_f32_16x16x32_bf16 v[2:5], v[154:157], v[240:243], v[2:5]
	v_mfma_f32_16x16x32_bf16 v[54:57], v[150:153], v[166:169], v[54:57]
	v_mfma_f32_16x16x32_bf16 v[50:53], v[158:161], v[166:169], v[50:53]
	v_mfma_f32_16x16x32_bf16 v[38:41], v[150:153], v[174:177], v[38:41]
	v_mfma_f32_16x16x32_bf16 v[34:37], v[158:161], v[174:177], v[34:37]
	v_mfma_f32_16x16x32_bf16 v[22:25], v[150:153], v[182:185], v[22:25]
	v_mfma_f32_16x16x32_bf16 v[18:21], v[158:161], v[182:185], v[18:21]
	v_mfma_f32_16x16x32_bf16 v[6:9], v[150:153], v[244:247], v[6:9]
	v_mfma_f32_16x16x32_bf16 v[2:5], v[158:161], v[244:247], v[2:5]
	s_setprio 0
	s_barrier
	v_add_u32_e32 v142, s79, v215
	v_add_u32_e32 v158, s80, v215
	ds_read_b128 v[130:133], v142
	ds_read_b128 v[134:137], v142 offset:1024
	ds_read_b128 v[138:141], v142 offset:2048
	ds_read_b128 v[142:145], v142 offset:3072
	ds_read_b128 v[146:149], v158
	ds_read_b128 v[150:153], v158 offset:1024
	ds_read_b128 v[154:157], v158 offset:2048
	ds_read_b128 v[158:161], v158 offset:3072
	s_mov_b32 m0, s64
	v_lshl_add_u64 v[208:209], v[252:253], 0, s[24:25]
	ds_read_b128 v[162:165], v236 offset:32768
	ds_read_b128 v[166:169], v236 offset:33792
	ds_read_b128 v[170:173], v236 offset:34816
	ds_read_b128 v[174:177], v236 offset:35840
	ds_read_b128 v[178:181], v236 offset:36864
	ds_read_b128 v[182:185], v236 offset:37888
	ds_read_b128 v[240:243], v236 offset:38912
	ds_read_b128 v[244:247], v236 offset:39936
	global_load_lds_dwordx4 v[208:209], off
	v_lshl_add_u64 v[208:209], v[252:253], 0, s[26:27]
	s_mov_b32 m0, s65
	s_nop 0
	global_load_lds_dwordx4 v[208:209], off
	s_waitcnt vmcnt(8)
	s_waitcnt lgkmcnt(0)
	s_barrier
	s_setprio 1
	v_mfma_f32_16x16x32_bf16 v[126:129], v[130:133], v[162:165], v[126:129]
	v_mfma_f32_16x16x32_bf16 v[122:125], v[138:141], v[162:165], v[122:125]
	v_mfma_f32_16x16x32_bf16 v[110:113], v[130:133], v[170:173], v[110:113]
	v_mfma_f32_16x16x32_bf16 v[106:109], v[138:141], v[170:173], v[106:109]
	v_mfma_f32_16x16x32_bf16 v[94:97], v[130:133], v[178:181], v[94:97]
	v_mfma_f32_16x16x32_bf16 v[90:93], v[138:141], v[178:181], v[90:93]
	v_mfma_f32_16x16x32_bf16 v[78:81], v[130:133], v[240:243], v[78:81]
	v_mfma_f32_16x16x32_bf16 v[74:77], v[138:141], v[240:243], v[74:77]
	v_mfma_f32_16x16x32_bf16 v[126:129], v[134:137], v[166:169], v[126:129]
	v_mfma_f32_16x16x32_bf16 v[122:125], v[142:145], v[166:169], v[122:125]
	v_mfma_f32_16x16x32_bf16 v[110:113], v[134:137], v[174:177], v[110:113]
	v_mfma_f32_16x16x32_bf16 v[106:109], v[142:145], v[174:177], v[106:109]
	v_mfma_f32_16x16x32_bf16 v[94:97], v[134:137], v[182:185], v[94:97]
	v_mfma_f32_16x16x32_bf16 v[90:93], v[142:145], v[182:185], v[90:93]
	v_mfma_f32_16x16x32_bf16 v[78:81], v[134:137], v[244:247], v[78:81]
	v_mfma_f32_16x16x32_bf16 v[74:77], v[142:145], v[244:247], v[74:77]
	s_setprio 0
	s_setprio 1
	v_mfma_f32_16x16x32_bf16 v[118:121], v[146:149], v[162:165], v[118:121]
	s_add_i32 s79, s79, s61
	v_mfma_f32_16x16x32_bf16 v[114:117], v[154:157], v[162:165], v[114:117]
	s_mov_b32 m0, s79
	v_mfma_f32_16x16x32_bf16 v[102:105], v[146:149], v[170:173], v[102:105]
	v_mfma_f32_16x16x32_bf16 v[98:101], v[154:157], v[170:173], v[98:101]
	v_mfma_f32_16x16x32_bf16 v[86:89], v[146:149], v[178:181], v[86:89]
	v_mfma_f32_16x16x32_bf16 v[82:85], v[154:157], v[178:181], v[82:85]
	v_mfma_f32_16x16x32_bf16 v[70:73], v[146:149], v[240:243], v[70:73]
	v_mfma_f32_16x16x32_bf16 v[66:69], v[154:157], v[240:243], v[66:69]
	v_mfma_f32_16x16x32_bf16 v[118:121], v[150:153], v[166:169], v[118:121]
	v_mfma_f32_16x16x32_bf16 v[114:117], v[158:161], v[166:169], v[114:117]
	v_mfma_f32_16x16x32_bf16 v[102:105], v[150:153], v[174:177], v[102:105]
	v_mfma_f32_16x16x32_bf16 v[98:101], v[158:161], v[174:177], v[98:101]
	v_mfma_f32_16x16x32_bf16 v[86:89], v[150:153], v[182:185], v[86:89]
	v_mfma_f32_16x16x32_bf16 v[82:85], v[158:161], v[182:185], v[82:85]
	v_mfma_f32_16x16x32_bf16 v[70:73], v[150:153], v[244:247], v[70:73]
	v_mfma_f32_16x16x32_bf16 v[66:69], v[158:161], v[244:247], v[66:69]
	s_setprio 0
	s_barrier
; #define PG8_STAGE(bufoff, gbase, voff) do { _Pragma("unroll") for (int _i = 0; _i < 2; ++_i) \
;         __builtin_amdgcn_global_load_lds((const unsigned*)((const char*)(gbase) + (voff)[_i]), (PG8_LAS unsigned*)(lds + (bufoff) + ldsw + _i * 8192), 16, 0, 0); } while (0)
; #define PG8_LDA(dst, b, h) do { _Pragma("unroll") for (int m = 0; m < 4; ++m) _Pragma("unroll") for (int k = 0; k < 2; ++k) dst[m][k] = *(const PG8_LAS bf16x8*)(lds + PG8_SA(b, h) + aoff + m * 2048 + k * 1024); } while (0)
; #define PG8_MMA(ai, bj, At, Bt) do { __builtin_amdgcn_s_setprio(1); _Pragma("unroll") for (int m = 0; m < 4; ++m) _Pragma("unroll") for (int n = 0; n < 2; ++n) _Pragma("unroll") for (int k = 0; k < 2; ++k) \
;         acc[ai][bj][m][n] = __builtin_amdgcn_mfma_f32_16x16x32_bf16(Bt[n][k], At[m][k], acc[ai][bj][m][n], 0, 0, 0); __builtin_amdgcn_s_setprio(0); } while (0)
; #define PG8_WAIT_V(n) asm volatile("s_waitcnt vmcnt(" #n ")" ::: "memory")
; #define PG8_WAIT_L(n) asm volatile("s_waitcnt lgkmcnt(" #n ")" ::: "memory")
; #define PG8_BAR __builtin_amdgcn_s_barrier()
; #define PG8_SCHED __builtin_amdgcn_sched_barrier(0)
; template <class Epi, bool ALIGN_EPI, bool ABLK = false>
; __device__ __forceinline__ void gemm_phase(PG8_LAS unsigned char* lds, const Gemm g, const StaticOrder& S, const Epi& E) {
;     ...
;             PG8_LDA(At, 1, 1); PG8_STAGE(PG8_SB(1, 0), b3, voffB); PG8_STAGE(PG8_SB(1, 1), b3 + hstepB, voffB); PG8_STAGE(PG8_SA(1, 0), a3, voffA);
;             PG8_WAIT_V(8); PG8_WAIT_L(0); PG8_BAR; PG8_MMA(1, 0, At, B0); PG8_MMA(1, 1, At, B1); PG8_BAR; PG8_SCHED;
;         }
;         if constexpr (ALIGN_EPI) { if (wr == 0) PG8_BAR; }
	v_lshl_add_u64 v[208:209], v[248:249], 0, s[34:35]
	ds_read_b128 v[162:165], v236 offset:49152
	ds_read_b128 v[166:169], v236 offset:50176
	ds_read_b128 v[170:173], v236 offset:51200
	ds_read_b128 v[174:177], v236 offset:52224
	ds_read_b128 v[178:181], v236 offset:53248
	ds_read_b128 v[182:185], v236 offset:54272
	ds_read_b128 v[240:243], v236 offset:55296
	ds_read_b128 v[244:247], v236 offset:56320
	global_load_lds_dwordx4 v[208:209], off
	s_add_i32 m0, s79, 0x2000
	s_add_u32 s54, s54, 0xb0080
	v_lshl_add_u64 v[208:209], v[250:251], 0, s[34:35]
	s_addc_u32 s55, s55, 0
	s_add_i32 s79, s80, s61
	global_load_lds_dwordx4 v[208:209], off
	v_lshl_add_u64 v[208:209], s[54:55], 0, v[188:189]
	s_mov_b32 m0, s79
	s_nop 0
	global_load_lds_dwordx4 v[208:209], off
	v_lshl_add_u64 v[208:209], s[54:55], 0, v[190:191]
	s_add_i32 m0, s79, 0x2000
	s_nop 0
	global_load_lds_dwordx4 v[208:209], off
	v_lshl_add_u64 v[208:209], v[252:253], 0, s[36:37]
	s_mov_b32 m0, s69
	s_nop 0
	global_load_lds_dwordx4 v[208:209], off
	v_lshl_add_u64 v[208:209], v[252:253], 0, s[38:39]
	s_mov_b32 m0, s70
	s_nop 0
	global_load_lds_dwordx4 v[208:209], off
	s_waitcnt vmcnt(8)
	s_waitcnt lgkmcnt(0)
	s_barrier
	s_setprio 1
	v_mfma_f32_16x16x32_bf16 v[62:65], v[130:133], v[162:165], v[62:65]
	v_mfma_f32_16x16x32_bf16 v[58:61], v[138:141], v[162:165], v[58:61]
	v_mfma_f32_16x16x32_bf16 v[46:49], v[130:133], v[170:173], v[46:49]
	v_mfma_f32_16x16x32_bf16 v[42:45], v[138:141], v[170:173], v[42:45]
	v_mfma_f32_16x16x32_bf16 v[30:33], v[130:133], v[178:181], v[30:33]
	v_mfma_f32_16x16x32_bf16 v[26:29], v[138:141], v[178:181], v[26:29]
	v_mfma_f32_16x16x32_bf16 v[14:17], v[130:133], v[240:243], v[14:17]
	v_mfma_f32_16x16x32_bf16 v[10:13], v[138:141], v[240:243], v[10:13]
	v_mfma_f32_16x16x32_bf16 v[62:65], v[134:137], v[166:169], v[62:65]
	v_mfma_f32_16x16x32_bf16 v[58:61], v[142:145], v[166:169], v[58:61]
	v_mfma_f32_16x16x32_bf16 v[46:49], v[134:137], v[174:177], v[46:49]
	v_mfma_f32_16x16x32_bf16 v[42:45], v[142:145], v[174:177], v[42:45]
	v_mfma_f32_16x16x32_bf16 v[30:33], v[134:137], v[182:185], v[30:33]
	v_mfma_f32_16x16x32_bf16 v[26:29], v[142:145], v[182:185], v[26:29]
	v_mfma_f32_16x16x32_bf16 v[14:17], v[134:137], v[244:247], v[14:17]
	v_mfma_f32_16x16x32_bf16 v[10:13], v[142:145], v[244:247], v[10:13]
	s_setprio 0
	s_setprio 1
	v_mfma_f32_16x16x32_bf16 v[54:57], v[146:149], v[162:165], v[54:57]
	s_add_i32 s57, s57, 2
	v_mfma_f32_16x16x32_bf16 v[50:53], v[154:157], v[162:165], v[50:53]
	s_add_u32 s51, s51, 0x100
	v_mfma_f32_16x16x32_bf16 v[38:41], v[146:149], v[170:173], v[38:41]
	s_addc_u32 s56, s56, 0
	v_mfma_f32_16x16x32_bf16 v[34:37], v[154:157], v[170:173], v[34:37]
	s_add_u32 s52, s52, 0x10000
	v_mfma_f32_16x16x32_bf16 v[22:25], v[146:149], v[178:181], v[22:25]
	s_addc_u32 s53, s53, 0
	v_mfma_f32_16x16x32_bf16 v[18:21], v[154:157], v[178:181], v[18:21]
	s_cmp_gt_u32 s57, 41
	v_mfma_f32_16x16x32_bf16 v[6:9], v[146:149], v[240:243], v[6:9]
	v_mfma_f32_16x16x32_bf16 v[2:5], v[154:157], v[240:243], v[2:5]
	v_mfma_f32_16x16x32_bf16 v[54:57], v[150:153], v[166:169], v[54:57]
	v_mfma_f32_16x16x32_bf16 v[50:53], v[158:161], v[166:169], v[50:53]
	v_mfma_f32_16x16x32_bf16 v[38:41], v[150:153], v[174:177], v[38:41]
	v_mfma_f32_16x16x32_bf16 v[34:37], v[158:161], v[174:177], v[34:37]
	v_mfma_f32_16x16x32_bf16 v[22:25], v[150:153], v[182:185], v[22:25]
	v_mfma_f32_16x16x32_bf16 v[18:21], v[158:161], v[182:185], v[18:21]
	v_mfma_f32_16x16x32_bf16 v[6:9], v[150:153], v[244:247], v[6:9]
	v_mfma_f32_16x16x32_bf16 v[2:5], v[158:161], v[244:247], v[2:5]
	s_setprio 0
	s_barrier
	s_cbranch_scc0 .LBB0_2631
	s_and_b64 vcc, exec, s[40:41]
	s_cbranch_vccz .LBB0_2634
	s_barrier
